# GEMM K-loops: flip pairs front-loaded (after MFMA 4, 8, 12, 16 and 24 of each 32-MFMA segment)
# speedup vs baseline: 1.0043x; 1.0043x over previous
; #define PG8_STAGE(bufoff, gbase, voff) do { _Pragma("unroll") for (int _i = 0; _i < 2; ++_i) \
;         __builtin_amdgcn_global_load_lds((const unsigned*)((const char*)(gbase) + (voff)[_i]), (PG8_LAS unsigned*)(lds + (bufoff) + ldsw + _i * 8192), 16, 0, 0); } while (0)
; #define PG8_LDA(dst, b, h) do { _Pragma("unroll") for (int m = 0; m < 4; ++m) _Pragma("unroll") for (int k = 0; k < 2; ++k) dst[m][k] = *(const PG8_LAS bf16x8*)(lds + PG8_SA(b, h) + aoff + m * 2048 + k * 1024); } while (0)
; #define PG8_LDB(dst, b, h) do { _Pragma("unroll") for (int n = 0; n < 2; ++n) _Pragma("unroll") for (int k = 0; k < 2; ++k) dst[n][k] = *(const PG8_LAS bf16x8*)(lds + PG8_SB(b, h) + boff + n * 2048 + k * 1024); } while (0)
; #define PG8_MMA(ai, bj, At, Bt) do { __builtin_amdgcn_s_setprio(1); _Pragma("unroll") for (int m = 0; m < 4; ++m) _Pragma("unroll") for (int n = 0; n < 2; ++n) _Pragma("unroll") for (int k = 0; k < 2; ++k) \
;         acc[ai][bj][m][n] = __builtin_amdgcn_mfma_f32_16x16x32_bf16(Bt[n][k], At[m][k], acc[ai][bj][m][n], 0, 0, 0); __builtin_amdgcn_s_setprio(0); } while (0)
; #define PG8_WAIT_V(n) asm volatile("s_waitcnt vmcnt(" #n ")" ::: "memory")
; #define PG8_BAR __builtin_amdgcn_s_barrier()
; template <class Epi, class Sched, bool ALIGN_EPI = false, bool SP2 = false>
; __device__ __forceinline__ void gemm_phase(PG8_LAS unsigned char* lds, const Gemm g, const Sched& S, const Epi& E, const int wave0) {
;     ...
;         for (int t = 0; t < nt; t += 2) {
;             const bool last = (t == nt - 2);
;             const char* a1 = cA + (size_t)(t + 1) * kstep;
;             const char* a2 = last ? nA : cA + (size_t)(t + 2) * kstep; const char* b2 = last ? nB : cB + (size_t)(t + 2) * kstep;
;             const char* a3 = a2 + kstep; const char* b3 = b2 + kstep;
;             if (last && has_next) S.a_ready(nxt);
;             if constexpr (SP2) {
;             PG8_LDB(B0, 0, 0); PG8_LDB(B1, 0, 1); PG8_SCHED; PG8_LDA(At, 0, 0); PG8_STAGE(PG8_SA(1, 1), a1 + hstepA, voffA);
;             PG8_WAIT_V(8); PG8_WAIT_L(0); PG8_BAR; PG8_MMA(0, 0, At, B0); PG8_MMA(0, 1, At, B1); PG8_BAR; PG8_SCHED;
;             PG8_LDA(At, 0, 1); PG8_STAGE(PG8_SB(0, 0), b2, voffB); PG8_STAGE(PG8_SB(0, 1), b2 + hstepB, voffB); PG8_STAGE(PG8_SA(0, 0), a2, voffA);
;             PG8_WAIT_V(8); PG8_WAIT_L(0); PG8_BAR; PG8_MMA(1, 0, At, B0); PG8_MMA(1, 1, At, B1); PG8_BAR; PG8_SCHED;
.LBB0_316:
	s_add_u32 s16, s0, 0xfff80080
	s_addc_u32 s17, s1, -1
	s_add_i32 s38, 0, 0x10000
	s_cmp_eq_u32 s37, 28
	s_cselect_b32 s19, s11, s17
	s_cselect_b32 s18, s33, s16
	s_cselect_b32 s17, s9, s36
	s_cselect_b32 s16, s34, s35
	s_add_i32 s40, 0, 0x14000
	ds_read_b128 v[144:147], v252
	ds_read_b128 v[148:151], v252 offset:1024
	ds_read_b128 v[152:155], v252 offset:2048
	ds_read_b128 v[156:159], v252 offset:3072
	ds_read_b128 v[178:181], v253
	ds_read_b128 v[182:185], v253 offset:1024
	ds_read_b128 v[186:189], v253 offset:2048
	ds_read_b128 v[190:193], v253 offset:3072
	s_add_i32 m0, s23, 0xc000
	ds_read_b128 v[194:197], v143
	ds_read_b128 v[208:211], v143 offset:1024
	ds_read_b128 v[212:215], v143 offset:2048
	ds_read_b128 v[216:219], v143 offset:3072
	ds_read_b128 v[220:223], v143 offset:4096
	ds_read_b128 v[224:227], v143 offset:5120
	ds_read_b128 v[228:231], v143 offset:6144
	ds_read_b128 v[232:235], v143 offset:7168
	global_load_lds_dwordx4 v136, s[0:1]
	s_add_i32 m0, s23, 0xe000
	s_nop 0
	global_load_lds_dwordx4 v138, s[0:1]
	s_waitcnt vmcnt(8)
	s_waitcnt lgkmcnt(0)
	s_barrier
	s_setprio 1
	s_waitcnt lgkmcnt(0)
	v_mfma_f32_16x16x32_bf16 v[126:129], v[144:147], v[194:197], v[126:129]
	v_mfma_f32_16x16x32_bf16 v[122:125], v[152:155], v[194:197], v[122:125]
	v_mfma_f32_16x16x32_bf16 v[118:121], v[144:147], v[212:215], v[118:121]
	v_mfma_f32_16x16x32_bf16 v[114:117], v[152:155], v[212:215], v[114:117]
	s_setprio 0
	s_setprio 1
	v_mfma_f32_16x16x32_bf16 v[102:105], v[144:147], v[220:223], v[102:105]
	v_mfma_f32_16x16x32_bf16 v[98:101], v[152:155], v[220:223], v[98:101]
	v_mfma_f32_16x16x32_bf16 v[86:89], v[144:147], v[228:231], v[86:89]
	v_mfma_f32_16x16x32_bf16 v[82:85], v[152:155], v[228:231], v[82:85]
	s_setprio 0
	s_setprio 1
	v_mfma_f32_16x16x32_bf16 v[126:129], v[148:151], v[208:211], v[126:129]
	v_mfma_f32_16x16x32_bf16 v[122:125], v[156:159], v[208:211], v[122:125]
	v_mfma_f32_16x16x32_bf16 v[118:121], v[148:151], v[216:219], v[118:121]
	v_mfma_f32_16x16x32_bf16 v[114:117], v[156:159], v[216:219], v[114:117]
	s_setprio 0
	s_setprio 1
	v_mfma_f32_16x16x32_bf16 v[102:105], v[148:151], v[224:227], v[102:105]
	v_mfma_f32_16x16x32_bf16 v[98:101], v[156:159], v[224:227], v[98:101]
	v_mfma_f32_16x16x32_bf16 v[86:89], v[148:151], v[232:235], v[86:89]
	v_mfma_f32_16x16x32_bf16 v[82:85], v[156:159], v[232:235], v[82:85]
	s_setprio 0
	s_setprio 1
	v_mfma_f32_16x16x32_bf16 v[110:113], v[178:181], v[194:197], v[110:113]
	v_mfma_f32_16x16x32_bf16 v[106:109], v[186:189], v[194:197], v[106:109]
	v_mfma_f32_16x16x32_bf16 v[94:97], v[178:181], v[212:215], v[94:97]
	v_mfma_f32_16x16x32_bf16 v[90:93], v[186:189], v[212:215], v[90:93]
	v_mfma_f32_16x16x32_bf16 v[78:81], v[178:181], v[220:223], v[78:81]
	v_mfma_f32_16x16x32_bf16 v[74:77], v[186:189], v[220:223], v[74:77]
	v_mfma_f32_16x16x32_bf16 v[70:73], v[178:181], v[228:231], v[70:73]
	v_mfma_f32_16x16x32_bf16 v[66:69], v[186:189], v[228:231], v[66:69]
	s_setprio 0
	s_setprio 1
	v_mfma_f32_16x16x32_bf16 v[110:113], v[182:185], v[208:211], v[110:113]
	v_mfma_f32_16x16x32_bf16 v[106:109], v[190:193], v[208:211], v[106:109]
	v_mfma_f32_16x16x32_bf16 v[94:97], v[182:185], v[216:219], v[94:97]
	v_mfma_f32_16x16x32_bf16 v[90:93], v[190:193], v[216:219], v[90:93]
	v_mfma_f32_16x16x32_bf16 v[78:81], v[182:185], v[224:227], v[78:81]
	v_mfma_f32_16x16x32_bf16 v[74:77], v[190:193], v[224:227], v[74:77]
	v_mfma_f32_16x16x32_bf16 v[70:73], v[182:185], v[232:235], v[70:73]
	v_mfma_f32_16x16x32_bf16 v[66:69], v[190:193], v[232:235], v[66:69]
	s_setprio 0
	s_barrier
	s_add_i32 s38, s38, s22
	s_mov_b32 m0, s38
	ds_read_b128 v[194:197], v143 offset:16384
	ds_read_b128 v[208:211], v143 offset:17408
	ds_read_b128 v[212:215], v143 offset:18432
	ds_read_b128 v[216:219], v143 offset:19456
	ds_read_b128 v[220:223], v143 offset:20480
	ds_read_b128 v[224:227], v143 offset:21504
	ds_read_b128 v[228:231], v143 offset:22528
	ds_read_b128 v[232:235], v143 offset:23552
	global_load_lds_dwordx4 v64, s[16:17]
	s_add_i32 m0, s38, 0x2000
	s_add_u32 s38, s16, 0x80000
	s_addc_u32 s39, s17, 0
	s_add_i32 s40, s40, s22
	global_load_lds_dwordx4 v130, s[16:17]
	s_mov_b32 m0, s40
	s_mov_b64 s[100:101], s[18:19]
	global_load_lds_dwordx4 v64, s[38:39]
	s_add_i32 m0, s40, 0x2000
	s_nop 0
	global_load_lds_dwordx4 v130, s[38:39]
	s_mov_b32 m0, s23
	s_nop 0
	global_load_lds_dwordx4 v134, s[18:19]
	s_mov_b32 m0, s24
	s_nop 0
	global_load_lds_dwordx4 v132, s[18:19]
	s_waitcnt vmcnt(8)
	s_waitcnt lgkmcnt(0)
	s_barrier
; #define PG8_STAGE(bufoff, gbase, voff) do { _Pragma("unroll") for (int _i = 0; _i < 2; ++_i) \
;         __builtin_amdgcn_global_load_lds((const unsigned*)((const char*)(gbase) + (voff)[_i]), (PG8_LAS unsigned*)(lds + (bufoff) + ldsw + _i * 8192), 16, 0, 0); } while (0)
; #define PG8_LDA(dst, b, h) do { _Pragma("unroll") for (int m = 0; m < 4; ++m) _Pragma("unroll") for (int k = 0; k < 2; ++k) dst[m][k] = *(const PG8_LAS bf16x8*)(lds + PG8_SA(b, h) + aoff + m * 2048 + k * 1024); } while (0)
; #define PG8_LDB(dst, b, h) do { _Pragma("unroll") for (int n = 0; n < 2; ++n) _Pragma("unroll") for (int k = 0; k < 2; ++k) dst[n][k] = *(const PG8_LAS bf16x8*)(lds + PG8_SB(b, h) + boff + n * 2048 + k * 1024); } while (0)
; #define PG8_MMA(ai, bj, At, Bt) do { __builtin_amdgcn_s_setprio(1); _Pragma("unroll") for (int m = 0; m < 4; ++m) _Pragma("unroll") for (int n = 0; n < 2; ++n) _Pragma("unroll") for (int k = 0; k < 2; ++k) \
;         acc[ai][bj][m][n] = __builtin_amdgcn_mfma_f32_16x16x32_bf16(Bt[n][k], At[m][k], acc[ai][bj][m][n], 0, 0, 0); __builtin_amdgcn_s_setprio(0); } while (0)
; #define PG8_WAIT_V(n) asm volatile("s_waitcnt vmcnt(" #n ")" ::: "memory")
; #define PG8_WAIT_L(n) asm volatile("s_waitcnt lgkmcnt(" #n ")" ::: "memory")
; #define PG8_BAR __builtin_amdgcn_s_barrier()
; #define PG8_SCHED __builtin_amdgcn_sched_barrier(0)
; template <class Epi, class Sched, bool ALIGN_EPI = false, bool SP2 = false>
; __device__ __forceinline__ void gemm_phase(PG8_LAS unsigned char* lds, const Gemm g, const Sched& S, const Epi& E, const int wave0) {
;     ...
;             PG8_WAIT_V(8); PG8_WAIT_L(0); PG8_BAR; PG8_MMA(1, 0, At, B0); PG8_MMA(1, 1, At, B1); PG8_BAR; PG8_SCHED;
;             PG8_LDB(B0, 1, 0); PG8_LDB(B1, 1, 1); PG8_SCHED; PG8_LDA(At, 1, 0); PG8_STAGE(PG8_SA(0, 1), a2 + hstepA, voffA);
;             PG8_WAIT_V(8); PG8_WAIT_L(0); PG8_BAR; PG8_MMA(0, 0, At, B0); PG8_MMA(0, 1, At, B1); PG8_BAR; PG8_SCHED;
	s_setprio 1
	s_waitcnt lgkmcnt(0)
	v_mfma_f32_16x16x32_bf16 v[60:63], v[144:147], v[194:197], v[60:63]
	v_mfma_f32_16x16x32_bf16 v[56:59], v[152:155], v[194:197], v[56:59]
	v_mfma_f32_16x16x32_bf16 v[52:55], v[144:147], v[212:215], v[52:55]
	v_mfma_f32_16x16x32_bf16 v[48:51], v[152:155], v[212:215], v[48:51]
	s_setprio 0
	s_setprio 1
	v_mfma_f32_16x16x32_bf16 v[36:39], v[144:147], v[220:223], v[36:39]
	v_mfma_f32_16x16x32_bf16 v[32:35], v[152:155], v[220:223], v[32:35]
	v_mfma_f32_16x16x32_bf16 v[20:23], v[144:147], v[228:231], v[20:23]
	v_mfma_f32_16x16x32_bf16 v[16:19], v[152:155], v[228:231], v[16:19]
	s_setprio 0
	s_setprio 1
	v_mfma_f32_16x16x32_bf16 v[60:63], v[148:151], v[208:211], v[60:63]
	v_mfma_f32_16x16x32_bf16 v[56:59], v[156:159], v[208:211], v[56:59]
	v_mfma_f32_16x16x32_bf16 v[52:55], v[148:151], v[216:219], v[52:55]
	v_mfma_f32_16x16x32_bf16 v[48:51], v[156:159], v[216:219], v[48:51]
	s_setprio 0
	s_setprio 1
	v_mfma_f32_16x16x32_bf16 v[36:39], v[148:151], v[224:227], v[36:39]
	v_mfma_f32_16x16x32_bf16 v[32:35], v[156:159], v[224:227], v[32:35]
	v_mfma_f32_16x16x32_bf16 v[20:23], v[148:151], v[232:235], v[20:23]
	v_mfma_f32_16x16x32_bf16 v[16:19], v[156:159], v[232:235], v[16:19]
	s_setprio 0
	s_setprio 1
	v_mfma_f32_16x16x32_bf16 v[44:47], v[178:181], v[194:197], v[44:47]
	v_mfma_f32_16x16x32_bf16 v[40:43], v[186:189], v[194:197], v[40:43]
	v_mfma_f32_16x16x32_bf16 v[28:31], v[178:181], v[212:215], v[28:31]
	v_mfma_f32_16x16x32_bf16 v[24:27], v[186:189], v[212:215], v[24:27]
	v_mfma_f32_16x16x32_bf16 v[12:15], v[178:181], v[220:223], v[12:15]
	v_mfma_f32_16x16x32_bf16 v[8:11], v[186:189], v[220:223], v[8:11]
	v_mfma_f32_16x16x32_bf16 v[4:7], v[178:181], v[228:231], v[4:7]
	v_mfma_f32_16x16x32_bf16 v[0:3], v[186:189], v[228:231], v[0:3]
	s_setprio 0
	s_setprio 1
	v_mfma_f32_16x16x32_bf16 v[44:47], v[182:185], v[208:211], v[44:47]
	v_mfma_f32_16x16x32_bf16 v[40:43], v[190:193], v[208:211], v[40:43]
	v_mfma_f32_16x16x32_bf16 v[28:31], v[182:185], v[216:219], v[28:31]
	v_mfma_f32_16x16x32_bf16 v[24:27], v[190:193], v[216:219], v[24:27]
	v_mfma_f32_16x16x32_bf16 v[12:15], v[182:185], v[224:227], v[12:15]
	v_mfma_f32_16x16x32_bf16 v[8:11], v[190:193], v[224:227], v[8:11]
	v_mfma_f32_16x16x32_bf16 v[4:7], v[182:185], v[232:235], v[4:7]
	v_mfma_f32_16x16x32_bf16 v[0:3], v[190:193], v[232:235], v[0:3]
	s_setprio 0
	s_barrier
	s_add_i32 s38, 0, 0x18000
	s_add_i32 s39, 0, 0x1c000
	ds_read_b128 v[144:147], v254
	ds_read_b128 v[148:151], v254 offset:1024
	ds_read_b128 v[152:155], v254 offset:2048
	ds_read_b128 v[156:159], v254 offset:3072
	ds_read_b128 v[178:181], v255
	ds_read_b128 v[182:185], v255 offset:1024
	ds_read_b128 v[186:189], v255 offset:2048
	ds_read_b128 v[190:193], v255 offset:3072
	s_add_u32 s18, s18, 0x80000
	s_addc_u32 s19, s19, 0
	s_mov_b32 m0, s25
	ds_read_b128 v[194:197], v143 offset:32768
	ds_read_b128 v[208:211], v143 offset:33792
	ds_read_b128 v[212:215], v143 offset:34816
	ds_read_b128 v[216:219], v143 offset:35840
	ds_read_b128 v[220:223], v143 offset:36864
	ds_read_b128 v[224:227], v143 offset:37888
	ds_read_b128 v[228:231], v143 offset:38912
	ds_read_b128 v[232:235], v143 offset:39936
	global_load_lds_dwordx4 v134, s[18:19]
	s_mov_b32 m0, s26
	s_nop 0
	global_load_lds_dwordx4 v132, s[18:19]
	s_waitcnt vmcnt(8)
	s_waitcnt lgkmcnt(0)
	s_barrier
	s_setprio 1
	s_waitcnt lgkmcnt(0)
	v_mfma_f32_16x16x32_bf16 v[126:129], v[144:147], v[194:197], v[126:129]
	v_mfma_f32_16x16x32_bf16 v[122:125], v[152:155], v[194:197], v[122:125]
	v_mfma_f32_16x16x32_bf16 v[118:121], v[144:147], v[212:215], v[118:121]
	v_mfma_f32_16x16x32_bf16 v[114:117], v[152:155], v[212:215], v[114:117]
	s_setprio 0
	s_setprio 1
	v_mfma_f32_16x16x32_bf16 v[102:105], v[144:147], v[220:223], v[102:105]
	v_mfma_f32_16x16x32_bf16 v[98:101], v[152:155], v[220:223], v[98:101]
	v_mfma_f32_16x16x32_bf16 v[86:89], v[144:147], v[228:231], v[86:89]
	v_mfma_f32_16x16x32_bf16 v[82:85], v[152:155], v[228:231], v[82:85]
	s_setprio 0
	s_setprio 1
	v_mfma_f32_16x16x32_bf16 v[126:129], v[148:151], v[208:211], v[126:129]
	v_mfma_f32_16x16x32_bf16 v[122:125], v[156:159], v[208:211], v[122:125]
	v_mfma_f32_16x16x32_bf16 v[118:121], v[148:151], v[216:219], v[118:121]
	v_mfma_f32_16x16x32_bf16 v[114:117], v[156:159], v[216:219], v[114:117]
	s_setprio 0
	s_setprio 1
	v_mfma_f32_16x16x32_bf16 v[102:105], v[148:151], v[224:227], v[102:105]
	v_mfma_f32_16x16x32_bf16 v[98:101], v[156:159], v[224:227], v[98:101]
	v_mfma_f32_16x16x32_bf16 v[86:89], v[148:151], v[232:235], v[86:89]
	v_mfma_f32_16x16x32_bf16 v[82:85], v[156:159], v[232:235], v[82:85]
	s_setprio 0
	s_setprio 1
	v_mfma_f32_16x16x32_bf16 v[110:113], v[178:181], v[194:197], v[110:113]
	v_mfma_f32_16x16x32_bf16 v[106:109], v[186:189], v[194:197], v[106:109]
	v_mfma_f32_16x16x32_bf16 v[94:97], v[178:181], v[212:215], v[94:97]
	v_mfma_f32_16x16x32_bf16 v[90:93], v[186:189], v[212:215], v[90:93]
	v_mfma_f32_16x16x32_bf16 v[78:81], v[178:181], v[220:223], v[78:81]
	v_mfma_f32_16x16x32_bf16 v[74:77], v[186:189], v[220:223], v[74:77]
	v_mfma_f32_16x16x32_bf16 v[70:73], v[178:181], v[228:231], v[70:73]
	v_mfma_f32_16x16x32_bf16 v[66:69], v[186:189], v[228:231], v[66:69]
	s_setprio 0
	s_setprio 1
	v_mfma_f32_16x16x32_bf16 v[110:113], v[182:185], v[208:211], v[110:113]
	v_mfma_f32_16x16x32_bf16 v[106:109], v[190:193], v[208:211], v[106:109]
	v_mfma_f32_16x16x32_bf16 v[94:97], v[182:185], v[216:219], v[94:97]
	v_mfma_f32_16x16x32_bf16 v[90:93], v[190:193], v[216:219], v[90:93]
	v_mfma_f32_16x16x32_bf16 v[78:81], v[182:185], v[224:227], v[78:81]
	v_mfma_f32_16x16x32_bf16 v[74:77], v[190:193], v[224:227], v[74:77]
	v_mfma_f32_16x16x32_bf16 v[70:73], v[182:185], v[232:235], v[70:73]
	v_mfma_f32_16x16x32_bf16 v[66:69], v[190:193], v[232:235], v[66:69]
	s_setprio 0
	s_barrier
; #define PG8_STAGE(bufoff, gbase, voff) do { _Pragma("unroll") for (int _i = 0; _i < 2; ++_i) \
;         __builtin_amdgcn_global_load_lds((const unsigned*)((const char*)(gbase) + (voff)[_i]), (PG8_LAS unsigned*)(lds + (bufoff) + ldsw + _i * 8192), 16, 0, 0); } while (0)
; #define PG8_LDA(dst, b, h) do { _Pragma("unroll") for (int m = 0; m < 4; ++m) _Pragma("unroll") for (int k = 0; k < 2; ++k) dst[m][k] = *(const PG8_LAS bf16x8*)(lds + PG8_SA(b, h) + aoff + m * 2048 + k * 1024); } while (0)
; #define PG8_MMA(ai, bj, At, Bt) do { __builtin_amdgcn_s_setprio(1); _Pragma("unroll") for (int m = 0; m < 4; ++m) _Pragma("unroll") for (int n = 0; n < 2; ++n) _Pragma("unroll") for (int k = 0; k < 2; ++k) \
;         acc[ai][bj][m][n] = __builtin_amdgcn_mfma_f32_16x16x32_bf16(Bt[n][k], At[m][k], acc[ai][bj][m][n], 0, 0, 0); __builtin_amdgcn_s_setprio(0); } while (0)
; #define PG8_WAIT_V(n) asm volatile("s_waitcnt vmcnt(" #n ")" ::: "memory")
; #define PG8_WAIT_L(n) asm volatile("s_waitcnt lgkmcnt(" #n ")" ::: "memory")
; #define PG8_BAR __builtin_amdgcn_s_barrier()
; #define PG8_SCHED __builtin_amdgcn_sched_barrier(0)
; template <class Epi, class Sched, bool ALIGN_EPI = false, bool SP2 = false>
; __device__ __forceinline__ void gemm_phase(PG8_LAS unsigned char* lds, const Gemm g, const Sched& S, const Epi& E, const int wave0) {
;     ...
;         for (int t = 0; t < nt; t += 2) {
;             const bool last = (t == nt - 2);
;             const char* a1 = cA + (size_t)(t + 1) * kstep;
;             const char* a2 = last ? nA : cA + (size_t)(t + 2) * kstep; const char* b2 = last ? nB : cB + (size_t)(t + 2) * kstep;
;     ...
;             PG8_LDA(At, 1, 1); PG8_STAGE(PG8_SB(1, 0), b3, voffB); PG8_STAGE(PG8_SB(1, 1), b3 + hstepB, voffB); PG8_STAGE(PG8_SA(1, 0), a3, voffA);
;             PG8_WAIT_V(8); PG8_WAIT_L(0); PG8_BAR; PG8_MMA(1, 0, At, B0); PG8_MMA(1, 1, At, B1); PG8_BAR; PG8_SCHED;
	s_add_i32 s18, s38, s22
	s_add_u32 s42, s16, 0x80
	s_addc_u32 s43, s17, 0
	s_mov_b32 m0, s18
	ds_read_b128 v[194:197], v143 offset:49152
	ds_read_b128 v[208:211], v143 offset:50176
	ds_read_b128 v[212:215], v143 offset:51200
	ds_read_b128 v[216:219], v143 offset:52224
	ds_read_b128 v[220:223], v143 offset:53248
	ds_read_b128 v[224:227], v143 offset:54272
	ds_read_b128 v[228:231], v143 offset:55296
	ds_read_b128 v[232:235], v143 offset:56320
	global_load_lds_dwordx4 v64, s[42:43]
	s_add_i32 m0, s18, 0x2000
	s_add_u32 s16, s16, 0x80080
	s_addc_u32 s17, s17, 0
	s_add_i32 s18, s39, s22
	global_load_lds_dwordx4 v130, s[42:43]
	s_mov_b32 m0, s18
	s_nop 0
	global_load_lds_dwordx4 v64, s[16:17]
	s_add_i32 m0, s18, 0x2000
	s_nop 0
	global_load_lds_dwordx4 v130, s[16:17]
	s_add_u32 s100, s100, 0x80
	s_addc_u32 s101, s101, 0
	s_mov_b32 m0, s27
	s_nop 0
	global_load_lds_dwordx4 v134, s[100:101]
	s_mov_b32 m0, s28
	s_nop 0
	global_load_lds_dwordx4 v132, s[100:101]
	s_waitcnt vmcnt(8)
	s_waitcnt lgkmcnt(0)
	s_barrier
	s_setprio 1
	s_waitcnt lgkmcnt(0)
	v_mfma_f32_16x16x32_bf16 v[60:63], v[144:147], v[194:197], v[60:63]
	v_mfma_f32_16x16x32_bf16 v[56:59], v[152:155], v[194:197], v[56:59]
	v_mfma_f32_16x16x32_bf16 v[52:55], v[144:147], v[212:215], v[52:55]
	v_mfma_f32_16x16x32_bf16 v[48:51], v[152:155], v[212:215], v[48:51]
	s_setprio 0
	s_setprio 1
	v_mfma_f32_16x16x32_bf16 v[36:39], v[144:147], v[220:223], v[36:39]
	v_mfma_f32_16x16x32_bf16 v[32:35], v[152:155], v[220:223], v[32:35]
	v_mfma_f32_16x16x32_bf16 v[20:23], v[144:147], v[228:231], v[20:23]
	v_mfma_f32_16x16x32_bf16 v[16:19], v[152:155], v[228:231], v[16:19]
	s_setprio 0
	s_setprio 1
	v_mfma_f32_16x16x32_bf16 v[60:63], v[148:151], v[208:211], v[60:63]
	v_mfma_f32_16x16x32_bf16 v[56:59], v[156:159], v[208:211], v[56:59]
	v_mfma_f32_16x16x32_bf16 v[52:55], v[148:151], v[216:219], v[52:55]
	v_mfma_f32_16x16x32_bf16 v[48:51], v[156:159], v[216:219], v[48:51]
	s_setprio 0
	s_setprio 1
	v_mfma_f32_16x16x32_bf16 v[36:39], v[148:151], v[224:227], v[36:39]
	v_mfma_f32_16x16x32_bf16 v[32:35], v[156:159], v[224:227], v[32:35]
	v_mfma_f32_16x16x32_bf16 v[20:23], v[148:151], v[232:235], v[20:23]
	v_mfma_f32_16x16x32_bf16 v[16:19], v[156:159], v[232:235], v[16:19]
	s_setprio 0
	s_setprio 1
	v_mfma_f32_16x16x32_bf16 v[44:47], v[178:181], v[194:197], v[44:47]
	v_mfma_f32_16x16x32_bf16 v[40:43], v[186:189], v[194:197], v[40:43]
	v_mfma_f32_16x16x32_bf16 v[28:31], v[178:181], v[212:215], v[28:31]
	v_mfma_f32_16x16x32_bf16 v[24:27], v[186:189], v[212:215], v[24:27]
	v_mfma_f32_16x16x32_bf16 v[12:15], v[178:181], v[220:223], v[12:15]
	v_mfma_f32_16x16x32_bf16 v[8:11], v[186:189], v[220:223], v[8:11]
	v_mfma_f32_16x16x32_bf16 v[4:7], v[178:181], v[228:231], v[4:7]
	v_mfma_f32_16x16x32_bf16 v[0:3], v[186:189], v[228:231], v[0:3]
	s_setprio 0
	s_setprio 1
	v_mfma_f32_16x16x32_bf16 v[44:47], v[182:185], v[208:211], v[44:47]
	v_mfma_f32_16x16x32_bf16 v[40:43], v[190:193], v[208:211], v[40:43]
	v_mfma_f32_16x16x32_bf16 v[28:31], v[182:185], v[216:219], v[28:31]
	v_mfma_f32_16x16x32_bf16 v[24:27], v[190:193], v[216:219], v[24:27]
	v_mfma_f32_16x16x32_bf16 v[12:15], v[182:185], v[224:227], v[12:15]
	v_mfma_f32_16x16x32_bf16 v[8:11], v[190:193], v[224:227], v[8:11]
	v_mfma_f32_16x16x32_bf16 v[4:7], v[182:185], v[232:235], v[4:7]
	v_mfma_f32_16x16x32_bf16 v[0:3], v[190:193], v[232:235], v[0:3]
	s_setprio 0
	s_barrier
	s_add_i32 s37, s37, 2
	s_add_u32 s0, s0, 0x100
	s_addc_u32 s1, s1, 0
	s_add_u32 s35, s35, 0x100
	s_addc_u32 s36, s36, 0
	s_cmp_gt_u32 s37, 29
	s_cbranch_scc0 .LBB0_316
	s_mov_b64 s[42:43], 0x80
	s_and_b64 vcc, exec, s[6:7]
	s_mov_b64 s[34:35], 0x45000
	s_cbranch_vccz .LBB0_319
	s_barrier

; #define PG8_STAGE(bufoff, gbase, voff) do { _Pragma("unroll") for (int _i = 0; _i < 2; ++_i) \
;         __builtin_amdgcn_global_load_lds((const unsigned*)((const char*)(gbase) + (voff)[_i]), (PG8_LAS unsigned*)(lds + (bufoff) + ldsw + _i * 8192), 16, 0, 0); } while (0)
; #define PG8_LDA(dst, b, h) do { _Pragma("unroll") for (int m = 0; m < 4; ++m) _Pragma("unroll") for (int k = 0; k < 2; ++k) dst[m][k] = *(const PG8_LAS bf16x8*)(lds + PG8_SA(b, h) + aoff + m * 2048 + k * 1024); } while (0)
; #define PG8_LDB(dst, b, h) do { _Pragma("unroll") for (int n = 0; n < 2; ++n) _Pragma("unroll") for (int k = 0; k < 2; ++k) dst[n][k] = *(const PG8_LAS bf16x8*)(lds + PG8_SB(b, h) + boff + n * 2048 + k * 1024); } while (0)
; #define PG8_MMA(ai, bj, At, Bt) do { __builtin_amdgcn_s_setprio(1); _Pragma("unroll") for (int m = 0; m < 4; ++m) _Pragma("unroll") for (int n = 0; n < 2; ++n) _Pragma("unroll") for (int k = 0; k < 2; ++k) \
;         acc[ai][bj][m][n] = __builtin_amdgcn_mfma_f32_16x16x32_bf16(Bt[n][k], At[m][k], acc[ai][bj][m][n], 0, 0, 0); __builtin_amdgcn_s_setprio(0); } while (0)
; #define PG8_WAIT_V(n) asm volatile("s_waitcnt vmcnt(" #n ")" ::: "memory")
; #define PG8_BAR __builtin_amdgcn_s_barrier()
; template <class Epi, class Sched, bool ALIGN_EPI = false, bool SP2 = false>
; __device__ __forceinline__ void gemm_phase(PG8_LAS unsigned char* lds, const Gemm g, const Sched& S, const Epi& E, const int wave0) {
;     ...
;         for (int t = 0; t < nt; t += 2) {
;             const bool last = (t == nt - 2);
;             const char* a1 = cA + (size_t)(t + 1) * kstep;
;             const char* a2 = last ? nA : cA + (size_t)(t + 2) * kstep; const char* b2 = last ? nB : cB + (size_t)(t + 2) * kstep;
;             const char* a3 = a2 + kstep; const char* b3 = b2 + kstep;
;             if (last && has_next) S.a_ready(nxt);
;             if constexpr (SP2) {
;             PG8_LDB(B0, 0, 0); PG8_LDB(B1, 0, 1); PG8_SCHED; PG8_LDA(At, 0, 0); PG8_STAGE(PG8_SA(1, 1), a1 + hstepA, voffA);
;             PG8_WAIT_V(8); PG8_WAIT_L(0); PG8_BAR; PG8_MMA(0, 0, At, B0); PG8_MMA(0, 1, At, B1); PG8_BAR; PG8_SCHED;
;             PG8_LDA(At, 0, 1); PG8_STAGE(PG8_SB(0, 0), b2, voffB); PG8_STAGE(PG8_SB(0, 1), b2 + hstepB, voffB); PG8_STAGE(PG8_SA(0, 0), a2, voffA);
;             PG8_WAIT_V(8); PG8_WAIT_L(0); PG8_BAR; PG8_MMA(1, 0, At, B0); PG8_MMA(1, 1, At, B1); PG8_BAR; PG8_SCHED;
.LBB0_1178:
	s_add_u32 s2, s0, 0xfffc0080
	s_addc_u32 s3, s1, -1
	s_add_i32 s31, 0, 0x10000
	s_cmp_eq_u32 s19, 12
	s_cselect_b32 s17, s45, s3
	s_cselect_b32 s16, s44, s2
	s_cselect_b32 s3, s9, s18
	s_cselect_b32 s2, s11, s13
	s_add_i32 s33, 0, 0x14000
	ds_read_b128 v[130:133], v252
	ds_read_b128 v[134:137], v252 offset:1024
	ds_read_b128 v[148:151], v252 offset:2048
	ds_read_b128 v[152:155], v252 offset:3072
	ds_read_b128 v[178:181], v253
	ds_read_b128 v[182:185], v253 offset:1024
	ds_read_b128 v[186:189], v253 offset:2048
	ds_read_b128 v[190:193], v253 offset:3072
	s_add_i32 m0, s23, 0xc000
	ds_read_b128 v[194:197], v159
	ds_read_b128 v[208:211], v159 offset:1024
	ds_read_b128 v[212:215], v159 offset:2048
	ds_read_b128 v[216:219], v159 offset:3072
	ds_read_b128 v[220:223], v159 offset:4096
	ds_read_b128 v[224:227], v159 offset:5120
	ds_read_b128 v[228:231], v159 offset:6144
	ds_read_b128 v[232:235], v159 offset:7168
	global_load_lds_dwordx4 v144, s[0:1]
	s_add_i32 m0, s23, 0xe000
	s_nop 0
	global_load_lds_dwordx4 v146, s[0:1]
	s_waitcnt vmcnt(8)
	s_waitcnt lgkmcnt(0)
	s_barrier
	s_setprio 1
	s_waitcnt lgkmcnt(0)
	v_mfma_f32_16x16x32_bf16 v[126:129], v[130:133], v[194:197], v[126:129]
	v_mfma_f32_16x16x32_bf16 v[122:125], v[148:151], v[194:197], v[122:125]
	v_mfma_f32_16x16x32_bf16 v[110:113], v[130:133], v[212:215], v[110:113]
	v_mfma_f32_16x16x32_bf16 v[106:109], v[148:151], v[212:215], v[106:109]
	s_setprio 0
	s_setprio 1
	v_mfma_f32_16x16x32_bf16 v[94:97], v[130:133], v[220:223], v[94:97]
	v_mfma_f32_16x16x32_bf16 v[90:93], v[148:151], v[220:223], v[90:93]
	v_mfma_f32_16x16x32_bf16 v[78:81], v[130:133], v[228:231], v[78:81]
	v_mfma_f32_16x16x32_bf16 v[74:77], v[148:151], v[228:231], v[74:77]
	s_setprio 0
	s_setprio 1
	v_mfma_f32_16x16x32_bf16 v[126:129], v[134:137], v[208:211], v[126:129]
	v_mfma_f32_16x16x32_bf16 v[122:125], v[152:155], v[208:211], v[122:125]
	v_mfma_f32_16x16x32_bf16 v[110:113], v[134:137], v[216:219], v[110:113]
	v_mfma_f32_16x16x32_bf16 v[106:109], v[152:155], v[216:219], v[106:109]
	s_setprio 0
	s_setprio 1
	v_mfma_f32_16x16x32_bf16 v[94:97], v[134:137], v[224:227], v[94:97]
	v_mfma_f32_16x16x32_bf16 v[90:93], v[152:155], v[224:227], v[90:93]
	v_mfma_f32_16x16x32_bf16 v[78:81], v[134:137], v[232:235], v[78:81]
	v_mfma_f32_16x16x32_bf16 v[74:77], v[152:155], v[232:235], v[74:77]
	s_setprio 0
	s_setprio 1
	v_mfma_f32_16x16x32_bf16 v[118:121], v[178:181], v[194:197], v[118:121]
	v_mfma_f32_16x16x32_bf16 v[114:117], v[186:189], v[194:197], v[114:117]
	v_mfma_f32_16x16x32_bf16 v[102:105], v[178:181], v[212:215], v[102:105]
	v_mfma_f32_16x16x32_bf16 v[98:101], v[186:189], v[212:215], v[98:101]
	v_mfma_f32_16x16x32_bf16 v[86:89], v[178:181], v[220:223], v[86:89]
	v_mfma_f32_16x16x32_bf16 v[82:85], v[186:189], v[220:223], v[82:85]
	v_mfma_f32_16x16x32_bf16 v[70:73], v[178:181], v[228:231], v[70:73]
	v_mfma_f32_16x16x32_bf16 v[66:69], v[186:189], v[228:231], v[66:69]
	s_setprio 0
	s_setprio 1
	v_mfma_f32_16x16x32_bf16 v[118:121], v[182:185], v[208:211], v[118:121]
	v_mfma_f32_16x16x32_bf16 v[114:117], v[190:193], v[208:211], v[114:117]
	v_mfma_f32_16x16x32_bf16 v[102:105], v[182:185], v[216:219], v[102:105]
	v_mfma_f32_16x16x32_bf16 v[98:101], v[190:193], v[216:219], v[98:101]
	v_mfma_f32_16x16x32_bf16 v[86:89], v[182:185], v[224:227], v[86:89]
	v_mfma_f32_16x16x32_bf16 v[82:85], v[190:193], v[224:227], v[82:85]
	v_mfma_f32_16x16x32_bf16 v[70:73], v[182:185], v[232:235], v[70:73]
	v_mfma_f32_16x16x32_bf16 v[66:69], v[190:193], v[232:235], v[66:69]
	s_setprio 0
	s_barrier
	s_add_i32 s31, s31, s22
	s_mov_b32 m0, s31
	ds_read_b128 v[194:197], v159 offset:16384
	ds_read_b128 v[208:211], v159 offset:17408
	ds_read_b128 v[212:215], v159 offset:18432
	ds_read_b128 v[216:219], v159 offset:19456
	ds_read_b128 v[220:223], v159 offset:20480
	ds_read_b128 v[224:227], v159 offset:21504
	ds_read_b128 v[228:231], v159 offset:22528
	ds_read_b128 v[232:235], v159 offset:23552
	global_load_lds_dwordx4 v64, s[2:3]
	s_add_i32 m0, s31, 0x2000
	s_add_u32 s34, s2, 0x40000
	s_addc_u32 s35, s3, 0
	s_add_i32 s31, s33, s22
	global_load_lds_dwordx4 v138, s[2:3]
	s_mov_b32 m0, s31
	s_mov_b64 s[100:101], s[16:17]
	global_load_lds_dwordx4 v64, s[34:35]
	s_add_i32 m0, s31, 0x2000
	s_nop 0
	global_load_lds_dwordx4 v138, s[34:35]
	s_mov_b32 m0, s23
	s_nop 0
	global_load_lds_dwordx4 v142, s[16:17]
	s_mov_b32 m0, s24
	s_nop 0
	global_load_lds_dwordx4 v140, s[16:17]
	s_waitcnt vmcnt(8)
	s_waitcnt lgkmcnt(0)
	s_barrier
; #define PG8_STAGE(bufoff, gbase, voff) do { _Pragma("unroll") for (int _i = 0; _i < 2; ++_i) \
;         __builtin_amdgcn_global_load_lds((const unsigned*)((const char*)(gbase) + (voff)[_i]), (PG8_LAS unsigned*)(lds + (bufoff) + ldsw + _i * 8192), 16, 0, 0); } while (0)
; #define PG8_LDA(dst, b, h) do { _Pragma("unroll") for (int m = 0; m < 4; ++m) _Pragma("unroll") for (int k = 0; k < 2; ++k) dst[m][k] = *(const PG8_LAS bf16x8*)(lds + PG8_SA(b, h) + aoff + m * 2048 + k * 1024); } while (0)
; #define PG8_LDB(dst, b, h) do { _Pragma("unroll") for (int n = 0; n < 2; ++n) _Pragma("unroll") for (int k = 0; k < 2; ++k) dst[n][k] = *(const PG8_LAS bf16x8*)(lds + PG8_SB(b, h) + boff + n * 2048 + k * 1024); } while (0)
; #define PG8_MMA(ai, bj, At, Bt) do { __builtin_amdgcn_s_setprio(1); _Pragma("unroll") for (int m = 0; m < 4; ++m) _Pragma("unroll") for (int n = 0; n < 2; ++n) _Pragma("unroll") for (int k = 0; k < 2; ++k) \
;         acc[ai][bj][m][n] = __builtin_amdgcn_mfma_f32_16x16x32_bf16(Bt[n][k], At[m][k], acc[ai][bj][m][n], 0, 0, 0); __builtin_amdgcn_s_setprio(0); } while (0)
; #define PG8_WAIT_V(n) asm volatile("s_waitcnt vmcnt(" #n ")" ::: "memory")
; #define PG8_WAIT_L(n) asm volatile("s_waitcnt lgkmcnt(" #n ")" ::: "memory")
; #define PG8_BAR __builtin_amdgcn_s_barrier()
; #define PG8_SCHED __builtin_amdgcn_sched_barrier(0)
; template <class Epi, class Sched, bool ALIGN_EPI = false, bool SP2 = false>
; __device__ __forceinline__ void gemm_phase(PG8_LAS unsigned char* lds, const Gemm g, const Sched& S, const Epi& E, const int wave0) {
;     ...
;             PG8_WAIT_V(8); PG8_WAIT_L(0); PG8_BAR; PG8_MMA(1, 0, At, B0); PG8_MMA(1, 1, At, B1); PG8_BAR; PG8_SCHED;
;             PG8_LDB(B0, 1, 0); PG8_LDB(B1, 1, 1); PG8_SCHED; PG8_LDA(At, 1, 0); PG8_STAGE(PG8_SA(0, 1), a2 + hstepA, voffA);
;             PG8_WAIT_V(8); PG8_WAIT_L(0); PG8_BAR; PG8_MMA(0, 0, At, B0); PG8_MMA(0, 1, At, B1); PG8_BAR; PG8_SCHED;
	s_setprio 1
	s_waitcnt lgkmcnt(0)
	v_mfma_f32_16x16x32_bf16 v[60:63], v[130:133], v[194:197], v[60:63]
	v_mfma_f32_16x16x32_bf16 v[56:59], v[148:151], v[194:197], v[56:59]
	v_mfma_f32_16x16x32_bf16 v[44:47], v[130:133], v[212:215], v[44:47]
	v_mfma_f32_16x16x32_bf16 v[40:43], v[148:151], v[212:215], v[40:43]
	s_setprio 0
	s_setprio 1
	v_mfma_f32_16x16x32_bf16 v[28:31], v[130:133], v[220:223], v[28:31]
	v_mfma_f32_16x16x32_bf16 v[24:27], v[148:151], v[220:223], v[24:27]
	v_mfma_f32_16x16x32_bf16 v[12:15], v[130:133], v[228:231], v[12:15]
	v_mfma_f32_16x16x32_bf16 v[8:11], v[148:151], v[228:231], v[8:11]
	s_setprio 0
	s_setprio 1
	v_mfma_f32_16x16x32_bf16 v[60:63], v[134:137], v[208:211], v[60:63]
	v_mfma_f32_16x16x32_bf16 v[56:59], v[152:155], v[208:211], v[56:59]
	v_mfma_f32_16x16x32_bf16 v[44:47], v[134:137], v[216:219], v[44:47]
	v_mfma_f32_16x16x32_bf16 v[40:43], v[152:155], v[216:219], v[40:43]
	s_setprio 0
	s_setprio 1
	v_mfma_f32_16x16x32_bf16 v[28:31], v[134:137], v[224:227], v[28:31]
	v_mfma_f32_16x16x32_bf16 v[24:27], v[152:155], v[224:227], v[24:27]
	v_mfma_f32_16x16x32_bf16 v[12:15], v[134:137], v[232:235], v[12:15]
	v_mfma_f32_16x16x32_bf16 v[8:11], v[152:155], v[232:235], v[8:11]
	s_setprio 0
	s_setprio 1
	v_mfma_f32_16x16x32_bf16 v[52:55], v[178:181], v[194:197], v[52:55]
	v_mfma_f32_16x16x32_bf16 v[48:51], v[186:189], v[194:197], v[48:51]
	v_mfma_f32_16x16x32_bf16 v[36:39], v[178:181], v[212:215], v[36:39]
	v_mfma_f32_16x16x32_bf16 v[32:35], v[186:189], v[212:215], v[32:35]
	v_mfma_f32_16x16x32_bf16 v[20:23], v[178:181], v[220:223], v[20:23]
	v_mfma_f32_16x16x32_bf16 v[16:19], v[186:189], v[220:223], v[16:19]
	v_mfma_f32_16x16x32_bf16 v[4:7], v[178:181], v[228:231], v[4:7]
	v_mfma_f32_16x16x32_bf16 v[0:3], v[186:189], v[228:231], v[0:3]
	s_setprio 0
	s_setprio 1
	v_mfma_f32_16x16x32_bf16 v[52:55], v[182:185], v[208:211], v[52:55]
	v_mfma_f32_16x16x32_bf16 v[48:51], v[190:193], v[208:211], v[48:51]
	v_mfma_f32_16x16x32_bf16 v[36:39], v[182:185], v[216:219], v[36:39]
	v_mfma_f32_16x16x32_bf16 v[32:35], v[190:193], v[216:219], v[32:35]
	v_mfma_f32_16x16x32_bf16 v[20:23], v[182:185], v[224:227], v[20:23]
	v_mfma_f32_16x16x32_bf16 v[16:19], v[190:193], v[224:227], v[16:19]
	v_mfma_f32_16x16x32_bf16 v[4:7], v[182:185], v[232:235], v[4:7]
	v_mfma_f32_16x16x32_bf16 v[0:3], v[190:193], v[232:235], v[0:3]
	s_setprio 0
	s_barrier
	s_add_i32 s31, 0, 0x18000
	s_add_i32 s33, 0, 0x1c000
	ds_read_b128 v[130:133], v254
	ds_read_b128 v[134:137], v254 offset:1024
	ds_read_b128 v[148:151], v254 offset:2048
	ds_read_b128 v[152:155], v254 offset:3072
	ds_read_b128 v[178:181], v255
	ds_read_b128 v[182:185], v255 offset:1024
	ds_read_b128 v[186:189], v255 offset:2048
	ds_read_b128 v[190:193], v255 offset:3072
	s_add_u32 s16, s16, 0x40000
	s_addc_u32 s17, s17, 0
	s_mov_b32 m0, s25
	ds_read_b128 v[194:197], v159 offset:32768
	ds_read_b128 v[208:211], v159 offset:33792
	ds_read_b128 v[212:215], v159 offset:34816
	ds_read_b128 v[216:219], v159 offset:35840
	ds_read_b128 v[220:223], v159 offset:36864
	ds_read_b128 v[224:227], v159 offset:37888
	ds_read_b128 v[228:231], v159 offset:38912
	ds_read_b128 v[232:235], v159 offset:39936
	global_load_lds_dwordx4 v142, s[16:17]
	s_mov_b32 m0, s26
	s_nop 0
	global_load_lds_dwordx4 v140, s[16:17]
	s_waitcnt vmcnt(8)
	s_waitcnt lgkmcnt(0)
	s_barrier
	s_setprio 1
	s_waitcnt lgkmcnt(0)
	v_mfma_f32_16x16x32_bf16 v[126:129], v[130:133], v[194:197], v[126:129]
	v_mfma_f32_16x16x32_bf16 v[122:125], v[148:151], v[194:197], v[122:125]
	v_mfma_f32_16x16x32_bf16 v[110:113], v[130:133], v[212:215], v[110:113]
	v_mfma_f32_16x16x32_bf16 v[106:109], v[148:151], v[212:215], v[106:109]
	s_setprio 0
	s_setprio 1
	v_mfma_f32_16x16x32_bf16 v[94:97], v[130:133], v[220:223], v[94:97]
	v_mfma_f32_16x16x32_bf16 v[90:93], v[148:151], v[220:223], v[90:93]
	v_mfma_f32_16x16x32_bf16 v[78:81], v[130:133], v[228:231], v[78:81]
	v_mfma_f32_16x16x32_bf16 v[74:77], v[148:151], v[228:231], v[74:77]
	s_setprio 0
	s_setprio 1
	v_mfma_f32_16x16x32_bf16 v[126:129], v[134:137], v[208:211], v[126:129]
	v_mfma_f32_16x16x32_bf16 v[122:125], v[152:155], v[208:211], v[122:125]
	v_mfma_f32_16x16x32_bf16 v[110:113], v[134:137], v[216:219], v[110:113]
	v_mfma_f32_16x16x32_bf16 v[106:109], v[152:155], v[216:219], v[106:109]
	s_setprio 0
	s_setprio 1
	v_mfma_f32_16x16x32_bf16 v[94:97], v[134:137], v[224:227], v[94:97]
	v_mfma_f32_16x16x32_bf16 v[90:93], v[152:155], v[224:227], v[90:93]
	v_mfma_f32_16x16x32_bf16 v[78:81], v[134:137], v[232:235], v[78:81]
	v_mfma_f32_16x16x32_bf16 v[74:77], v[152:155], v[232:235], v[74:77]
	s_setprio 0
	s_setprio 1
	v_mfma_f32_16x16x32_bf16 v[118:121], v[178:181], v[194:197], v[118:121]
	v_mfma_f32_16x16x32_bf16 v[114:117], v[186:189], v[194:197], v[114:117]
	v_mfma_f32_16x16x32_bf16 v[102:105], v[178:181], v[212:215], v[102:105]
	v_mfma_f32_16x16x32_bf16 v[98:101], v[186:189], v[212:215], v[98:101]
	v_mfma_f32_16x16x32_bf16 v[86:89], v[178:181], v[220:223], v[86:89]
	v_mfma_f32_16x16x32_bf16 v[82:85], v[186:189], v[220:223], v[82:85]
	v_mfma_f32_16x16x32_bf16 v[70:73], v[178:181], v[228:231], v[70:73]
	v_mfma_f32_16x16x32_bf16 v[66:69], v[186:189], v[228:231], v[66:69]
	s_setprio 0
	s_setprio 1
	v_mfma_f32_16x16x32_bf16 v[118:121], v[182:185], v[208:211], v[118:121]
	v_mfma_f32_16x16x32_bf16 v[114:117], v[190:193], v[208:211], v[114:117]
	v_mfma_f32_16x16x32_bf16 v[102:105], v[182:185], v[216:219], v[102:105]
	v_mfma_f32_16x16x32_bf16 v[98:101], v[190:193], v[216:219], v[98:101]
	v_mfma_f32_16x16x32_bf16 v[86:89], v[182:185], v[224:227], v[86:89]
	v_mfma_f32_16x16x32_bf16 v[82:85], v[190:193], v[224:227], v[82:85]
	v_mfma_f32_16x16x32_bf16 v[70:73], v[182:185], v[232:235], v[70:73]
	v_mfma_f32_16x16x32_bf16 v[66:69], v[190:193], v[232:235], v[66:69]
	s_setprio 0
	s_barrier
; #define PG8_STAGE(bufoff, gbase, voff) do { _Pragma("unroll") for (int _i = 0; _i < 2; ++_i) \
;         __builtin_amdgcn_global_load_lds((const unsigned*)((const char*)(gbase) + (voff)[_i]), (PG8_LAS unsigned*)(lds + (bufoff) + ldsw + _i * 8192), 16, 0, 0); } while (0)
; #define PG8_LDA(dst, b, h) do { _Pragma("unroll") for (int m = 0; m < 4; ++m) _Pragma("unroll") for (int k = 0; k < 2; ++k) dst[m][k] = *(const PG8_LAS bf16x8*)(lds + PG8_SA(b, h) + aoff + m * 2048 + k * 1024); } while (0)
; #define PG8_MMA(ai, bj, At, Bt) do { __builtin_amdgcn_s_setprio(1); _Pragma("unroll") for (int m = 0; m < 4; ++m) _Pragma("unroll") for (int n = 0; n < 2; ++n) _Pragma("unroll") for (int k = 0; k < 2; ++k) \
;         acc[ai][bj][m][n] = __builtin_amdgcn_mfma_f32_16x16x32_bf16(Bt[n][k], At[m][k], acc[ai][bj][m][n], 0, 0, 0); __builtin_amdgcn_s_setprio(0); } while (0)
; #define PG8_WAIT_V(n) asm volatile("s_waitcnt vmcnt(" #n ")" ::: "memory")
; #define PG8_WAIT_L(n) asm volatile("s_waitcnt lgkmcnt(" #n ")" ::: "memory")
; #define PG8_BAR __builtin_amdgcn_s_barrier()
; #define PG8_SCHED __builtin_amdgcn_sched_barrier(0)
; template <class Epi, class Sched, bool ALIGN_EPI = false, bool SP2 = false>
; __device__ __forceinline__ void gemm_phase(PG8_LAS unsigned char* lds, const Gemm g, const Sched& S, const Epi& E, const int wave0) {
;     ...
;         for (int t = 0; t < nt; t += 2) {
;             const bool last = (t == nt - 2);
;             const char* a1 = cA + (size_t)(t + 1) * kstep;
;             const char* a2 = last ? nA : cA + (size_t)(t + 2) * kstep; const char* b2 = last ? nB : cB + (size_t)(t + 2) * kstep;
;     ...
;             PG8_LDA(At, 1, 1); PG8_STAGE(PG8_SB(1, 0), b3, voffB); PG8_STAGE(PG8_SB(1, 1), b3 + hstepB, voffB); PG8_STAGE(PG8_SA(1, 0), a3, voffA);
;             PG8_WAIT_V(8); PG8_WAIT_L(0); PG8_BAR; PG8_MMA(1, 0, At, B0); PG8_MMA(1, 1, At, B1); PG8_BAR; PG8_SCHED;
	s_add_i32 s16, s31, s22
	s_add_u32 s36, s2, 0x80
	s_addc_u32 s37, s3, 0
	s_mov_b32 m0, s16
	ds_read_b128 v[194:197], v159 offset:49152
	ds_read_b128 v[208:211], v159 offset:50176
	ds_read_b128 v[212:215], v159 offset:51200
	ds_read_b128 v[216:219], v159 offset:52224
	ds_read_b128 v[220:223], v159 offset:53248
	ds_read_b128 v[224:227], v159 offset:54272
	ds_read_b128 v[228:231], v159 offset:55296
	ds_read_b128 v[232:235], v159 offset:56320
	global_load_lds_dwordx4 v64, s[36:37]
	s_add_i32 m0, s16, 0x2000
	s_add_u32 s2, s2, 0x40080
	s_addc_u32 s3, s3, 0
	s_add_i32 s16, s33, s22
	global_load_lds_dwordx4 v138, s[36:37]
	s_mov_b32 m0, s16
	s_nop 0
	global_load_lds_dwordx4 v64, s[2:3]
	s_add_i32 m0, s16, 0x2000
	s_nop 0
	global_load_lds_dwordx4 v138, s[2:3]
	s_add_u32 s100, s100, 0x80
	s_addc_u32 s101, s101, 0
	s_mov_b32 m0, s27
	s_nop 0
	global_load_lds_dwordx4 v142, s[100:101]
	s_mov_b32 m0, s28
	s_nop 0
	global_load_lds_dwordx4 v140, s[100:101]
	s_waitcnt vmcnt(8)
	s_waitcnt lgkmcnt(0)
	s_barrier
	s_setprio 1
	s_waitcnt lgkmcnt(0)
	v_mfma_f32_16x16x32_bf16 v[60:63], v[130:133], v[194:197], v[60:63]
	v_mfma_f32_16x16x32_bf16 v[56:59], v[148:151], v[194:197], v[56:59]
	v_mfma_f32_16x16x32_bf16 v[44:47], v[130:133], v[212:215], v[44:47]
	v_mfma_f32_16x16x32_bf16 v[40:43], v[148:151], v[212:215], v[40:43]
	s_setprio 0
	s_setprio 1
	v_mfma_f32_16x16x32_bf16 v[28:31], v[130:133], v[220:223], v[28:31]
	v_mfma_f32_16x16x32_bf16 v[24:27], v[148:151], v[220:223], v[24:27]
	v_mfma_f32_16x16x32_bf16 v[12:15], v[130:133], v[228:231], v[12:15]
	v_mfma_f32_16x16x32_bf16 v[8:11], v[148:151], v[228:231], v[8:11]
	s_setprio 0
	s_setprio 1
	v_mfma_f32_16x16x32_bf16 v[60:63], v[134:137], v[208:211], v[60:63]
	v_mfma_f32_16x16x32_bf16 v[56:59], v[152:155], v[208:211], v[56:59]
	v_mfma_f32_16x16x32_bf16 v[44:47], v[134:137], v[216:219], v[44:47]
	v_mfma_f32_16x16x32_bf16 v[40:43], v[152:155], v[216:219], v[40:43]
	s_setprio 0
	s_setprio 1
	v_mfma_f32_16x16x32_bf16 v[28:31], v[134:137], v[224:227], v[28:31]
	v_mfma_f32_16x16x32_bf16 v[24:27], v[152:155], v[224:227], v[24:27]
	v_mfma_f32_16x16x32_bf16 v[12:15], v[134:137], v[232:235], v[12:15]
	v_mfma_f32_16x16x32_bf16 v[8:11], v[152:155], v[232:235], v[8:11]
	s_setprio 0
	s_setprio 1
	v_mfma_f32_16x16x32_bf16 v[52:55], v[178:181], v[194:197], v[52:55]
	v_mfma_f32_16x16x32_bf16 v[48:51], v[186:189], v[194:197], v[48:51]
	v_mfma_f32_16x16x32_bf16 v[36:39], v[178:181], v[212:215], v[36:39]
	v_mfma_f32_16x16x32_bf16 v[32:35], v[186:189], v[212:215], v[32:35]
	v_mfma_f32_16x16x32_bf16 v[20:23], v[178:181], v[220:223], v[20:23]
	v_mfma_f32_16x16x32_bf16 v[16:19], v[186:189], v[220:223], v[16:19]
	v_mfma_f32_16x16x32_bf16 v[4:7], v[178:181], v[228:231], v[4:7]
	v_mfma_f32_16x16x32_bf16 v[0:3], v[186:189], v[228:231], v[0:3]
	s_setprio 0
	s_setprio 1
	v_mfma_f32_16x16x32_bf16 v[52:55], v[182:185], v[208:211], v[52:55]
	v_mfma_f32_16x16x32_bf16 v[48:51], v[190:193], v[208:211], v[48:51]
	v_mfma_f32_16x16x32_bf16 v[36:39], v[182:185], v[216:219], v[36:39]
	v_mfma_f32_16x16x32_bf16 v[32:35], v[190:193], v[216:219], v[32:35]
	v_mfma_f32_16x16x32_bf16 v[20:23], v[182:185], v[224:227], v[20:23]
	v_mfma_f32_16x16x32_bf16 v[16:19], v[190:193], v[224:227], v[16:19]
	v_mfma_f32_16x16x32_bf16 v[4:7], v[182:185], v[232:235], v[4:7]
	v_mfma_f32_16x16x32_bf16 v[0:3], v[190:193], v[232:235], v[0:3]
	s_setprio 0
	s_barrier
	s_add_i32 s19, s19, 2
	s_add_u32 s0, s0, 0x100
	s_addc_u32 s1, s1, 0
	s_add_u32 s13, s13, 0x100
	s_addc_u32 s18, s18, 0
	s_cmp_gt_u32 s19, 13
	s_cbranch_scc0 .LBB0_1178
	s_mov_b64 s[36:37], 0x80
	s_and_b64 vcc, exec, s[6:7]
	s_cbranch_vccz .LBB0_1181
	s_barrier

; #define PG8_STAGE(bufoff, gbase, voff) do { _Pragma("unroll") for (int _i = 0; _i < 2; ++_i) \
;         __builtin_amdgcn_global_load_lds((const unsigned*)((const char*)(gbase) + (voff)[_i]), (PG8_LAS unsigned*)(lds + (bufoff) + ldsw + _i * 8192), 16, 0, 0); } while (0)
; #define PG8_LDA(dst, b, h) do { _Pragma("unroll") for (int m = 0; m < 4; ++m) _Pragma("unroll") for (int k = 0; k < 2; ++k) dst[m][k] = *(const PG8_LAS bf16x8*)(lds + PG8_SA(b, h) + aoff + m * 2048 + k * 1024); } while (0)
; #define PG8_LDB(dst, b, h) do { _Pragma("unroll") for (int n = 0; n < 2; ++n) _Pragma("unroll") for (int k = 0; k < 2; ++k) dst[n][k] = *(const PG8_LAS bf16x8*)(lds + PG8_SB(b, h) + boff + n * 2048 + k * 1024); } while (0)
; #define PG8_MMA(ai, bj, At, Bt) do { __builtin_amdgcn_s_setprio(1); _Pragma("unroll") for (int m = 0; m < 4; ++m) _Pragma("unroll") for (int n = 0; n < 2; ++n) _Pragma("unroll") for (int k = 0; k < 2; ++k) \
;         acc[ai][bj][m][n] = __builtin_amdgcn_mfma_f32_16x16x32_bf16(Bt[n][k], At[m][k], acc[ai][bj][m][n], 0, 0, 0); __builtin_amdgcn_s_setprio(0); } while (0)
; #define PG8_WAIT_V(n) asm volatile("s_waitcnt vmcnt(" #n ")" ::: "memory")
; #define PG8_BAR __builtin_amdgcn_s_barrier()
; template <class Epi, class Sched, bool ALIGN_EPI = false, bool SP2 = false>
; __device__ __forceinline__ void gemm_phase(PG8_LAS unsigned char* lds, const Gemm g, const Sched& S, const Epi& E, const int wave0) {
;     ...
;         for (int t = 0; t < nt; t += 2) {
;             const bool last = (t == nt - 2);
;             const char* a1 = cA + (size_t)(t + 1) * kstep;
;             const char* a2 = last ? nA : cA + (size_t)(t + 2) * kstep; const char* b2 = last ? nB : cB + (size_t)(t + 2) * kstep;
;             const char* a3 = a2 + kstep; const char* b3 = b2 + kstep;
;             if (last && has_next) S.a_ready(nxt);
;             if constexpr (SP2) {
;             PG8_LDB(B0, 0, 0); PG8_LDB(B1, 0, 1); PG8_SCHED; PG8_LDA(At, 0, 0); PG8_STAGE(PG8_SA(1, 1), a1 + hstepA, voffA);
;             PG8_WAIT_V(8); PG8_WAIT_L(0); PG8_BAR; PG8_MMA(0, 0, At, B0); PG8_MMA(0, 1, At, B1); PG8_BAR; PG8_SCHED;
;             PG8_LDA(At, 0, 1); PG8_STAGE(PG8_SB(0, 0), b2, voffB); PG8_STAGE(PG8_SB(0, 1), b2 + hstepB, voffB); PG8_STAGE(PG8_SA(0, 0), a2, voffA);
;             PG8_WAIT_V(8); PG8_WAIT_L(0); PG8_BAR; PG8_MMA(1, 0, At, B0); PG8_MMA(1, 1, At, B1); PG8_BAR; PG8_SCHED;
.LBB0_1231:
	s_add_u32 s2, s0, 0xfffc0080
	s_addc_u32 s3, s1, -1
	s_add_i32 s31, 0, 0x10000
	s_cmp_eq_u32 s19, 12
	s_cselect_b32 s17, s43, s3
	s_cselect_b32 s16, s42, s2
	s_cselect_b32 s3, s9, s18
	s_cselect_b32 s2, s11, s13
	s_add_i32 s33, 0, 0x14000
	ds_read_b128 v[140:143], v252
	ds_read_b128 v[144:147], v252 offset:1024
	ds_read_b128 v[154:157], v252 offset:2048
	ds_read_b128 v[158:161], v252 offset:3072
	ds_read_b128 v[178:181], v253
	ds_read_b128 v[182:185], v253 offset:1024
	ds_read_b128 v[186:189], v253 offset:2048
	ds_read_b128 v[190:193], v253 offset:3072
	s_add_i32 m0, s23, 0xc000
	ds_read_b128 v[194:197], v153
	ds_read_b128 v[208:211], v153 offset:1024
	ds_read_b128 v[212:215], v153 offset:2048
	ds_read_b128 v[216:219], v153 offset:3072
	ds_read_b128 v[220:223], v153 offset:4096
	ds_read_b128 v[224:227], v153 offset:5120
	ds_read_b128 v[228:231], v153 offset:6144
	ds_read_b128 v[232:235], v153 offset:7168
	global_load_lds_dwordx4 v136, s[0:1]
	s_add_i32 m0, s23, 0xe000
	s_nop 0
	global_load_lds_dwordx4 v138, s[0:1]
	s_waitcnt vmcnt(8)
	s_waitcnt lgkmcnt(0)
	s_barrier
	s_setprio 1
	s_waitcnt lgkmcnt(0)
	v_mfma_f32_16x16x32_bf16 v[126:129], v[140:143], v[194:197], v[126:129]
	v_mfma_f32_16x16x32_bf16 v[122:125], v[154:157], v[194:197], v[122:125]
	v_mfma_f32_16x16x32_bf16 v[110:113], v[140:143], v[212:215], v[110:113]
	v_mfma_f32_16x16x32_bf16 v[106:109], v[154:157], v[212:215], v[106:109]
	s_setprio 0
	s_setprio 1
	v_mfma_f32_16x16x32_bf16 v[94:97], v[140:143], v[220:223], v[94:97]
	v_mfma_f32_16x16x32_bf16 v[90:93], v[154:157], v[220:223], v[90:93]
	v_mfma_f32_16x16x32_bf16 v[78:81], v[140:143], v[228:231], v[78:81]
	v_mfma_f32_16x16x32_bf16 v[74:77], v[154:157], v[228:231], v[74:77]
	s_setprio 0
	s_setprio 1
	v_mfma_f32_16x16x32_bf16 v[126:129], v[144:147], v[208:211], v[126:129]
	v_mfma_f32_16x16x32_bf16 v[122:125], v[158:161], v[208:211], v[122:125]
	v_mfma_f32_16x16x32_bf16 v[110:113], v[144:147], v[216:219], v[110:113]
	v_mfma_f32_16x16x32_bf16 v[106:109], v[158:161], v[216:219], v[106:109]
	s_setprio 0
	s_setprio 1
	v_mfma_f32_16x16x32_bf16 v[94:97], v[144:147], v[224:227], v[94:97]
	v_mfma_f32_16x16x32_bf16 v[90:93], v[158:161], v[224:227], v[90:93]
	v_mfma_f32_16x16x32_bf16 v[78:81], v[144:147], v[232:235], v[78:81]
	v_mfma_f32_16x16x32_bf16 v[74:77], v[158:161], v[232:235], v[74:77]
	s_setprio 0
	s_setprio 1
	v_mfma_f32_16x16x32_bf16 v[118:121], v[178:181], v[194:197], v[118:121]
	v_mfma_f32_16x16x32_bf16 v[114:117], v[186:189], v[194:197], v[114:117]
	v_mfma_f32_16x16x32_bf16 v[102:105], v[178:181], v[212:215], v[102:105]
	v_mfma_f32_16x16x32_bf16 v[98:101], v[186:189], v[212:215], v[98:101]
	v_mfma_f32_16x16x32_bf16 v[86:89], v[178:181], v[220:223], v[86:89]
	v_mfma_f32_16x16x32_bf16 v[82:85], v[186:189], v[220:223], v[82:85]
	v_mfma_f32_16x16x32_bf16 v[70:73], v[178:181], v[228:231], v[70:73]
	v_mfma_f32_16x16x32_bf16 v[66:69], v[186:189], v[228:231], v[66:69]
	s_setprio 0
	s_setprio 1
	v_mfma_f32_16x16x32_bf16 v[118:121], v[182:185], v[208:211], v[118:121]
	v_mfma_f32_16x16x32_bf16 v[114:117], v[190:193], v[208:211], v[114:117]
	v_mfma_f32_16x16x32_bf16 v[102:105], v[182:185], v[216:219], v[102:105]
	v_mfma_f32_16x16x32_bf16 v[98:101], v[190:193], v[216:219], v[98:101]
	v_mfma_f32_16x16x32_bf16 v[86:89], v[182:185], v[224:227], v[86:89]
	v_mfma_f32_16x16x32_bf16 v[82:85], v[190:193], v[224:227], v[82:85]
	v_mfma_f32_16x16x32_bf16 v[70:73], v[182:185], v[232:235], v[70:73]
	v_mfma_f32_16x16x32_bf16 v[66:69], v[190:193], v[232:235], v[66:69]
	s_setprio 0
	s_barrier
	s_add_i32 s31, s31, s22
	s_mov_b32 m0, s31
	ds_read_b128 v[194:197], v153 offset:16384
	ds_read_b128 v[208:211], v153 offset:17408
	ds_read_b128 v[212:215], v153 offset:18432
	ds_read_b128 v[216:219], v153 offset:19456
	ds_read_b128 v[220:223], v153 offset:20480
	ds_read_b128 v[224:227], v153 offset:21504
	ds_read_b128 v[228:231], v153 offset:22528
	ds_read_b128 v[232:235], v153 offset:23552
	global_load_lds_dwordx4 v64, s[2:3]
	s_add_i32 m0, s31, 0x2000
	s_add_u32 s34, s2, 0x40000
	s_addc_u32 s35, s3, 0
	s_add_i32 s31, s33, s22
	global_load_lds_dwordx4 v130, s[2:3]
	s_mov_b32 m0, s31
	s_mov_b64 s[100:101], s[16:17]
	global_load_lds_dwordx4 v64, s[34:35]
	s_add_i32 m0, s31, 0x2000
	s_nop 0
	global_load_lds_dwordx4 v130, s[34:35]
	s_mov_b32 m0, s23
	s_nop 0
	global_load_lds_dwordx4 v134, s[16:17]
	s_mov_b32 m0, s24
	s_nop 0
	global_load_lds_dwordx4 v132, s[16:17]
	s_waitcnt vmcnt(8)
	s_waitcnt lgkmcnt(0)
	s_barrier
; #define PG8_STAGE(bufoff, gbase, voff) do { _Pragma("unroll") for (int _i = 0; _i < 2; ++_i) \
;         __builtin_amdgcn_global_load_lds((const unsigned*)((const char*)(gbase) + (voff)[_i]), (PG8_LAS unsigned*)(lds + (bufoff) + ldsw + _i * 8192), 16, 0, 0); } while (0)
; #define PG8_LDA(dst, b, h) do { _Pragma("unroll") for (int m = 0; m < 4; ++m) _Pragma("unroll") for (int k = 0; k < 2; ++k) dst[m][k] = *(const PG8_LAS bf16x8*)(lds + PG8_SA(b, h) + aoff + m * 2048 + k * 1024); } while (0)
; #define PG8_LDB(dst, b, h) do { _Pragma("unroll") for (int n = 0; n < 2; ++n) _Pragma("unroll") for (int k = 0; k < 2; ++k) dst[n][k] = *(const PG8_LAS bf16x8*)(lds + PG8_SB(b, h) + boff + n * 2048 + k * 1024); } while (0)
; #define PG8_MMA(ai, bj, At, Bt) do { __builtin_amdgcn_s_setprio(1); _Pragma("unroll") for (int m = 0; m < 4; ++m) _Pragma("unroll") for (int n = 0; n < 2; ++n) _Pragma("unroll") for (int k = 0; k < 2; ++k) \
;         acc[ai][bj][m][n] = __builtin_amdgcn_mfma_f32_16x16x32_bf16(Bt[n][k], At[m][k], acc[ai][bj][m][n], 0, 0, 0); __builtin_amdgcn_s_setprio(0); } while (0)
; #define PG8_WAIT_V(n) asm volatile("s_waitcnt vmcnt(" #n ")" ::: "memory")
; #define PG8_WAIT_L(n) asm volatile("s_waitcnt lgkmcnt(" #n ")" ::: "memory")
; #define PG8_BAR __builtin_amdgcn_s_barrier()
; #define PG8_SCHED __builtin_amdgcn_sched_barrier(0)
; template <class Epi, class Sched, bool ALIGN_EPI = false, bool SP2 = false>
; __device__ __forceinline__ void gemm_phase(PG8_LAS unsigned char* lds, const Gemm g, const Sched& S, const Epi& E, const int wave0) {
;     ...
;             PG8_WAIT_V(8); PG8_WAIT_L(0); PG8_BAR; PG8_MMA(1, 0, At, B0); PG8_MMA(1, 1, At, B1); PG8_BAR; PG8_SCHED;
;             PG8_LDB(B0, 1, 0); PG8_LDB(B1, 1, 1); PG8_SCHED; PG8_LDA(At, 1, 0); PG8_STAGE(PG8_SA(0, 1), a2 + hstepA, voffA);
;             PG8_WAIT_V(8); PG8_WAIT_L(0); PG8_BAR; PG8_MMA(0, 0, At, B0); PG8_MMA(0, 1, At, B1); PG8_BAR; PG8_SCHED;
	s_setprio 1
	s_waitcnt lgkmcnt(0)
	v_mfma_f32_16x16x32_bf16 v[60:63], v[140:143], v[194:197], v[60:63]
	v_mfma_f32_16x16x32_bf16 v[56:59], v[154:157], v[194:197], v[56:59]
	v_mfma_f32_16x16x32_bf16 v[44:47], v[140:143], v[212:215], v[44:47]
	v_mfma_f32_16x16x32_bf16 v[40:43], v[154:157], v[212:215], v[40:43]
	s_setprio 0
	s_setprio 1
	v_mfma_f32_16x16x32_bf16 v[28:31], v[140:143], v[220:223], v[28:31]
	v_mfma_f32_16x16x32_bf16 v[24:27], v[154:157], v[220:223], v[24:27]
	v_mfma_f32_16x16x32_bf16 v[12:15], v[140:143], v[228:231], v[12:15]
	v_mfma_f32_16x16x32_bf16 v[8:11], v[154:157], v[228:231], v[8:11]
	s_setprio 0
	s_setprio 1
	v_mfma_f32_16x16x32_bf16 v[60:63], v[144:147], v[208:211], v[60:63]
	v_mfma_f32_16x16x32_bf16 v[56:59], v[158:161], v[208:211], v[56:59]
	v_mfma_f32_16x16x32_bf16 v[44:47], v[144:147], v[216:219], v[44:47]
	v_mfma_f32_16x16x32_bf16 v[40:43], v[158:161], v[216:219], v[40:43]
	s_setprio 0
	s_setprio 1
	v_mfma_f32_16x16x32_bf16 v[28:31], v[144:147], v[224:227], v[28:31]
	v_mfma_f32_16x16x32_bf16 v[24:27], v[158:161], v[224:227], v[24:27]
	v_mfma_f32_16x16x32_bf16 v[12:15], v[144:147], v[232:235], v[12:15]
	v_mfma_f32_16x16x32_bf16 v[8:11], v[158:161], v[232:235], v[8:11]
	s_setprio 0
	s_setprio 1
	v_mfma_f32_16x16x32_bf16 v[52:55], v[178:181], v[194:197], v[52:55]
	v_mfma_f32_16x16x32_bf16 v[48:51], v[186:189], v[194:197], v[48:51]
	v_mfma_f32_16x16x32_bf16 v[36:39], v[178:181], v[212:215], v[36:39]
	v_mfma_f32_16x16x32_bf16 v[32:35], v[186:189], v[212:215], v[32:35]
	v_mfma_f32_16x16x32_bf16 v[20:23], v[178:181], v[220:223], v[20:23]
	v_mfma_f32_16x16x32_bf16 v[16:19], v[186:189], v[220:223], v[16:19]
	v_mfma_f32_16x16x32_bf16 v[4:7], v[178:181], v[228:231], v[4:7]
	v_mfma_f32_16x16x32_bf16 v[0:3], v[186:189], v[228:231], v[0:3]
	s_setprio 0
	s_setprio 1
	v_mfma_f32_16x16x32_bf16 v[52:55], v[182:185], v[208:211], v[52:55]
	v_mfma_f32_16x16x32_bf16 v[48:51], v[190:193], v[208:211], v[48:51]
	v_mfma_f32_16x16x32_bf16 v[36:39], v[182:185], v[216:219], v[36:39]
	v_mfma_f32_16x16x32_bf16 v[32:35], v[190:193], v[216:219], v[32:35]
	v_mfma_f32_16x16x32_bf16 v[20:23], v[182:185], v[224:227], v[20:23]
	v_mfma_f32_16x16x32_bf16 v[16:19], v[190:193], v[224:227], v[16:19]
	v_mfma_f32_16x16x32_bf16 v[4:7], v[182:185], v[232:235], v[4:7]
	v_mfma_f32_16x16x32_bf16 v[0:3], v[190:193], v[232:235], v[0:3]
	s_setprio 0
	s_barrier
	s_add_i32 s31, 0, 0x18000
	s_add_i32 s33, 0, 0x1c000
	ds_read_b128 v[140:143], v254
	ds_read_b128 v[144:147], v254 offset:1024
	ds_read_b128 v[154:157], v254 offset:2048
	ds_read_b128 v[158:161], v254 offset:3072
	ds_read_b128 v[178:181], v255
	ds_read_b128 v[182:185], v255 offset:1024
	ds_read_b128 v[186:189], v255 offset:2048
	ds_read_b128 v[190:193], v255 offset:3072
	s_add_u32 s16, s16, 0x40000
	s_addc_u32 s17, s17, 0
	s_mov_b32 m0, s25
	ds_read_b128 v[194:197], v153 offset:32768
	ds_read_b128 v[208:211], v153 offset:33792
	ds_read_b128 v[212:215], v153 offset:34816
	ds_read_b128 v[216:219], v153 offset:35840
	ds_read_b128 v[220:223], v153 offset:36864
	ds_read_b128 v[224:227], v153 offset:37888
	ds_read_b128 v[228:231], v153 offset:38912
	ds_read_b128 v[232:235], v153 offset:39936
	global_load_lds_dwordx4 v134, s[16:17]
	s_mov_b32 m0, s26
	s_nop 0
	global_load_lds_dwordx4 v132, s[16:17]
	s_waitcnt vmcnt(8)
	s_waitcnt lgkmcnt(0)
	s_barrier
	s_setprio 1
	s_waitcnt lgkmcnt(0)
	v_mfma_f32_16x16x32_bf16 v[126:129], v[140:143], v[194:197], v[126:129]
	v_mfma_f32_16x16x32_bf16 v[122:125], v[154:157], v[194:197], v[122:125]
	v_mfma_f32_16x16x32_bf16 v[110:113], v[140:143], v[212:215], v[110:113]
	v_mfma_f32_16x16x32_bf16 v[106:109], v[154:157], v[212:215], v[106:109]
	s_setprio 0
	s_setprio 1
	v_mfma_f32_16x16x32_bf16 v[94:97], v[140:143], v[220:223], v[94:97]
	v_mfma_f32_16x16x32_bf16 v[90:93], v[154:157], v[220:223], v[90:93]
	v_mfma_f32_16x16x32_bf16 v[78:81], v[140:143], v[228:231], v[78:81]
	v_mfma_f32_16x16x32_bf16 v[74:77], v[154:157], v[228:231], v[74:77]
	s_setprio 0
	s_setprio 1
	v_mfma_f32_16x16x32_bf16 v[126:129], v[144:147], v[208:211], v[126:129]
	v_mfma_f32_16x16x32_bf16 v[122:125], v[158:161], v[208:211], v[122:125]
	v_mfma_f32_16x16x32_bf16 v[110:113], v[144:147], v[216:219], v[110:113]
	v_mfma_f32_16x16x32_bf16 v[106:109], v[158:161], v[216:219], v[106:109]
	s_setprio 0
	s_setprio 1
	v_mfma_f32_16x16x32_bf16 v[94:97], v[144:147], v[224:227], v[94:97]
	v_mfma_f32_16x16x32_bf16 v[90:93], v[158:161], v[224:227], v[90:93]
	v_mfma_f32_16x16x32_bf16 v[78:81], v[144:147], v[232:235], v[78:81]
	v_mfma_f32_16x16x32_bf16 v[74:77], v[158:161], v[232:235], v[74:77]
	s_setprio 0
	s_setprio 1
	v_mfma_f32_16x16x32_bf16 v[118:121], v[178:181], v[194:197], v[118:121]
	v_mfma_f32_16x16x32_bf16 v[114:117], v[186:189], v[194:197], v[114:117]
	v_mfma_f32_16x16x32_bf16 v[102:105], v[178:181], v[212:215], v[102:105]
	v_mfma_f32_16x16x32_bf16 v[98:101], v[186:189], v[212:215], v[98:101]
	v_mfma_f32_16x16x32_bf16 v[86:89], v[178:181], v[220:223], v[86:89]
	v_mfma_f32_16x16x32_bf16 v[82:85], v[186:189], v[220:223], v[82:85]
	v_mfma_f32_16x16x32_bf16 v[70:73], v[178:181], v[228:231], v[70:73]
	v_mfma_f32_16x16x32_bf16 v[66:69], v[186:189], v[228:231], v[66:69]
	s_setprio 0
	s_setprio 1
	v_mfma_f32_16x16x32_bf16 v[118:121], v[182:185], v[208:211], v[118:121]
	v_mfma_f32_16x16x32_bf16 v[114:117], v[190:193], v[208:211], v[114:117]
	v_mfma_f32_16x16x32_bf16 v[102:105], v[182:185], v[216:219], v[102:105]
	v_mfma_f32_16x16x32_bf16 v[98:101], v[190:193], v[216:219], v[98:101]
	v_mfma_f32_16x16x32_bf16 v[86:89], v[182:185], v[224:227], v[86:89]
	v_mfma_f32_16x16x32_bf16 v[82:85], v[190:193], v[224:227], v[82:85]
	v_mfma_f32_16x16x32_bf16 v[70:73], v[182:185], v[232:235], v[70:73]
	v_mfma_f32_16x16x32_bf16 v[66:69], v[190:193], v[232:235], v[66:69]
	s_setprio 0
	s_barrier
; #define PG8_STAGE(bufoff, gbase, voff) do { _Pragma("unroll") for (int _i = 0; _i < 2; ++_i) \
;         __builtin_amdgcn_global_load_lds((const unsigned*)((const char*)(gbase) + (voff)[_i]), (PG8_LAS unsigned*)(lds + (bufoff) + ldsw + _i * 8192), 16, 0, 0); } while (0)
; #define PG8_LDA(dst, b, h) do { _Pragma("unroll") for (int m = 0; m < 4; ++m) _Pragma("unroll") for (int k = 0; k < 2; ++k) dst[m][k] = *(const PG8_LAS bf16x8*)(lds + PG8_SA(b, h) + aoff + m * 2048 + k * 1024); } while (0)
; #define PG8_MMA(ai, bj, At, Bt) do { __builtin_amdgcn_s_setprio(1); _Pragma("unroll") for (int m = 0; m < 4; ++m) _Pragma("unroll") for (int n = 0; n < 2; ++n) _Pragma("unroll") for (int k = 0; k < 2; ++k) \
;         acc[ai][bj][m][n] = __builtin_amdgcn_mfma_f32_16x16x32_bf16(Bt[n][k], At[m][k], acc[ai][bj][m][n], 0, 0, 0); __builtin_amdgcn_s_setprio(0); } while (0)
; #define PG8_WAIT_V(n) asm volatile("s_waitcnt vmcnt(" #n ")" ::: "memory")
; #define PG8_WAIT_L(n) asm volatile("s_waitcnt lgkmcnt(" #n ")" ::: "memory")
; #define PG8_BAR __builtin_amdgcn_s_barrier()
; #define PG8_SCHED __builtin_amdgcn_sched_barrier(0)
; template <class Epi, class Sched, bool ALIGN_EPI = false, bool SP2 = false>
; __device__ __forceinline__ void gemm_phase(PG8_LAS unsigned char* lds, const Gemm g, const Sched& S, const Epi& E, const int wave0) {
;     ...
;         for (int t = 0; t < nt; t += 2) {
;             const bool last = (t == nt - 2);
;             const char* a1 = cA + (size_t)(t + 1) * kstep;
;             const char* a2 = last ? nA : cA + (size_t)(t + 2) * kstep; const char* b2 = last ? nB : cB + (size_t)(t + 2) * kstep;
;     ...
;             PG8_LDA(At, 1, 1); PG8_STAGE(PG8_SB(1, 0), b3, voffB); PG8_STAGE(PG8_SB(1, 1), b3 + hstepB, voffB); PG8_STAGE(PG8_SA(1, 0), a3, voffA);
;             PG8_WAIT_V(8); PG8_WAIT_L(0); PG8_BAR; PG8_MMA(1, 0, At, B0); PG8_MMA(1, 1, At, B1); PG8_BAR; PG8_SCHED;
	s_add_i32 s16, s31, s22
	s_add_u32 s36, s2, 0x80
	s_addc_u32 s37, s3, 0
	s_mov_b32 m0, s16
	ds_read_b128 v[194:197], v153 offset:49152
	ds_read_b128 v[208:211], v153 offset:50176
	ds_read_b128 v[212:215], v153 offset:51200
	ds_read_b128 v[216:219], v153 offset:52224
	ds_read_b128 v[220:223], v153 offset:53248
	ds_read_b128 v[224:227], v153 offset:54272
	ds_read_b128 v[228:231], v153 offset:55296
	ds_read_b128 v[232:235], v153 offset:56320
	global_load_lds_dwordx4 v64, s[36:37]
	s_add_i32 m0, s16, 0x2000
	s_add_u32 s2, s2, 0x40080
	s_addc_u32 s3, s3, 0
	s_add_i32 s16, s33, s22
	global_load_lds_dwordx4 v130, s[36:37]
	s_mov_b32 m0, s16
	s_nop 0
	global_load_lds_dwordx4 v64, s[2:3]
	s_add_i32 m0, s16, 0x2000
	s_nop 0
	global_load_lds_dwordx4 v130, s[2:3]
	s_add_u32 s100, s100, 0x80
	s_addc_u32 s101, s101, 0
	s_mov_b32 m0, s27
	s_nop 0
	global_load_lds_dwordx4 v134, s[100:101]
	s_mov_b32 m0, s28
	s_nop 0
	global_load_lds_dwordx4 v132, s[100:101]
	s_waitcnt vmcnt(8)
	s_waitcnt lgkmcnt(0)
	s_barrier
	s_setprio 1
	s_waitcnt lgkmcnt(0)
	v_mfma_f32_16x16x32_bf16 v[60:63], v[140:143], v[194:197], v[60:63]
	v_mfma_f32_16x16x32_bf16 v[56:59], v[154:157], v[194:197], v[56:59]
	v_mfma_f32_16x16x32_bf16 v[44:47], v[140:143], v[212:215], v[44:47]
	v_mfma_f32_16x16x32_bf16 v[40:43], v[154:157], v[212:215], v[40:43]
	s_setprio 0
	s_setprio 1
	v_mfma_f32_16x16x32_bf16 v[28:31], v[140:143], v[220:223], v[28:31]
	v_mfma_f32_16x16x32_bf16 v[24:27], v[154:157], v[220:223], v[24:27]
	v_mfma_f32_16x16x32_bf16 v[12:15], v[140:143], v[228:231], v[12:15]
	v_mfma_f32_16x16x32_bf16 v[8:11], v[154:157], v[228:231], v[8:11]
	s_setprio 0
	s_setprio 1
	v_mfma_f32_16x16x32_bf16 v[60:63], v[144:147], v[208:211], v[60:63]
	v_mfma_f32_16x16x32_bf16 v[56:59], v[158:161], v[208:211], v[56:59]
	v_mfma_f32_16x16x32_bf16 v[44:47], v[144:147], v[216:219], v[44:47]
	v_mfma_f32_16x16x32_bf16 v[40:43], v[158:161], v[216:219], v[40:43]
	s_setprio 0
	s_setprio 1
	v_mfma_f32_16x16x32_bf16 v[28:31], v[144:147], v[224:227], v[28:31]
	v_mfma_f32_16x16x32_bf16 v[24:27], v[158:161], v[224:227], v[24:27]
	v_mfma_f32_16x16x32_bf16 v[12:15], v[144:147], v[232:235], v[12:15]
	v_mfma_f32_16x16x32_bf16 v[8:11], v[158:161], v[232:235], v[8:11]
	s_setprio 0
	s_setprio 1
	v_mfma_f32_16x16x32_bf16 v[52:55], v[178:181], v[194:197], v[52:55]
	v_mfma_f32_16x16x32_bf16 v[48:51], v[186:189], v[194:197], v[48:51]
	v_mfma_f32_16x16x32_bf16 v[36:39], v[178:181], v[212:215], v[36:39]
	v_mfma_f32_16x16x32_bf16 v[32:35], v[186:189], v[212:215], v[32:35]
	v_mfma_f32_16x16x32_bf16 v[20:23], v[178:181], v[220:223], v[20:23]
	v_mfma_f32_16x16x32_bf16 v[16:19], v[186:189], v[220:223], v[16:19]
	v_mfma_f32_16x16x32_bf16 v[4:7], v[178:181], v[228:231], v[4:7]
	v_mfma_f32_16x16x32_bf16 v[0:3], v[186:189], v[228:231], v[0:3]
	s_setprio 0
	s_setprio 1
	v_mfma_f32_16x16x32_bf16 v[52:55], v[182:185], v[208:211], v[52:55]
	v_mfma_f32_16x16x32_bf16 v[48:51], v[190:193], v[208:211], v[48:51]
	v_mfma_f32_16x16x32_bf16 v[36:39], v[182:185], v[216:219], v[36:39]
	v_mfma_f32_16x16x32_bf16 v[32:35], v[190:193], v[216:219], v[32:35]
	v_mfma_f32_16x16x32_bf16 v[20:23], v[182:185], v[224:227], v[20:23]
	v_mfma_f32_16x16x32_bf16 v[16:19], v[190:193], v[224:227], v[16:19]
	v_mfma_f32_16x16x32_bf16 v[4:7], v[182:185], v[232:235], v[4:7]
	v_mfma_f32_16x16x32_bf16 v[0:3], v[190:193], v[232:235], v[0:3]
	s_setprio 0
	s_barrier
	s_add_i32 s19, s19, 2
	s_add_u32 s0, s0, 0x100
	s_addc_u32 s1, s1, 0
	s_add_u32 s13, s13, 0x100
	s_addc_u32 s18, s18, 0
	s_cmp_gt_u32 s19, 13
	s_cbranch_scc0 .LBB0_1231
	s_mov_b64 s[36:37], 0x80
	s_and_b64 vcc, exec, s[6:7]
	s_cbranch_vccz .LBB0_1234
	s_barrier

; #define PG8_STAGE(bufoff, gbase, voff) do { _Pragma("unroll") for (int _i = 0; _i < 2; ++_i) \
;         __builtin_amdgcn_global_load_lds((const unsigned*)((const char*)(gbase) + (voff)[_i]), (PG8_LAS unsigned*)(lds + (bufoff) + ldsw + _i * 8192), 16, 0, 0); } while (0)
; #define PG8_LDA(dst, b, h) do { _Pragma("unroll") for (int m = 0; m < 4; ++m) _Pragma("unroll") for (int k = 0; k < 2; ++k) dst[m][k] = *(const PG8_LAS bf16x8*)(lds + PG8_SA(b, h) + aoff + m * 2048 + k * 1024); } while (0)
; #define PG8_LDB(dst, b, h) do { _Pragma("unroll") for (int n = 0; n < 2; ++n) _Pragma("unroll") for (int k = 0; k < 2; ++k) dst[n][k] = *(const PG8_LAS bf16x8*)(lds + PG8_SB(b, h) + boff + n * 2048 + k * 1024); } while (0)
; #define PG8_MMA(ai, bj, At, Bt) do { __builtin_amdgcn_s_setprio(1); _Pragma("unroll") for (int m = 0; m < 4; ++m) _Pragma("unroll") for (int n = 0; n < 2; ++n) _Pragma("unroll") for (int k = 0; k < 2; ++k) \
;         acc[ai][bj][m][n] = __builtin_amdgcn_mfma_f32_16x16x32_bf16(Bt[n][k], At[m][k], acc[ai][bj][m][n], 0, 0, 0); __builtin_amdgcn_s_setprio(0); } while (0)
; #define PG8_WAIT_V(n) asm volatile("s_waitcnt vmcnt(" #n ")" ::: "memory")
; #define PG8_BAR __builtin_amdgcn_s_barrier()
; template <class Epi, class Sched, bool ALIGN_EPI = false, bool SP2 = false>
; __device__ __forceinline__ void gemm_phase(PG8_LAS unsigned char* lds, const Gemm g, const Sched& S, const Epi& E, const int wave0) {
;     ...
;         for (int t = 0; t < nt; t += 2) {
;             const bool last = (t == nt - 2);
;             const char* a1 = cA + (size_t)(t + 1) * kstep;
;             const char* a2 = last ? nA : cA + (size_t)(t + 2) * kstep; const char* b2 = last ? nB : cB + (size_t)(t + 2) * kstep;
;             const char* a3 = a2 + kstep; const char* b3 = b2 + kstep;
;             if (last && has_next) S.a_ready(nxt);
;             if constexpr (SP2) {
;             PG8_LDB(B0, 0, 0); PG8_LDB(B1, 0, 1); PG8_SCHED; PG8_LDA(At, 0, 0); PG8_STAGE(PG8_SA(1, 1), a1 + hstepA, voffA);
;             PG8_WAIT_V(8); PG8_WAIT_L(0); PG8_BAR; PG8_MMA(0, 0, At, B0); PG8_MMA(0, 1, At, B1); PG8_BAR; PG8_SCHED;
;             PG8_LDA(At, 0, 1); PG8_STAGE(PG8_SB(0, 0), b2, voffB); PG8_STAGE(PG8_SB(0, 1), b2 + hstepB, voffB); PG8_STAGE(PG8_SA(0, 0), a2, voffA);
;             PG8_WAIT_V(8); PG8_WAIT_L(0); PG8_BAR; PG8_MMA(1, 0, At, B0); PG8_MMA(1, 1, At, B1); PG8_BAR; PG8_SCHED;
.LBB0_1341:
	s_add_u32 s16, s0, 0xfff80080
	s_addc_u32 s17, s1, -1
	s_add_i32 s40, 0, 0x10000
	s_cmp_eq_u32 s37, 28
	s_cselect_b32 s19, s11, s17
	s_cselect_b32 s18, s33, s16
	s_cselect_b32 s17, s9, s36
	s_cselect_b32 s16, s34, s35
	s_add_i32 s42, 0, 0x14000
	ds_read_b128 v[144:147], v252
	ds_read_b128 v[148:151], v252 offset:1024
	ds_read_b128 v[152:155], v252 offset:2048
	ds_read_b128 v[156:159], v252 offset:3072
	ds_read_b128 v[178:181], v253
	ds_read_b128 v[182:185], v253 offset:1024
	ds_read_b128 v[186:189], v253 offset:2048
	ds_read_b128 v[190:193], v253 offset:3072
	s_add_i32 m0, s23, 0xc000
	ds_read_b128 v[194:197], v143
	ds_read_b128 v[208:211], v143 offset:1024
	ds_read_b128 v[212:215], v143 offset:2048
	ds_read_b128 v[216:219], v143 offset:3072
	ds_read_b128 v[220:223], v143 offset:4096
	ds_read_b128 v[224:227], v143 offset:5120
	ds_read_b128 v[228:231], v143 offset:6144
	ds_read_b128 v[232:235], v143 offset:7168
	global_load_lds_dwordx4 v136, s[0:1]
	s_add_i32 m0, s23, 0xe000
	s_nop 0
	global_load_lds_dwordx4 v138, s[0:1]
	s_waitcnt vmcnt(8)
	s_waitcnt lgkmcnt(0)
	s_barrier
	s_setprio 1
	s_waitcnt lgkmcnt(0)
	v_mfma_f32_16x16x32_bf16 v[126:129], v[144:147], v[194:197], v[126:129]
	v_mfma_f32_16x16x32_bf16 v[122:125], v[152:155], v[194:197], v[122:125]
	v_mfma_f32_16x16x32_bf16 v[118:121], v[144:147], v[212:215], v[118:121]
	v_mfma_f32_16x16x32_bf16 v[114:117], v[152:155], v[212:215], v[114:117]
	s_setprio 0
	s_setprio 1
	v_mfma_f32_16x16x32_bf16 v[102:105], v[144:147], v[220:223], v[102:105]
	v_mfma_f32_16x16x32_bf16 v[98:101], v[152:155], v[220:223], v[98:101]
	v_mfma_f32_16x16x32_bf16 v[86:89], v[144:147], v[228:231], v[86:89]
	v_mfma_f32_16x16x32_bf16 v[82:85], v[152:155], v[228:231], v[82:85]
	s_setprio 0
	s_setprio 1
	v_mfma_f32_16x16x32_bf16 v[126:129], v[148:151], v[208:211], v[126:129]
	v_mfma_f32_16x16x32_bf16 v[122:125], v[156:159], v[208:211], v[122:125]
	v_mfma_f32_16x16x32_bf16 v[118:121], v[148:151], v[216:219], v[118:121]
	v_mfma_f32_16x16x32_bf16 v[114:117], v[156:159], v[216:219], v[114:117]
	s_setprio 0
	s_setprio 1
	v_mfma_f32_16x16x32_bf16 v[102:105], v[148:151], v[224:227], v[102:105]
	v_mfma_f32_16x16x32_bf16 v[98:101], v[156:159], v[224:227], v[98:101]
	v_mfma_f32_16x16x32_bf16 v[86:89], v[148:151], v[232:235], v[86:89]
	v_mfma_f32_16x16x32_bf16 v[82:85], v[156:159], v[232:235], v[82:85]
	s_setprio 0
	s_setprio 1
	v_mfma_f32_16x16x32_bf16 v[110:113], v[178:181], v[194:197], v[110:113]
	v_mfma_f32_16x16x32_bf16 v[106:109], v[186:189], v[194:197], v[106:109]
	v_mfma_f32_16x16x32_bf16 v[94:97], v[178:181], v[212:215], v[94:97]
	v_mfma_f32_16x16x32_bf16 v[90:93], v[186:189], v[212:215], v[90:93]
	v_mfma_f32_16x16x32_bf16 v[78:81], v[178:181], v[220:223], v[78:81]
	v_mfma_f32_16x16x32_bf16 v[74:77], v[186:189], v[220:223], v[74:77]
	v_mfma_f32_16x16x32_bf16 v[70:73], v[178:181], v[228:231], v[70:73]
	v_mfma_f32_16x16x32_bf16 v[66:69], v[186:189], v[228:231], v[66:69]
	s_setprio 0
	s_setprio 1
	v_mfma_f32_16x16x32_bf16 v[110:113], v[182:185], v[208:211], v[110:113]
	v_mfma_f32_16x16x32_bf16 v[106:109], v[190:193], v[208:211], v[106:109]
	v_mfma_f32_16x16x32_bf16 v[94:97], v[182:185], v[216:219], v[94:97]
	v_mfma_f32_16x16x32_bf16 v[90:93], v[190:193], v[216:219], v[90:93]
	v_mfma_f32_16x16x32_bf16 v[78:81], v[182:185], v[224:227], v[78:81]
	v_mfma_f32_16x16x32_bf16 v[74:77], v[190:193], v[224:227], v[74:77]
	v_mfma_f32_16x16x32_bf16 v[70:73], v[182:185], v[232:235], v[70:73]
	v_mfma_f32_16x16x32_bf16 v[66:69], v[190:193], v[232:235], v[66:69]
	s_setprio 0
	s_barrier
	s_add_i32 s40, s40, s22
	s_mov_b32 m0, s40
	ds_read_b128 v[194:197], v143 offset:16384
	ds_read_b128 v[208:211], v143 offset:17408
	ds_read_b128 v[212:215], v143 offset:18432
	ds_read_b128 v[216:219], v143 offset:19456
	ds_read_b128 v[220:223], v143 offset:20480
	ds_read_b128 v[224:227], v143 offset:21504
	ds_read_b128 v[228:231], v143 offset:22528
	ds_read_b128 v[232:235], v143 offset:23552
	global_load_lds_dwordx4 v64, s[16:17]
	s_add_i32 m0, s40, 0x2000
	s_add_u32 s40, s16, 0x80000
	s_addc_u32 s41, s17, 0
	s_add_i32 s42, s42, s22
	global_load_lds_dwordx4 v130, s[16:17]
	s_mov_b32 m0, s42
	s_mov_b64 s[100:101], s[18:19]
	global_load_lds_dwordx4 v64, s[40:41]
	s_add_i32 m0, s42, 0x2000
	s_nop 0
	global_load_lds_dwordx4 v130, s[40:41]
	s_mov_b32 m0, s23
	s_nop 0
	global_load_lds_dwordx4 v134, s[18:19]
	s_mov_b32 m0, s24
	s_nop 0
	global_load_lds_dwordx4 v132, s[18:19]
	s_waitcnt vmcnt(8)
	s_waitcnt lgkmcnt(0)
	s_barrier
; #define PG8_STAGE(bufoff, gbase, voff) do { _Pragma("unroll") for (int _i = 0; _i < 2; ++_i) \
;         __builtin_amdgcn_global_load_lds((const unsigned*)((const char*)(gbase) + (voff)[_i]), (PG8_LAS unsigned*)(lds + (bufoff) + ldsw + _i * 8192), 16, 0, 0); } while (0)
; #define PG8_LDA(dst, b, h) do { _Pragma("unroll") for (int m = 0; m < 4; ++m) _Pragma("unroll") for (int k = 0; k < 2; ++k) dst[m][k] = *(const PG8_LAS bf16x8*)(lds + PG8_SA(b, h) + aoff + m * 2048 + k * 1024); } while (0)
; #define PG8_LDB(dst, b, h) do { _Pragma("unroll") for (int n = 0; n < 2; ++n) _Pragma("unroll") for (int k = 0; k < 2; ++k) dst[n][k] = *(const PG8_LAS bf16x8*)(lds + PG8_SB(b, h) + boff + n * 2048 + k * 1024); } while (0)
; #define PG8_MMA(ai, bj, At, Bt) do { __builtin_amdgcn_s_setprio(1); _Pragma("unroll") for (int m = 0; m < 4; ++m) _Pragma("unroll") for (int n = 0; n < 2; ++n) _Pragma("unroll") for (int k = 0; k < 2; ++k) \
;         acc[ai][bj][m][n] = __builtin_amdgcn_mfma_f32_16x16x32_bf16(Bt[n][k], At[m][k], acc[ai][bj][m][n], 0, 0, 0); __builtin_amdgcn_s_setprio(0); } while (0)
; template <class Epi, class Sched, bool ALIGN_EPI = false, bool SP2 = false>
; __device__ __forceinline__ void gemm_phase(PG8_LAS unsigned char* lds, const Gemm g, const Sched& S, const Epi& E, const int wave0) {
;     ...
;             if constexpr (SP2) {
;             PG8_LDB(B0, 0, 0); PG8_LDB(B1, 0, 1); PG8_SCHED; PG8_LDA(At, 0, 0); PG8_STAGE(PG8_SA(1, 1), a1 + hstepA, voffA);
;             PG8_WAIT_V(8); PG8_WAIT_L(0); PG8_BAR; PG8_MMA(0, 0, At, B0); PG8_MMA(0, 1, At, B1); PG8_BAR; PG8_SCHED;
;             PG8_LDA(At, 0, 1); PG8_STAGE(PG8_SB(0, 0), b2, voffB); PG8_STAGE(PG8_SB(0, 1), b2 + hstepB, voffB); PG8_STAGE(PG8_SA(0, 0), a2, voffA);
;             PG8_WAIT_V(8); PG8_WAIT_L(0); PG8_BAR; PG8_MMA(1, 0, At, B0); PG8_MMA(1, 1, At, B1); PG8_BAR; PG8_SCHED;
;             PG8_LDB(B0, 1, 0); PG8_LDB(B1, 1, 1); PG8_SCHED; PG8_LDA(At, 1, 0); PG8_STAGE(PG8_SA(0, 1), a2 + hstepA, voffA);
;             PG8_WAIT_V(8); PG8_WAIT_L(0); PG8_BAR; PG8_MMA(0, 0, At, B0); PG8_MMA(0, 1, At, B1); PG8_BAR; PG8_SCHED;
;             PG8_LDA(At, 1, 1); PG8_STAGE(PG8_SB(1, 0), b3, voffB); PG8_STAGE(PG8_SB(1, 1), b3 + hstepB, voffB); PG8_STAGE(PG8_SA(1, 0), a3, voffA);
;             PG8_WAIT_V(8); PG8_WAIT_L(0); PG8_BAR; PG8_MMA(1, 0, At, B0); PG8_MMA(1, 1, At, B1); PG8_BAR; PG8_SCHED;
	s_setprio 1
	s_waitcnt lgkmcnt(0)
	v_mfma_f32_16x16x32_bf16 v[60:63], v[144:147], v[194:197], v[60:63]
	v_mfma_f32_16x16x32_bf16 v[56:59], v[152:155], v[194:197], v[56:59]
	v_mfma_f32_16x16x32_bf16 v[52:55], v[144:147], v[212:215], v[52:55]
	v_mfma_f32_16x16x32_bf16 v[48:51], v[152:155], v[212:215], v[48:51]
	s_setprio 0
	s_setprio 1
	v_mfma_f32_16x16x32_bf16 v[36:39], v[144:147], v[220:223], v[36:39]
	v_mfma_f32_16x16x32_bf16 v[32:35], v[152:155], v[220:223], v[32:35]
	v_mfma_f32_16x16x32_bf16 v[20:23], v[144:147], v[228:231], v[20:23]
	v_mfma_f32_16x16x32_bf16 v[16:19], v[152:155], v[228:231], v[16:19]
	s_setprio 0
	s_setprio 1
	v_mfma_f32_16x16x32_bf16 v[60:63], v[148:151], v[208:211], v[60:63]
	v_mfma_f32_16x16x32_bf16 v[56:59], v[156:159], v[208:211], v[56:59]
	v_mfma_f32_16x16x32_bf16 v[52:55], v[148:151], v[216:219], v[52:55]
	v_mfma_f32_16x16x32_bf16 v[48:51], v[156:159], v[216:219], v[48:51]
	s_setprio 0
	s_setprio 1
	v_mfma_f32_16x16x32_bf16 v[36:39], v[148:151], v[224:227], v[36:39]
	v_mfma_f32_16x16x32_bf16 v[32:35], v[156:159], v[224:227], v[32:35]
	v_mfma_f32_16x16x32_bf16 v[20:23], v[148:151], v[232:235], v[20:23]
	v_mfma_f32_16x16x32_bf16 v[16:19], v[156:159], v[232:235], v[16:19]
	s_setprio 0
	s_setprio 1
	v_mfma_f32_16x16x32_bf16 v[44:47], v[178:181], v[194:197], v[44:47]
	v_mfma_f32_16x16x32_bf16 v[40:43], v[186:189], v[194:197], v[40:43]
	v_mfma_f32_16x16x32_bf16 v[28:31], v[178:181], v[212:215], v[28:31]
	v_mfma_f32_16x16x32_bf16 v[24:27], v[186:189], v[212:215], v[24:27]
	v_mfma_f32_16x16x32_bf16 v[12:15], v[178:181], v[220:223], v[12:15]
	v_mfma_f32_16x16x32_bf16 v[8:11], v[186:189], v[220:223], v[8:11]
	v_mfma_f32_16x16x32_bf16 v[4:7], v[178:181], v[228:231], v[4:7]
	v_mfma_f32_16x16x32_bf16 v[0:3], v[186:189], v[228:231], v[0:3]
	s_setprio 0
	s_setprio 1
	v_mfma_f32_16x16x32_bf16 v[44:47], v[182:185], v[208:211], v[44:47]
	v_mfma_f32_16x16x32_bf16 v[40:43], v[190:193], v[208:211], v[40:43]
	v_mfma_f32_16x16x32_bf16 v[28:31], v[182:185], v[216:219], v[28:31]
	v_mfma_f32_16x16x32_bf16 v[24:27], v[190:193], v[216:219], v[24:27]
	v_mfma_f32_16x16x32_bf16 v[12:15], v[182:185], v[224:227], v[12:15]
	v_mfma_f32_16x16x32_bf16 v[8:11], v[190:193], v[224:227], v[8:11]
	v_mfma_f32_16x16x32_bf16 v[4:7], v[182:185], v[232:235], v[4:7]
	v_mfma_f32_16x16x32_bf16 v[0:3], v[190:193], v[232:235], v[0:3]
	s_setprio 0
	s_barrier
	s_add_i32 s40, 0, 0x18000
	s_add_i32 s41, 0, 0x1c000
	ds_read_b128 v[144:147], v254
	ds_read_b128 v[148:151], v254 offset:1024
	ds_read_b128 v[152:155], v254 offset:2048
	ds_read_b128 v[156:159], v254 offset:3072
	ds_read_b128 v[178:181], v255
	ds_read_b128 v[182:185], v255 offset:1024
	ds_read_b128 v[186:189], v255 offset:2048
	ds_read_b128 v[190:193], v255 offset:3072
	s_add_u32 s18, s18, 0x80000
	s_addc_u32 s19, s19, 0
	s_mov_b32 m0, s25
	ds_read_b128 v[194:197], v143 offset:32768
	ds_read_b128 v[208:211], v143 offset:33792
	ds_read_b128 v[212:215], v143 offset:34816
	ds_read_b128 v[216:219], v143 offset:35840
	ds_read_b128 v[220:223], v143 offset:36864
	ds_read_b128 v[224:227], v143 offset:37888
	ds_read_b128 v[228:231], v143 offset:38912
	ds_read_b128 v[232:235], v143 offset:39936
	global_load_lds_dwordx4 v134, s[18:19]
	s_mov_b32 m0, s26
	s_nop 0
	global_load_lds_dwordx4 v132, s[18:19]
	s_waitcnt vmcnt(8)
	s_waitcnt lgkmcnt(0)
	s_barrier
	s_setprio 1
	s_waitcnt lgkmcnt(0)
	v_mfma_f32_16x16x32_bf16 v[126:129], v[144:147], v[194:197], v[126:129]
	v_mfma_f32_16x16x32_bf16 v[122:125], v[152:155], v[194:197], v[122:125]
	v_mfma_f32_16x16x32_bf16 v[118:121], v[144:147], v[212:215], v[118:121]
	v_mfma_f32_16x16x32_bf16 v[114:117], v[152:155], v[212:215], v[114:117]
	s_setprio 0
	s_setprio 1
	v_mfma_f32_16x16x32_bf16 v[102:105], v[144:147], v[220:223], v[102:105]
	v_mfma_f32_16x16x32_bf16 v[98:101], v[152:155], v[220:223], v[98:101]
	v_mfma_f32_16x16x32_bf16 v[86:89], v[144:147], v[228:231], v[86:89]
	v_mfma_f32_16x16x32_bf16 v[82:85], v[152:155], v[228:231], v[82:85]
	s_setprio 0
	s_setprio 1
	v_mfma_f32_16x16x32_bf16 v[126:129], v[148:151], v[208:211], v[126:129]
	v_mfma_f32_16x16x32_bf16 v[122:125], v[156:159], v[208:211], v[122:125]
	v_mfma_f32_16x16x32_bf16 v[118:121], v[148:151], v[216:219], v[118:121]
	v_mfma_f32_16x16x32_bf16 v[114:117], v[156:159], v[216:219], v[114:117]
	s_setprio 0
	s_setprio 1
	v_mfma_f32_16x16x32_bf16 v[102:105], v[148:151], v[224:227], v[102:105]
	v_mfma_f32_16x16x32_bf16 v[98:101], v[156:159], v[224:227], v[98:101]
	v_mfma_f32_16x16x32_bf16 v[86:89], v[148:151], v[232:235], v[86:89]
	v_mfma_f32_16x16x32_bf16 v[82:85], v[156:159], v[232:235], v[82:85]
	s_setprio 0
	s_setprio 1
	v_mfma_f32_16x16x32_bf16 v[110:113], v[178:181], v[194:197], v[110:113]
	v_mfma_f32_16x16x32_bf16 v[106:109], v[186:189], v[194:197], v[106:109]
	v_mfma_f32_16x16x32_bf16 v[94:97], v[178:181], v[212:215], v[94:97]
	v_mfma_f32_16x16x32_bf16 v[90:93], v[186:189], v[212:215], v[90:93]
	v_mfma_f32_16x16x32_bf16 v[78:81], v[178:181], v[220:223], v[78:81]
	v_mfma_f32_16x16x32_bf16 v[74:77], v[186:189], v[220:223], v[74:77]
	v_mfma_f32_16x16x32_bf16 v[70:73], v[178:181], v[228:231], v[70:73]
	v_mfma_f32_16x16x32_bf16 v[66:69], v[186:189], v[228:231], v[66:69]
	s_setprio 0
	s_setprio 1
	v_mfma_f32_16x16x32_bf16 v[110:113], v[182:185], v[208:211], v[110:113]
	v_mfma_f32_16x16x32_bf16 v[106:109], v[190:193], v[208:211], v[106:109]
	v_mfma_f32_16x16x32_bf16 v[94:97], v[182:185], v[216:219], v[94:97]
	v_mfma_f32_16x16x32_bf16 v[90:93], v[190:193], v[216:219], v[90:93]
	v_mfma_f32_16x16x32_bf16 v[78:81], v[182:185], v[224:227], v[78:81]
	v_mfma_f32_16x16x32_bf16 v[74:77], v[190:193], v[224:227], v[74:77]
	v_mfma_f32_16x16x32_bf16 v[70:73], v[182:185], v[232:235], v[70:73]
	v_mfma_f32_16x16x32_bf16 v[66:69], v[190:193], v[232:235], v[66:69]
	s_setprio 0
	s_barrier
; #define PG8_STAGE(bufoff, gbase, voff) do { _Pragma("unroll") for (int _i = 0; _i < 2; ++_i) \
;         __builtin_amdgcn_global_load_lds((const unsigned*)((const char*)(gbase) + (voff)[_i]), (PG8_LAS unsigned*)(lds + (bufoff) + ldsw + _i * 8192), 16, 0, 0); } while (0)
; #define PG8_LDA(dst, b, h) do { _Pragma("unroll") for (int m = 0; m < 4; ++m) _Pragma("unroll") for (int k = 0; k < 2; ++k) dst[m][k] = *(const PG8_LAS bf16x8*)(lds + PG8_SA(b, h) + aoff + m * 2048 + k * 1024); } while (0)
; #define PG8_WAIT_V(n) asm volatile("s_waitcnt vmcnt(" #n ")" ::: "memory")
; #define PG8_WAIT_L(n) asm volatile("s_waitcnt lgkmcnt(" #n ")" ::: "memory")
; #define PG8_BAR __builtin_amdgcn_s_barrier()
; template <class Epi, class Sched, bool ALIGN_EPI = false, bool SP2 = false>
; __device__ __forceinline__ void gemm_phase(PG8_LAS unsigned char* lds, const Gemm g, const Sched& S, const Epi& E, const int wave0) {
;     ...
;         for (int t = 0; t < nt; t += 2) {
;             const bool last = (t == nt - 2);
;             const char* a1 = cA + (size_t)(t + 1) * kstep;
;             const char* a2 = last ? nA : cA + (size_t)(t + 2) * kstep; const char* b2 = last ? nB : cB + (size_t)(t + 2) * kstep;
;             const char* a3 = a2 + kstep; const char* b3 = b2 + kstep;
;             if (last && has_next) S.a_ready(nxt);
;             if constexpr (SP2) {
;             PG8_LDB(B0, 0, 0); PG8_LDB(B1, 0, 1); PG8_SCHED; PG8_LDA(At, 0, 0); PG8_STAGE(PG8_SA(1, 1), a1 + hstepA, voffA);
;             PG8_WAIT_V(8); PG8_WAIT_L(0); PG8_BAR; PG8_MMA(0, 0, At, B0); PG8_MMA(0, 1, At, B1); PG8_BAR; PG8_SCHED;
;             PG8_LDA(At, 0, 1); PG8_STAGE(PG8_SB(0, 0), b2, voffB); PG8_STAGE(PG8_SB(0, 1), b2 + hstepB, voffB); PG8_STAGE(PG8_SA(0, 0), a2, voffA);
;             PG8_WAIT_V(8); PG8_WAIT_L(0); PG8_BAR; PG8_MMA(1, 0, At, B0); PG8_MMA(1, 1, At, B1); PG8_BAR; PG8_SCHED;
;             PG8_LDB(B0, 1, 0); PG8_LDB(B1, 1, 1); PG8_SCHED; PG8_LDA(At, 1, 0); PG8_STAGE(PG8_SA(0, 1), a2 + hstepA, voffA);
;             PG8_WAIT_V(8); PG8_WAIT_L(0); PG8_BAR; PG8_MMA(0, 0, At, B0); PG8_MMA(0, 1, At, B1); PG8_BAR; PG8_SCHED;
;             PG8_LDA(At, 1, 1); PG8_STAGE(PG8_SB(1, 0), b3, voffB); PG8_STAGE(PG8_SB(1, 1), b3 + hstepB, voffB); PG8_STAGE(PG8_SA(1, 0), a3, voffA);
;             PG8_WAIT_V(8); PG8_WAIT_L(0); PG8_BAR; PG8_MMA(1, 0, At, B0); PG8_MMA(1, 1, At, B1); PG8_BAR; PG8_SCHED;
	s_add_i32 s18, s40, s22
	s_add_u32 s44, s16, 0x80
	s_addc_u32 s45, s17, 0
	s_mov_b32 m0, s18
	ds_read_b128 v[194:197], v143 offset:49152
	ds_read_b128 v[208:211], v143 offset:50176
	ds_read_b128 v[212:215], v143 offset:51200
	ds_read_b128 v[216:219], v143 offset:52224
	ds_read_b128 v[220:223], v143 offset:53248
	ds_read_b128 v[224:227], v143 offset:54272
	ds_read_b128 v[228:231], v143 offset:55296
	ds_read_b128 v[232:235], v143 offset:56320
	global_load_lds_dwordx4 v64, s[44:45]
	s_add_i32 m0, s18, 0x2000
	s_add_u32 s16, s16, 0x80080
	s_addc_u32 s17, s17, 0
	s_add_i32 s18, s41, s22
	global_load_lds_dwordx4 v130, s[44:45]
	s_mov_b32 m0, s18
	s_nop 0
	global_load_lds_dwordx4 v64, s[16:17]
	s_add_i32 m0, s18, 0x2000
	s_nop 0
	global_load_lds_dwordx4 v130, s[16:17]
	s_add_u32 s100, s100, 0x80
	s_addc_u32 s101, s101, 0
	s_mov_b32 m0, s27
	s_nop 0
	global_load_lds_dwordx4 v134, s[100:101]
	s_mov_b32 m0, s28
	s_nop 0
	global_load_lds_dwordx4 v132, s[100:101]
	s_waitcnt vmcnt(8)
	s_waitcnt lgkmcnt(0)
	s_barrier
	s_setprio 1
	s_waitcnt lgkmcnt(0)
	v_mfma_f32_16x16x32_bf16 v[60:63], v[144:147], v[194:197], v[60:63]
	v_mfma_f32_16x16x32_bf16 v[56:59], v[152:155], v[194:197], v[56:59]
	v_mfma_f32_16x16x32_bf16 v[52:55], v[144:147], v[212:215], v[52:55]
	v_mfma_f32_16x16x32_bf16 v[48:51], v[152:155], v[212:215], v[48:51]
	s_setprio 0
	s_setprio 1
	v_mfma_f32_16x16x32_bf16 v[36:39], v[144:147], v[220:223], v[36:39]
	v_mfma_f32_16x16x32_bf16 v[32:35], v[152:155], v[220:223], v[32:35]
	v_mfma_f32_16x16x32_bf16 v[20:23], v[144:147], v[228:231], v[20:23]
	v_mfma_f32_16x16x32_bf16 v[16:19], v[152:155], v[228:231], v[16:19]
	s_setprio 0
	s_setprio 1
	v_mfma_f32_16x16x32_bf16 v[60:63], v[148:151], v[208:211], v[60:63]
	v_mfma_f32_16x16x32_bf16 v[56:59], v[156:159], v[208:211], v[56:59]
	v_mfma_f32_16x16x32_bf16 v[52:55], v[148:151], v[216:219], v[52:55]
	v_mfma_f32_16x16x32_bf16 v[48:51], v[156:159], v[216:219], v[48:51]
	s_setprio 0
	s_setprio 1
	v_mfma_f32_16x16x32_bf16 v[36:39], v[148:151], v[224:227], v[36:39]
	v_mfma_f32_16x16x32_bf16 v[32:35], v[156:159], v[224:227], v[32:35]
	v_mfma_f32_16x16x32_bf16 v[20:23], v[148:151], v[232:235], v[20:23]
	v_mfma_f32_16x16x32_bf16 v[16:19], v[156:159], v[232:235], v[16:19]
	s_setprio 0
	s_setprio 1
	v_mfma_f32_16x16x32_bf16 v[44:47], v[178:181], v[194:197], v[44:47]
	v_mfma_f32_16x16x32_bf16 v[40:43], v[186:189], v[194:197], v[40:43]
	v_mfma_f32_16x16x32_bf16 v[28:31], v[178:181], v[212:215], v[28:31]
	v_mfma_f32_16x16x32_bf16 v[24:27], v[186:189], v[212:215], v[24:27]
	v_mfma_f32_16x16x32_bf16 v[12:15], v[178:181], v[220:223], v[12:15]
	v_mfma_f32_16x16x32_bf16 v[8:11], v[186:189], v[220:223], v[8:11]
	v_mfma_f32_16x16x32_bf16 v[4:7], v[178:181], v[228:231], v[4:7]
	v_mfma_f32_16x16x32_bf16 v[0:3], v[186:189], v[228:231], v[0:3]
	s_setprio 0
	s_setprio 1
	v_mfma_f32_16x16x32_bf16 v[44:47], v[182:185], v[208:211], v[44:47]
	v_mfma_f32_16x16x32_bf16 v[40:43], v[190:193], v[208:211], v[40:43]
	v_mfma_f32_16x16x32_bf16 v[28:31], v[182:185], v[216:219], v[28:31]
	v_mfma_f32_16x16x32_bf16 v[24:27], v[190:193], v[216:219], v[24:27]
	v_mfma_f32_16x16x32_bf16 v[12:15], v[182:185], v[224:227], v[12:15]
	v_mfma_f32_16x16x32_bf16 v[8:11], v[190:193], v[224:227], v[8:11]
	v_mfma_f32_16x16x32_bf16 v[4:7], v[182:185], v[232:235], v[4:7]
	v_mfma_f32_16x16x32_bf16 v[0:3], v[190:193], v[232:235], v[0:3]
	s_setprio 0
	s_barrier
	s_add_i32 s37, s37, 2
	s_add_u32 s0, s0, 0x100
	s_addc_u32 s1, s1, 0
	s_add_u32 s35, s35, 0x100
	s_addc_u32 s36, s36, 0
	s_cmp_gt_u32 s37, 29
	s_cbranch_scc0 .LBB0_1341
	s_mov_b64 s[44:45], 0x80
	s_and_b64 vcc, exec, s[6:7]
	s_mov_b64 s[34:35], 0x45000
	s_cbranch_vccz .LBB0_1344
	s_barrier

; #define PG8_STAGE(bufoff, gbase, voff) do { _Pragma("unroll") for (int _i = 0; _i < 2; ++_i) \
;         __builtin_amdgcn_global_load_lds((const unsigned*)((const char*)(gbase) + (voff)[_i]), (PG8_LAS unsigned*)(lds + (bufoff) + ldsw + _i * 8192), 16, 0, 0); } while (0)
; #define PG8_LDA(dst, b, h) do { _Pragma("unroll") for (int m = 0; m < 4; ++m) _Pragma("unroll") for (int k = 0; k < 2; ++k) dst[m][k] = *(const PG8_LAS bf16x8*)(lds + PG8_SA(b, h) + aoff + m * 2048 + k * 1024); } while (0)
; #define PG8_WAIT_V(n) asm volatile("s_waitcnt vmcnt(" #n ")" ::: "memory")
; #define PG8_WAIT_L(n) asm volatile("s_waitcnt lgkmcnt(" #n ")" ::: "memory")
; #define PG8_BAR __builtin_amdgcn_s_barrier()
; template <class Epi, class Sched, bool ALIGN_EPI = false, bool SP2 = false>
; __device__ __forceinline__ void gemm_phase(PG8_LAS unsigned char* lds, const Gemm g, const Sched& S, const Epi& E, const int wave0) {
;     ...
;         for (int t = 0; t < nt; t += 2) {
;             const bool last = (t == nt - 2);
;             const char* a1 = cA + (size_t)(t + 1) * kstep;
;             const char* a2 = last ? nA : cA + (size_t)(t + 2) * kstep; const char* b2 = last ? nB : cB + (size_t)(t + 2) * kstep;
;             const char* a3 = a2 + kstep; const char* b3 = b2 + kstep;
;             if (last && has_next) S.a_ready(nxt);
;             if constexpr (SP2) {
;             PG8_LDB(B0, 0, 0); PG8_LDB(B1, 0, 1); PG8_SCHED; PG8_LDA(At, 0, 0); PG8_STAGE(PG8_SA(1, 1), a1 + hstepA, voffA);
;             PG8_WAIT_V(8); PG8_WAIT_L(0); PG8_BAR; PG8_MMA(0, 0, At, B0); PG8_MMA(0, 1, At, B1); PG8_BAR; PG8_SCHED;
;             PG8_LDA(At, 0, 1); PG8_STAGE(PG8_SB(0, 0), b2, voffB); PG8_STAGE(PG8_SB(0, 1), b2 + hstepB, voffB); PG8_STAGE(PG8_SA(0, 0), a2, voffA);
;             PG8_WAIT_V(8); PG8_WAIT_L(0); PG8_BAR; PG8_MMA(1, 0, At, B0); PG8_MMA(1, 1, At, B1); PG8_BAR; PG8_SCHED;
;             PG8_LDB(B0, 1, 0); PG8_LDB(B1, 1, 1); PG8_SCHED; PG8_LDA(At, 1, 0); PG8_STAGE(PG8_SA(0, 1), a2 + hstepA, voffA);
;             PG8_WAIT_V(8); PG8_WAIT_L(0); PG8_BAR; PG8_MMA(0, 0, At, B0); PG8_MMA(0, 1, At, B1); PG8_BAR; PG8_SCHED;
;             PG8_LDA(At, 1, 1); PG8_STAGE(PG8_SB(1, 0), b3, voffB); PG8_STAGE(PG8_SB(1, 1), b3 + hstepB, voffB); PG8_STAGE(PG8_SA(1, 0), a3, voffA);
;             PG8_WAIT_V(8); PG8_WAIT_L(0); PG8_BAR; PG8_MMA(1, 0, At, B0); PG8_MMA(1, 1, At, B1); PG8_BAR; PG8_SCHED;
.LBB0_1360:
	s_add_u32 s16, s0, 0xfff80080
	s_addc_u32 s17, s1, -1
	s_add_i32 s42, 0, 0x10000
	s_cmp_eq_u32 s41, 12
	s_cselect_b32 s19, s5, s17
	s_cselect_b32 s18, s4, s16
	s_cselect_b32 s17, s11, s27
	s_cselect_b32 s16, s13, s15
	s_add_i32 s44, 0, 0x14000
	ds_read_b128 v[144:147], v252
	ds_read_b128 v[148:151], v252 offset:1024
	ds_read_b128 v[152:155], v252 offset:2048
	ds_read_b128 v[156:159], v252 offset:3072
	ds_read_b128 v[178:181], v253
	ds_read_b128 v[182:185], v253 offset:1024
	ds_read_b128 v[186:189], v253 offset:2048
	ds_read_b128 v[190:193], v253 offset:3072
	s_add_i32 m0, s23, 0xc000
	ds_read_b128 v[194:197], v143
	ds_read_b128 v[208:211], v143 offset:1024
	ds_read_b128 v[212:215], v143 offset:2048
	ds_read_b128 v[216:219], v143 offset:3072
	ds_read_b128 v[220:223], v143 offset:4096
	ds_read_b128 v[224:227], v143 offset:5120
	ds_read_b128 v[228:231], v143 offset:6144
	ds_read_b128 v[232:235], v143 offset:7168
	global_load_lds_dwordx4 v136, s[0:1]
	s_add_i32 m0, s23, 0xe000
	s_nop 0
	global_load_lds_dwordx4 v138, s[0:1]
	s_waitcnt vmcnt(8)
	s_waitcnt lgkmcnt(0)
	s_barrier
	s_setprio 1
	s_waitcnt lgkmcnt(0)
	v_mfma_f32_16x16x32_bf16 v[126:129], v[144:147], v[194:197], v[126:129]
	v_mfma_f32_16x16x32_bf16 v[122:125], v[152:155], v[194:197], v[122:125]
	v_mfma_f32_16x16x32_bf16 v[118:121], v[144:147], v[212:215], v[118:121]
	v_mfma_f32_16x16x32_bf16 v[114:117], v[152:155], v[212:215], v[114:117]
	s_setprio 0
	s_setprio 1
	v_mfma_f32_16x16x32_bf16 v[102:105], v[144:147], v[220:223], v[102:105]
	v_mfma_f32_16x16x32_bf16 v[98:101], v[152:155], v[220:223], v[98:101]
	v_mfma_f32_16x16x32_bf16 v[86:89], v[144:147], v[228:231], v[86:89]
	v_mfma_f32_16x16x32_bf16 v[82:85], v[152:155], v[228:231], v[82:85]
	s_setprio 0
	s_setprio 1
	v_mfma_f32_16x16x32_bf16 v[126:129], v[148:151], v[208:211], v[126:129]
	v_mfma_f32_16x16x32_bf16 v[122:125], v[156:159], v[208:211], v[122:125]
	v_mfma_f32_16x16x32_bf16 v[118:121], v[148:151], v[216:219], v[118:121]
	v_mfma_f32_16x16x32_bf16 v[114:117], v[156:159], v[216:219], v[114:117]
	s_setprio 0
	s_setprio 1
	v_mfma_f32_16x16x32_bf16 v[102:105], v[148:151], v[224:227], v[102:105]
	v_mfma_f32_16x16x32_bf16 v[98:101], v[156:159], v[224:227], v[98:101]
	v_mfma_f32_16x16x32_bf16 v[86:89], v[148:151], v[232:235], v[86:89]
	v_mfma_f32_16x16x32_bf16 v[82:85], v[156:159], v[232:235], v[82:85]
	s_setprio 0
	s_setprio 1
	v_mfma_f32_16x16x32_bf16 v[110:113], v[178:181], v[194:197], v[110:113]
	v_mfma_f32_16x16x32_bf16 v[106:109], v[186:189], v[194:197], v[106:109]
	v_mfma_f32_16x16x32_bf16 v[94:97], v[178:181], v[212:215], v[94:97]
	v_mfma_f32_16x16x32_bf16 v[90:93], v[186:189], v[212:215], v[90:93]
	v_mfma_f32_16x16x32_bf16 v[78:81], v[178:181], v[220:223], v[78:81]
	v_mfma_f32_16x16x32_bf16 v[74:77], v[186:189], v[220:223], v[74:77]
	v_mfma_f32_16x16x32_bf16 v[70:73], v[178:181], v[228:231], v[70:73]
	v_mfma_f32_16x16x32_bf16 v[66:69], v[186:189], v[228:231], v[66:69]
	s_setprio 0
	s_setprio 1
	v_mfma_f32_16x16x32_bf16 v[110:113], v[182:185], v[208:211], v[110:113]
	v_mfma_f32_16x16x32_bf16 v[106:109], v[190:193], v[208:211], v[106:109]
	v_mfma_f32_16x16x32_bf16 v[94:97], v[182:185], v[216:219], v[94:97]
	v_mfma_f32_16x16x32_bf16 v[90:93], v[190:193], v[216:219], v[90:93]
	v_mfma_f32_16x16x32_bf16 v[78:81], v[182:185], v[224:227], v[78:81]
	v_mfma_f32_16x16x32_bf16 v[74:77], v[190:193], v[224:227], v[74:77]
	v_mfma_f32_16x16x32_bf16 v[70:73], v[182:185], v[232:235], v[70:73]
	v_mfma_f32_16x16x32_bf16 v[66:69], v[190:193], v[232:235], v[66:69]
	s_setprio 0
	s_barrier
	s_add_i32 s42, s42, s22
	s_mov_b32 m0, s42
	ds_read_b128 v[194:197], v143 offset:16384
	ds_read_b128 v[208:211], v143 offset:17408
	ds_read_b128 v[212:215], v143 offset:18432
	ds_read_b128 v[216:219], v143 offset:19456
	ds_read_b128 v[220:223], v143 offset:20480
	ds_read_b128 v[224:227], v143 offset:21504
	ds_read_b128 v[228:231], v143 offset:22528
	ds_read_b128 v[232:235], v143 offset:23552
	global_load_lds_dwordx4 v64, s[16:17]
	s_add_i32 m0, s42, 0x2000
	s_add_u32 s42, s16, 0x80000
	s_addc_u32 s43, s17, 0
	s_add_i32 s44, s44, s22
	global_load_lds_dwordx4 v130, s[16:17]
	s_mov_b32 m0, s44
	s_mov_b64 s[100:101], s[18:19]
	global_load_lds_dwordx4 v64, s[42:43]
	s_add_i32 m0, s44, 0x2000
	s_nop 0
	global_load_lds_dwordx4 v130, s[42:43]
	s_mov_b32 m0, s23
	s_nop 0
	global_load_lds_dwordx4 v134, s[18:19]
	s_mov_b32 m0, s24
	s_nop 0
	global_load_lds_dwordx4 v132, s[18:19]
	s_waitcnt vmcnt(8)
	s_waitcnt lgkmcnt(0)
	s_barrier
; #define PG8_STAGE(bufoff, gbase, voff) do { _Pragma("unroll") for (int _i = 0; _i < 2; ++_i) \
;         __builtin_amdgcn_global_load_lds((const unsigned*)((const char*)(gbase) + (voff)[_i]), (PG8_LAS unsigned*)(lds + (bufoff) + ldsw + _i * 8192), 16, 0, 0); } while (0)
; #define PG8_LDA(dst, b, h) do { _Pragma("unroll") for (int m = 0; m < 4; ++m) _Pragma("unroll") for (int k = 0; k < 2; ++k) dst[m][k] = *(const PG8_LAS bf16x8*)(lds + PG8_SA(b, h) + aoff + m * 2048 + k * 1024); } while (0)
; #define PG8_LDB(dst, b, h) do { _Pragma("unroll") for (int n = 0; n < 2; ++n) _Pragma("unroll") for (int k = 0; k < 2; ++k) dst[n][k] = *(const PG8_LAS bf16x8*)(lds + PG8_SB(b, h) + boff + n * 2048 + k * 1024); } while (0)
; #define PG8_MMA(ai, bj, At, Bt) do { __builtin_amdgcn_s_setprio(1); _Pragma("unroll") for (int m = 0; m < 4; ++m) _Pragma("unroll") for (int n = 0; n < 2; ++n) _Pragma("unroll") for (int k = 0; k < 2; ++k) \
;         acc[ai][bj][m][n] = __builtin_amdgcn_mfma_f32_16x16x32_bf16(Bt[n][k], At[m][k], acc[ai][bj][m][n], 0, 0, 0); __builtin_amdgcn_s_setprio(0); } while (0)
; template <class Epi, class Sched, bool ALIGN_EPI = false, bool SP2 = false>
; __device__ __forceinline__ void gemm_phase(PG8_LAS unsigned char* lds, const Gemm g, const Sched& S, const Epi& E, const int wave0) {
;     ...
;             if constexpr (SP2) {
;             PG8_LDB(B0, 0, 0); PG8_LDB(B1, 0, 1); PG8_SCHED; PG8_LDA(At, 0, 0); PG8_STAGE(PG8_SA(1, 1), a1 + hstepA, voffA);
;             PG8_WAIT_V(8); PG8_WAIT_L(0); PG8_BAR; PG8_MMA(0, 0, At, B0); PG8_MMA(0, 1, At, B1); PG8_BAR; PG8_SCHED;
;             PG8_LDA(At, 0, 1); PG8_STAGE(PG8_SB(0, 0), b2, voffB); PG8_STAGE(PG8_SB(0, 1), b2 + hstepB, voffB); PG8_STAGE(PG8_SA(0, 0), a2, voffA);
;             PG8_WAIT_V(8); PG8_WAIT_L(0); PG8_BAR; PG8_MMA(1, 0, At, B0); PG8_MMA(1, 1, At, B1); PG8_BAR; PG8_SCHED;
;             PG8_LDB(B0, 1, 0); PG8_LDB(B1, 1, 1); PG8_SCHED; PG8_LDA(At, 1, 0); PG8_STAGE(PG8_SA(0, 1), a2 + hstepA, voffA);
;             PG8_WAIT_V(8); PG8_WAIT_L(0); PG8_BAR; PG8_MMA(0, 0, At, B0); PG8_MMA(0, 1, At, B1); PG8_BAR; PG8_SCHED;
;             PG8_LDA(At, 1, 1); PG8_STAGE(PG8_SB(1, 0), b3, voffB); PG8_STAGE(PG8_SB(1, 1), b3 + hstepB, voffB); PG8_STAGE(PG8_SA(1, 0), a3, voffA);
;             PG8_WAIT_V(8); PG8_WAIT_L(0); PG8_BAR; PG8_MMA(1, 0, At, B0); PG8_MMA(1, 1, At, B1); PG8_BAR; PG8_SCHED;
	s_setprio 1
	s_waitcnt lgkmcnt(0)
	v_mfma_f32_16x16x32_bf16 v[60:63], v[144:147], v[194:197], v[60:63]
	v_mfma_f32_16x16x32_bf16 v[56:59], v[152:155], v[194:197], v[56:59]
	v_mfma_f32_16x16x32_bf16 v[52:55], v[144:147], v[212:215], v[52:55]
	v_mfma_f32_16x16x32_bf16 v[48:51], v[152:155], v[212:215], v[48:51]
	s_setprio 0
	s_setprio 1
	v_mfma_f32_16x16x32_bf16 v[36:39], v[144:147], v[220:223], v[36:39]
	v_mfma_f32_16x16x32_bf16 v[32:35], v[152:155], v[220:223], v[32:35]
	v_mfma_f32_16x16x32_bf16 v[20:23], v[144:147], v[228:231], v[20:23]
	v_mfma_f32_16x16x32_bf16 v[16:19], v[152:155], v[228:231], v[16:19]
	s_setprio 0
	s_setprio 1
	v_mfma_f32_16x16x32_bf16 v[60:63], v[148:151], v[208:211], v[60:63]
	v_mfma_f32_16x16x32_bf16 v[56:59], v[156:159], v[208:211], v[56:59]
	v_mfma_f32_16x16x32_bf16 v[52:55], v[148:151], v[216:219], v[52:55]
	v_mfma_f32_16x16x32_bf16 v[48:51], v[156:159], v[216:219], v[48:51]
	s_setprio 0
	s_setprio 1
	v_mfma_f32_16x16x32_bf16 v[36:39], v[148:151], v[224:227], v[36:39]
	v_mfma_f32_16x16x32_bf16 v[32:35], v[156:159], v[224:227], v[32:35]
	v_mfma_f32_16x16x32_bf16 v[20:23], v[148:151], v[232:235], v[20:23]
	v_mfma_f32_16x16x32_bf16 v[16:19], v[156:159], v[232:235], v[16:19]
	s_setprio 0
	s_setprio 1
	v_mfma_f32_16x16x32_bf16 v[44:47], v[178:181], v[194:197], v[44:47]
	v_mfma_f32_16x16x32_bf16 v[40:43], v[186:189], v[194:197], v[40:43]
	v_mfma_f32_16x16x32_bf16 v[28:31], v[178:181], v[212:215], v[28:31]
	v_mfma_f32_16x16x32_bf16 v[24:27], v[186:189], v[212:215], v[24:27]
	v_mfma_f32_16x16x32_bf16 v[12:15], v[178:181], v[220:223], v[12:15]
	v_mfma_f32_16x16x32_bf16 v[8:11], v[186:189], v[220:223], v[8:11]
	v_mfma_f32_16x16x32_bf16 v[4:7], v[178:181], v[228:231], v[4:7]
	v_mfma_f32_16x16x32_bf16 v[0:3], v[186:189], v[228:231], v[0:3]
	s_setprio 0
	s_setprio 1
	v_mfma_f32_16x16x32_bf16 v[44:47], v[182:185], v[208:211], v[44:47]
	v_mfma_f32_16x16x32_bf16 v[40:43], v[190:193], v[208:211], v[40:43]
	v_mfma_f32_16x16x32_bf16 v[28:31], v[182:185], v[216:219], v[28:31]
	v_mfma_f32_16x16x32_bf16 v[24:27], v[190:193], v[216:219], v[24:27]
	v_mfma_f32_16x16x32_bf16 v[12:15], v[182:185], v[224:227], v[12:15]
	v_mfma_f32_16x16x32_bf16 v[8:11], v[190:193], v[224:227], v[8:11]
	v_mfma_f32_16x16x32_bf16 v[4:7], v[182:185], v[232:235], v[4:7]
	v_mfma_f32_16x16x32_bf16 v[0:3], v[190:193], v[232:235], v[0:3]
	s_setprio 0
	s_barrier
	s_add_i32 s42, 0, 0x18000
	s_add_i32 s43, 0, 0x1c000
	ds_read_b128 v[144:147], v254
	ds_read_b128 v[148:151], v254 offset:1024
	ds_read_b128 v[152:155], v254 offset:2048
	ds_read_b128 v[156:159], v254 offset:3072
	ds_read_b128 v[178:181], v255
	ds_read_b128 v[182:185], v255 offset:1024
	ds_read_b128 v[186:189], v255 offset:2048
	ds_read_b128 v[190:193], v255 offset:3072
	s_add_u32 s18, s18, 0x80000
	s_addc_u32 s19, s19, 0
	s_mov_b32 m0, s25
	ds_read_b128 v[194:197], v143 offset:32768
	ds_read_b128 v[208:211], v143 offset:33792
	ds_read_b128 v[212:215], v143 offset:34816
	ds_read_b128 v[216:219], v143 offset:35840
	ds_read_b128 v[220:223], v143 offset:36864
	ds_read_b128 v[224:227], v143 offset:37888
	ds_read_b128 v[228:231], v143 offset:38912
	ds_read_b128 v[232:235], v143 offset:39936
	global_load_lds_dwordx4 v134, s[18:19]
	s_mov_b32 m0, s33
	s_nop 0
	global_load_lds_dwordx4 v132, s[18:19]
	s_waitcnt vmcnt(8)
	s_waitcnt lgkmcnt(0)
	s_barrier
	s_setprio 1
	s_waitcnt lgkmcnt(0)
	v_mfma_f32_16x16x32_bf16 v[126:129], v[144:147], v[194:197], v[126:129]
	v_mfma_f32_16x16x32_bf16 v[122:125], v[152:155], v[194:197], v[122:125]
	v_mfma_f32_16x16x32_bf16 v[118:121], v[144:147], v[212:215], v[118:121]
	v_mfma_f32_16x16x32_bf16 v[114:117], v[152:155], v[212:215], v[114:117]
	s_setprio 0
	s_setprio 1
	v_mfma_f32_16x16x32_bf16 v[102:105], v[144:147], v[220:223], v[102:105]
	v_mfma_f32_16x16x32_bf16 v[98:101], v[152:155], v[220:223], v[98:101]
	v_mfma_f32_16x16x32_bf16 v[86:89], v[144:147], v[228:231], v[86:89]
	v_mfma_f32_16x16x32_bf16 v[82:85], v[152:155], v[228:231], v[82:85]
	s_setprio 0
	s_setprio 1
	v_mfma_f32_16x16x32_bf16 v[126:129], v[148:151], v[208:211], v[126:129]
	v_mfma_f32_16x16x32_bf16 v[122:125], v[156:159], v[208:211], v[122:125]
	v_mfma_f32_16x16x32_bf16 v[118:121], v[148:151], v[216:219], v[118:121]
	v_mfma_f32_16x16x32_bf16 v[114:117], v[156:159], v[216:219], v[114:117]
	s_setprio 0
	s_setprio 1
	v_mfma_f32_16x16x32_bf16 v[102:105], v[148:151], v[224:227], v[102:105]
	v_mfma_f32_16x16x32_bf16 v[98:101], v[156:159], v[224:227], v[98:101]
	v_mfma_f32_16x16x32_bf16 v[86:89], v[148:151], v[232:235], v[86:89]
	v_mfma_f32_16x16x32_bf16 v[82:85], v[156:159], v[232:235], v[82:85]
	s_setprio 0
	s_setprio 1
	v_mfma_f32_16x16x32_bf16 v[110:113], v[178:181], v[194:197], v[110:113]
	v_mfma_f32_16x16x32_bf16 v[106:109], v[186:189], v[194:197], v[106:109]
	v_mfma_f32_16x16x32_bf16 v[94:97], v[178:181], v[212:215], v[94:97]
	v_mfma_f32_16x16x32_bf16 v[90:93], v[186:189], v[212:215], v[90:93]
	v_mfma_f32_16x16x32_bf16 v[78:81], v[178:181], v[220:223], v[78:81]
	v_mfma_f32_16x16x32_bf16 v[74:77], v[186:189], v[220:223], v[74:77]
	v_mfma_f32_16x16x32_bf16 v[70:73], v[178:181], v[228:231], v[70:73]
	v_mfma_f32_16x16x32_bf16 v[66:69], v[186:189], v[228:231], v[66:69]
	s_setprio 0
	s_setprio 1
	v_mfma_f32_16x16x32_bf16 v[110:113], v[182:185], v[208:211], v[110:113]
	v_mfma_f32_16x16x32_bf16 v[106:109], v[190:193], v[208:211], v[106:109]
	v_mfma_f32_16x16x32_bf16 v[94:97], v[182:185], v[216:219], v[94:97]
	v_mfma_f32_16x16x32_bf16 v[90:93], v[190:193], v[216:219], v[90:93]
	v_mfma_f32_16x16x32_bf16 v[78:81], v[182:185], v[224:227], v[78:81]
	v_mfma_f32_16x16x32_bf16 v[74:77], v[190:193], v[224:227], v[74:77]
	v_mfma_f32_16x16x32_bf16 v[70:73], v[182:185], v[232:235], v[70:73]
	v_mfma_f32_16x16x32_bf16 v[66:69], v[190:193], v[232:235], v[66:69]
	s_setprio 0
	s_barrier
; #define PG8_STAGE(bufoff, gbase, voff) do { _Pragma("unroll") for (int _i = 0; _i < 2; ++_i) \
;         __builtin_amdgcn_global_load_lds((const unsigned*)((const char*)(gbase) + (voff)[_i]), (PG8_LAS unsigned*)(lds + (bufoff) + ldsw + _i * 8192), 16, 0, 0); } while (0)
; #define PG8_LDA(dst, b, h) do { _Pragma("unroll") for (int m = 0; m < 4; ++m) _Pragma("unroll") for (int k = 0; k < 2; ++k) dst[m][k] = *(const PG8_LAS bf16x8*)(lds + PG8_SA(b, h) + aoff + m * 2048 + k * 1024); } while (0)
; #define PG8_WAIT_V(n) asm volatile("s_waitcnt vmcnt(" #n ")" ::: "memory")
; #define PG8_WAIT_L(n) asm volatile("s_waitcnt lgkmcnt(" #n ")" ::: "memory")
; #define PG8_BAR __builtin_amdgcn_s_barrier()
; template <class Epi, class Sched, bool ALIGN_EPI = false, bool SP2 = false>
; __device__ __forceinline__ void gemm_phase(PG8_LAS unsigned char* lds, const Gemm g, const Sched& S, const Epi& E, const int wave0) {
;     ...
;         for (int t = 0; t < nt; t += 2) {
;             const bool last = (t == nt - 2);
;             const char* a1 = cA + (size_t)(t + 1) * kstep;
;             const char* a2 = last ? nA : cA + (size_t)(t + 2) * kstep; const char* b2 = last ? nB : cB + (size_t)(t + 2) * kstep;
;             const char* a3 = a2 + kstep; const char* b3 = b2 + kstep;
;             if (last && has_next) S.a_ready(nxt);
;             if constexpr (SP2) {
;             PG8_LDB(B0, 0, 0); PG8_LDB(B1, 0, 1); PG8_SCHED; PG8_LDA(At, 0, 0); PG8_STAGE(PG8_SA(1, 1), a1 + hstepA, voffA);
;             PG8_WAIT_V(8); PG8_WAIT_L(0); PG8_BAR; PG8_MMA(0, 0, At, B0); PG8_MMA(0, 1, At, B1); PG8_BAR; PG8_SCHED;
;             PG8_LDA(At, 0, 1); PG8_STAGE(PG8_SB(0, 0), b2, voffB); PG8_STAGE(PG8_SB(0, 1), b2 + hstepB, voffB); PG8_STAGE(PG8_SA(0, 0), a2, voffA);
;             PG8_WAIT_V(8); PG8_WAIT_L(0); PG8_BAR; PG8_MMA(1, 0, At, B0); PG8_MMA(1, 1, At, B1); PG8_BAR; PG8_SCHED;
;             PG8_LDB(B0, 1, 0); PG8_LDB(B1, 1, 1); PG8_SCHED; PG8_LDA(At, 1, 0); PG8_STAGE(PG8_SA(0, 1), a2 + hstepA, voffA);
;             PG8_WAIT_V(8); PG8_WAIT_L(0); PG8_BAR; PG8_MMA(0, 0, At, B0); PG8_MMA(0, 1, At, B1); PG8_BAR; PG8_SCHED;
;             PG8_LDA(At, 1, 1); PG8_STAGE(PG8_SB(1, 0), b3, voffB); PG8_STAGE(PG8_SB(1, 1), b3 + hstepB, voffB); PG8_STAGE(PG8_SA(1, 0), a3, voffA);
;             PG8_WAIT_V(8); PG8_WAIT_L(0); PG8_BAR; PG8_MMA(1, 0, At, B0); PG8_MMA(1, 1, At, B1); PG8_BAR; PG8_SCHED;
	s_add_i32 s18, s42, s22
	s_add_u32 s46, s16, 0x80
	s_addc_u32 s47, s17, 0
	s_mov_b32 m0, s18
	ds_read_b128 v[194:197], v143 offset:49152
	ds_read_b128 v[208:211], v143 offset:50176
	ds_read_b128 v[212:215], v143 offset:51200
	ds_read_b128 v[216:219], v143 offset:52224
	ds_read_b128 v[220:223], v143 offset:53248
	ds_read_b128 v[224:227], v143 offset:54272
	ds_read_b128 v[228:231], v143 offset:55296
	ds_read_b128 v[232:235], v143 offset:56320
	global_load_lds_dwordx4 v64, s[46:47]
	s_add_i32 m0, s18, 0x2000
	s_add_u32 s16, s16, 0x80080
	s_addc_u32 s17, s17, 0
	s_add_i32 s18, s43, s22
	global_load_lds_dwordx4 v130, s[46:47]
	s_mov_b32 m0, s18
	s_nop 0
	global_load_lds_dwordx4 v64, s[16:17]
	s_add_i32 m0, s18, 0x2000
	s_nop 0
	global_load_lds_dwordx4 v130, s[16:17]
	s_add_u32 s100, s100, 0x80
	s_addc_u32 s101, s101, 0
	s_mov_b32 m0, s34
	s_nop 0
	global_load_lds_dwordx4 v134, s[100:101]
	s_mov_b32 m0, s35
	s_nop 0
	global_load_lds_dwordx4 v132, s[100:101]
	s_waitcnt vmcnt(8)
	s_waitcnt lgkmcnt(0)
	s_barrier
	s_setprio 1
	s_waitcnt lgkmcnt(0)
	v_mfma_f32_16x16x32_bf16 v[60:63], v[144:147], v[194:197], v[60:63]
	v_mfma_f32_16x16x32_bf16 v[56:59], v[152:155], v[194:197], v[56:59]
	v_mfma_f32_16x16x32_bf16 v[52:55], v[144:147], v[212:215], v[52:55]
	v_mfma_f32_16x16x32_bf16 v[48:51], v[152:155], v[212:215], v[48:51]
	s_setprio 0
	s_setprio 1
	v_mfma_f32_16x16x32_bf16 v[36:39], v[144:147], v[220:223], v[36:39]
	v_mfma_f32_16x16x32_bf16 v[32:35], v[152:155], v[220:223], v[32:35]
	v_mfma_f32_16x16x32_bf16 v[20:23], v[144:147], v[228:231], v[20:23]
	v_mfma_f32_16x16x32_bf16 v[16:19], v[152:155], v[228:231], v[16:19]
	s_setprio 0
	s_setprio 1
	v_mfma_f32_16x16x32_bf16 v[60:63], v[148:151], v[208:211], v[60:63]
	v_mfma_f32_16x16x32_bf16 v[56:59], v[156:159], v[208:211], v[56:59]
	v_mfma_f32_16x16x32_bf16 v[52:55], v[148:151], v[216:219], v[52:55]
	v_mfma_f32_16x16x32_bf16 v[48:51], v[156:159], v[216:219], v[48:51]
	s_setprio 0
	s_setprio 1
	v_mfma_f32_16x16x32_bf16 v[36:39], v[148:151], v[224:227], v[36:39]
	v_mfma_f32_16x16x32_bf16 v[32:35], v[156:159], v[224:227], v[32:35]
	v_mfma_f32_16x16x32_bf16 v[20:23], v[148:151], v[232:235], v[20:23]
	v_mfma_f32_16x16x32_bf16 v[16:19], v[156:159], v[232:235], v[16:19]
	s_setprio 0
	s_setprio 1
	v_mfma_f32_16x16x32_bf16 v[44:47], v[178:181], v[194:197], v[44:47]
	v_mfma_f32_16x16x32_bf16 v[40:43], v[186:189], v[194:197], v[40:43]
	v_mfma_f32_16x16x32_bf16 v[28:31], v[178:181], v[212:215], v[28:31]
	v_mfma_f32_16x16x32_bf16 v[24:27], v[186:189], v[212:215], v[24:27]
	v_mfma_f32_16x16x32_bf16 v[12:15], v[178:181], v[220:223], v[12:15]
	v_mfma_f32_16x16x32_bf16 v[8:11], v[186:189], v[220:223], v[8:11]
	v_mfma_f32_16x16x32_bf16 v[4:7], v[178:181], v[228:231], v[4:7]
	v_mfma_f32_16x16x32_bf16 v[0:3], v[186:189], v[228:231], v[0:3]
	s_setprio 0
	s_setprio 1
	v_mfma_f32_16x16x32_bf16 v[44:47], v[182:185], v[208:211], v[44:47]
	v_mfma_f32_16x16x32_bf16 v[40:43], v[190:193], v[208:211], v[40:43]
	v_mfma_f32_16x16x32_bf16 v[28:31], v[182:185], v[216:219], v[28:31]
	v_mfma_f32_16x16x32_bf16 v[24:27], v[190:193], v[216:219], v[24:27]
	v_mfma_f32_16x16x32_bf16 v[12:15], v[182:185], v[224:227], v[12:15]
	v_mfma_f32_16x16x32_bf16 v[8:11], v[190:193], v[224:227], v[8:11]
	v_mfma_f32_16x16x32_bf16 v[4:7], v[182:185], v[232:235], v[4:7]
	v_mfma_f32_16x16x32_bf16 v[0:3], v[190:193], v[232:235], v[0:3]
	s_setprio 0
	s_barrier
	s_add_i32 s41, s41, 2
	s_add_u32 s0, s0, 0x100
	s_addc_u32 s1, s1, 0
	s_add_u32 s15, s15, 0x100
	s_addc_u32 s27, s27, 0
	s_cmp_gt_u32 s41, 13
	s_cbranch_scc0 .LBB0_1360
	s_mov_b64 s[46:47], 0x80
	s_and_b64 vcc, exec, s[8:9]
	s_cbranch_vccz .LBB0_1363
	s_barrier

; #define PG8_STAGE(bufoff, gbase, voff) do { _Pragma("unroll") for (int _i = 0; _i < 2; ++_i) \
;         __builtin_amdgcn_global_load_lds((const unsigned*)((const char*)(gbase) + (voff)[_i]), (PG8_LAS unsigned*)(lds + (bufoff) + ldsw + _i * 8192), 16, 0, 0); } while (0)
; #define PG8_LDA(dst, b, h) do { _Pragma("unroll") for (int m = 0; m < 4; ++m) _Pragma("unroll") for (int k = 0; k < 2; ++k) dst[m][k] = *(const PG8_LAS bf16x8*)(lds + PG8_SA(b, h) + aoff + m * 2048 + k * 1024); } while (0)
; #define PG8_WAIT_V(n) asm volatile("s_waitcnt vmcnt(" #n ")" ::: "memory")
; #define PG8_WAIT_L(n) asm volatile("s_waitcnt lgkmcnt(" #n ")" ::: "memory")
; #define PG8_BAR __builtin_amdgcn_s_barrier()
; template <class Epi, class Sched, bool ALIGN_EPI = false, bool SP2 = false>
; __device__ __forceinline__ void gemm_phase(PG8_LAS unsigned char* lds, const Gemm g, const Sched& S, const Epi& E, const int wave0) {
;     ...
;         for (int t = 0; t < nt; t += 2) {
;             const bool last = (t == nt - 2);
;             const char* a1 = cA + (size_t)(t + 1) * kstep;
;             const char* a2 = last ? nA : cA + (size_t)(t + 2) * kstep; const char* b2 = last ? nB : cB + (size_t)(t + 2) * kstep;
;             const char* a3 = a2 + kstep; const char* b3 = b2 + kstep;
;             if (last && has_next) S.a_ready(nxt);
;             if constexpr (SP2) {
;             PG8_LDB(B0, 0, 0); PG8_LDB(B1, 0, 1); PG8_SCHED; PG8_LDA(At, 0, 0); PG8_STAGE(PG8_SA(1, 1), a1 + hstepA, voffA);
;             PG8_WAIT_V(8); PG8_WAIT_L(0); PG8_BAR; PG8_MMA(0, 0, At, B0); PG8_MMA(0, 1, At, B1); PG8_BAR; PG8_SCHED;
;             PG8_LDA(At, 0, 1); PG8_STAGE(PG8_SB(0, 0), b2, voffB); PG8_STAGE(PG8_SB(0, 1), b2 + hstepB, voffB); PG8_STAGE(PG8_SA(0, 0), a2, voffA);
;             PG8_WAIT_V(8); PG8_WAIT_L(0); PG8_BAR; PG8_MMA(1, 0, At, B0); PG8_MMA(1, 1, At, B1); PG8_BAR; PG8_SCHED;
;             PG8_LDB(B0, 1, 0); PG8_LDB(B1, 1, 1); PG8_SCHED; PG8_LDA(At, 1, 0); PG8_STAGE(PG8_SA(0, 1), a2 + hstepA, voffA);
;             PG8_WAIT_V(8); PG8_WAIT_L(0); PG8_BAR; PG8_MMA(0, 0, At, B0); PG8_MMA(0, 1, At, B1); PG8_BAR; PG8_SCHED;
;             PG8_LDA(At, 1, 1); PG8_STAGE(PG8_SB(1, 0), b3, voffB); PG8_STAGE(PG8_SB(1, 1), b3 + hstepB, voffB); PG8_STAGE(PG8_SA(1, 0), a3, voffA);
;             PG8_WAIT_V(8); PG8_WAIT_L(0); PG8_BAR; PG8_MMA(1, 0, At, B0); PG8_MMA(1, 1, At, B1); PG8_BAR; PG8_SCHED;
.LBB0_1571:
	s_add_u32 s16, s0, 0xfff80080
	s_addc_u32 s17, s1, -1
	s_add_i32 s46, 0, 0x10000
	s_cmp_eq_u32 s45, 28
	s_cselect_b32 s19, s9, s17
	s_cselect_b32 s18, s33, s16
	s_cselect_b32 s17, s7, s44
	s_cselect_b32 s16, s36, s37
	s_add_i32 s48, 0, 0x14000
	ds_read_b128 v[140:143], v252
	ds_read_b128 v[148:151], v252 offset:1024
	ds_read_b128 v[152:155], v252 offset:2048
	ds_read_b128 v[156:159], v252 offset:3072
	ds_read_b128 v[178:181], v253
	ds_read_b128 v[182:185], v253 offset:1024
	ds_read_b128 v[186:189], v253 offset:2048
	ds_read_b128 v[190:193], v253 offset:3072
	s_add_i32 m0, s15, 0xc000
	ds_read_b128 v[194:197], v147
	ds_read_b128 v[208:211], v147 offset:1024
	ds_read_b128 v[212:215], v147 offset:2048
	ds_read_b128 v[216:219], v147 offset:3072
	ds_read_b128 v[220:223], v147 offset:4096
	ds_read_b128 v[224:227], v147 offset:5120
	ds_read_b128 v[228:231], v147 offset:6144
	ds_read_b128 v[232:235], v147 offset:7168
	global_load_lds_dwordx4 v136, s[0:1]
	s_add_i32 m0, s15, 0xe000
	s_nop 0
	global_load_lds_dwordx4 v138, s[0:1]
	s_waitcnt vmcnt(8)
	s_waitcnt lgkmcnt(0)
	s_barrier
	s_setprio 1
	s_waitcnt lgkmcnt(0)
	v_mfma_f32_16x16x32_bf16 v[126:129], v[140:143], v[194:197], v[126:129]
	v_mfma_f32_16x16x32_bf16 v[122:125], v[152:155], v[194:197], v[122:125]
	v_mfma_f32_16x16x32_bf16 v[110:113], v[140:143], v[212:215], v[110:113]
	v_mfma_f32_16x16x32_bf16 v[106:109], v[152:155], v[212:215], v[106:109]
	s_setprio 0
	s_setprio 1
	v_mfma_f32_16x16x32_bf16 v[94:97], v[140:143], v[220:223], v[94:97]
	v_mfma_f32_16x16x32_bf16 v[90:93], v[152:155], v[220:223], v[90:93]
	v_mfma_f32_16x16x32_bf16 v[78:81], v[140:143], v[228:231], v[78:81]
	v_mfma_f32_16x16x32_bf16 v[74:77], v[152:155], v[228:231], v[74:77]
	s_setprio 0
	s_setprio 1
	v_mfma_f32_16x16x32_bf16 v[126:129], v[148:151], v[208:211], v[126:129]
	v_mfma_f32_16x16x32_bf16 v[122:125], v[156:159], v[208:211], v[122:125]
	v_mfma_f32_16x16x32_bf16 v[110:113], v[148:151], v[216:219], v[110:113]
	v_mfma_f32_16x16x32_bf16 v[106:109], v[156:159], v[216:219], v[106:109]
	s_setprio 0
	s_setprio 1
	v_mfma_f32_16x16x32_bf16 v[94:97], v[148:151], v[224:227], v[94:97]
	v_mfma_f32_16x16x32_bf16 v[90:93], v[156:159], v[224:227], v[90:93]
	v_mfma_f32_16x16x32_bf16 v[78:81], v[148:151], v[232:235], v[78:81]
	v_mfma_f32_16x16x32_bf16 v[74:77], v[156:159], v[232:235], v[74:77]
	s_setprio 0
	s_setprio 1
	v_mfma_f32_16x16x32_bf16 v[118:121], v[178:181], v[194:197], v[118:121]
	v_mfma_f32_16x16x32_bf16 v[114:117], v[186:189], v[194:197], v[114:117]
	v_mfma_f32_16x16x32_bf16 v[102:105], v[178:181], v[212:215], v[102:105]
	v_mfma_f32_16x16x32_bf16 v[98:101], v[186:189], v[212:215], v[98:101]
	v_mfma_f32_16x16x32_bf16 v[86:89], v[178:181], v[220:223], v[86:89]
	v_mfma_f32_16x16x32_bf16 v[82:85], v[186:189], v[220:223], v[82:85]
	v_mfma_f32_16x16x32_bf16 v[70:73], v[178:181], v[228:231], v[70:73]
	v_mfma_f32_16x16x32_bf16 v[66:69], v[186:189], v[228:231], v[66:69]
	s_setprio 0
	s_setprio 1
	v_mfma_f32_16x16x32_bf16 v[118:121], v[182:185], v[208:211], v[118:121]
	v_mfma_f32_16x16x32_bf16 v[114:117], v[190:193], v[208:211], v[114:117]
	v_mfma_f32_16x16x32_bf16 v[102:105], v[182:185], v[216:219], v[102:105]
	v_mfma_f32_16x16x32_bf16 v[98:101], v[190:193], v[216:219], v[98:101]
	v_mfma_f32_16x16x32_bf16 v[86:89], v[182:185], v[224:227], v[86:89]
	v_mfma_f32_16x16x32_bf16 v[82:85], v[190:193], v[224:227], v[82:85]
	v_mfma_f32_16x16x32_bf16 v[70:73], v[182:185], v[232:235], v[70:73]
	v_mfma_f32_16x16x32_bf16 v[66:69], v[190:193], v[232:235], v[66:69]
	s_setprio 0
	s_barrier
	s_add_i32 s46, s46, s28
	s_mov_b32 m0, s46
	ds_read_b128 v[194:197], v147 offset:16384
	ds_read_b128 v[208:211], v147 offset:17408
	ds_read_b128 v[212:215], v147 offset:18432
	ds_read_b128 v[216:219], v147 offset:19456
	ds_read_b128 v[220:223], v147 offset:20480
	ds_read_b128 v[224:227], v147 offset:21504
	ds_read_b128 v[228:231], v147 offset:22528
	ds_read_b128 v[232:235], v147 offset:23552
	global_load_lds_dwordx4 v64, s[16:17]
	s_add_i32 m0, s46, 0x2000
	s_add_u32 s46, s16, 0x80000
	s_addc_u32 s47, s17, 0
	s_add_i32 s48, s48, s28
	global_load_lds_dwordx4 v130, s[16:17]
	s_mov_b32 m0, s48
	s_mov_b64 s[100:101], s[18:19]
	global_load_lds_dwordx4 v64, s[46:47]
	s_add_i32 m0, s48, 0x2000
	s_nop 0
	global_load_lds_dwordx4 v130, s[46:47]
	s_mov_b32 m0, s15
	s_nop 0
	global_load_lds_dwordx4 v134, s[18:19]
	s_mov_b32 m0, s27
	s_nop 0
	global_load_lds_dwordx4 v132, s[18:19]
	s_waitcnt vmcnt(8)
	s_waitcnt lgkmcnt(0)
	s_barrier
; #define PG8_STAGE(bufoff, gbase, voff) do { _Pragma("unroll") for (int _i = 0; _i < 2; ++_i) \
;         __builtin_amdgcn_global_load_lds((const unsigned*)((const char*)(gbase) + (voff)[_i]), (PG8_LAS unsigned*)(lds + (bufoff) + ldsw + _i * 8192), 16, 0, 0); } while (0)
; #define PG8_LDA(dst, b, h) do { _Pragma("unroll") for (int m = 0; m < 4; ++m) _Pragma("unroll") for (int k = 0; k < 2; ++k) dst[m][k] = *(const PG8_LAS bf16x8*)(lds + PG8_SA(b, h) + aoff + m * 2048 + k * 1024); } while (0)
; #define PG8_LDB(dst, b, h) do { _Pragma("unroll") for (int n = 0; n < 2; ++n) _Pragma("unroll") for (int k = 0; k < 2; ++k) dst[n][k] = *(const PG8_LAS bf16x8*)(lds + PG8_SB(b, h) + boff + n * 2048 + k * 1024); } while (0)
; #define PG8_MMA(ai, bj, At, Bt) do { __builtin_amdgcn_s_setprio(1); _Pragma("unroll") for (int m = 0; m < 4; ++m) _Pragma("unroll") for (int n = 0; n < 2; ++n) _Pragma("unroll") for (int k = 0; k < 2; ++k) \
;         acc[ai][bj][m][n] = __builtin_amdgcn_mfma_f32_16x16x32_bf16(Bt[n][k], At[m][k], acc[ai][bj][m][n], 0, 0, 0); __builtin_amdgcn_s_setprio(0); } while (0)
; template <class Epi, class Sched, bool ALIGN_EPI = false, bool SP2 = false>
; __device__ __forceinline__ void gemm_phase(PG8_LAS unsigned char* lds, const Gemm g, const Sched& S, const Epi& E, const int wave0) {
;     ...
;             if constexpr (SP2) {
;             PG8_LDB(B0, 0, 0); PG8_LDB(B1, 0, 1); PG8_SCHED; PG8_LDA(At, 0, 0); PG8_STAGE(PG8_SA(1, 1), a1 + hstepA, voffA);
;             PG8_WAIT_V(8); PG8_WAIT_L(0); PG8_BAR; PG8_MMA(0, 0, At, B0); PG8_MMA(0, 1, At, B1); PG8_BAR; PG8_SCHED;
;             PG8_LDA(At, 0, 1); PG8_STAGE(PG8_SB(0, 0), b2, voffB); PG8_STAGE(PG8_SB(0, 1), b2 + hstepB, voffB); PG8_STAGE(PG8_SA(0, 0), a2, voffA);
;             PG8_WAIT_V(8); PG8_WAIT_L(0); PG8_BAR; PG8_MMA(1, 0, At, B0); PG8_MMA(1, 1, At, B1); PG8_BAR; PG8_SCHED;
;             PG8_LDB(B0, 1, 0); PG8_LDB(B1, 1, 1); PG8_SCHED; PG8_LDA(At, 1, 0); PG8_STAGE(PG8_SA(0, 1), a2 + hstepA, voffA);
;             PG8_WAIT_V(8); PG8_WAIT_L(0); PG8_BAR; PG8_MMA(0, 0, At, B0); PG8_MMA(0, 1, At, B1); PG8_BAR; PG8_SCHED;
;             PG8_LDA(At, 1, 1); PG8_STAGE(PG8_SB(1, 0), b3, voffB); PG8_STAGE(PG8_SB(1, 1), b3 + hstepB, voffB); PG8_STAGE(PG8_SA(1, 0), a3, voffA);
;             PG8_WAIT_V(8); PG8_WAIT_L(0); PG8_BAR; PG8_MMA(1, 0, At, B0); PG8_MMA(1, 1, At, B1); PG8_BAR; PG8_SCHED;
	s_setprio 1
	s_waitcnt lgkmcnt(0)
	v_mfma_f32_16x16x32_bf16 v[60:63], v[140:143], v[194:197], v[60:63]
	v_mfma_f32_16x16x32_bf16 v[56:59], v[152:155], v[194:197], v[56:59]
	v_mfma_f32_16x16x32_bf16 v[44:47], v[140:143], v[212:215], v[44:47]
	v_mfma_f32_16x16x32_bf16 v[40:43], v[152:155], v[212:215], v[40:43]
	s_setprio 0
	s_setprio 1
	v_mfma_f32_16x16x32_bf16 v[28:31], v[140:143], v[220:223], v[28:31]
	v_mfma_f32_16x16x32_bf16 v[24:27], v[152:155], v[220:223], v[24:27]
	v_mfma_f32_16x16x32_bf16 v[12:15], v[140:143], v[228:231], v[12:15]
	v_mfma_f32_16x16x32_bf16 v[8:11], v[152:155], v[228:231], v[8:11]
	s_setprio 0
	s_setprio 1
	v_mfma_f32_16x16x32_bf16 v[60:63], v[148:151], v[208:211], v[60:63]
	v_mfma_f32_16x16x32_bf16 v[56:59], v[156:159], v[208:211], v[56:59]
	v_mfma_f32_16x16x32_bf16 v[44:47], v[148:151], v[216:219], v[44:47]
	v_mfma_f32_16x16x32_bf16 v[40:43], v[156:159], v[216:219], v[40:43]
	s_setprio 0
	s_setprio 1
	v_mfma_f32_16x16x32_bf16 v[28:31], v[148:151], v[224:227], v[28:31]
	v_mfma_f32_16x16x32_bf16 v[24:27], v[156:159], v[224:227], v[24:27]
	v_mfma_f32_16x16x32_bf16 v[12:15], v[148:151], v[232:235], v[12:15]
	v_mfma_f32_16x16x32_bf16 v[8:11], v[156:159], v[232:235], v[8:11]
	s_setprio 0
	s_setprio 1
	v_mfma_f32_16x16x32_bf16 v[52:55], v[178:181], v[194:197], v[52:55]
	v_mfma_f32_16x16x32_bf16 v[48:51], v[186:189], v[194:197], v[48:51]
	v_mfma_f32_16x16x32_bf16 v[36:39], v[178:181], v[212:215], v[36:39]
	v_mfma_f32_16x16x32_bf16 v[32:35], v[186:189], v[212:215], v[32:35]
	v_mfma_f32_16x16x32_bf16 v[20:23], v[178:181], v[220:223], v[20:23]
	v_mfma_f32_16x16x32_bf16 v[16:19], v[186:189], v[220:223], v[16:19]
	v_mfma_f32_16x16x32_bf16 v[4:7], v[178:181], v[228:231], v[4:7]
	v_mfma_f32_16x16x32_bf16 v[0:3], v[186:189], v[228:231], v[0:3]
	s_setprio 0
	s_setprio 1
	v_mfma_f32_16x16x32_bf16 v[52:55], v[182:185], v[208:211], v[52:55]
	v_mfma_f32_16x16x32_bf16 v[48:51], v[190:193], v[208:211], v[48:51]
	v_mfma_f32_16x16x32_bf16 v[36:39], v[182:185], v[216:219], v[36:39]
	v_mfma_f32_16x16x32_bf16 v[32:35], v[190:193], v[216:219], v[32:35]
	v_mfma_f32_16x16x32_bf16 v[20:23], v[182:185], v[224:227], v[20:23]
	v_mfma_f32_16x16x32_bf16 v[16:19], v[190:193], v[224:227], v[16:19]
	v_mfma_f32_16x16x32_bf16 v[4:7], v[182:185], v[232:235], v[4:7]
	v_mfma_f32_16x16x32_bf16 v[0:3], v[190:193], v[232:235], v[0:3]
	s_setprio 0
	s_barrier
	s_add_i32 s46, 0, 0x18000
	s_add_i32 s47, 0, 0x1c000
	ds_read_b128 v[140:143], v254
	ds_read_b128 v[148:151], v254 offset:1024
	ds_read_b128 v[152:155], v254 offset:2048
	ds_read_b128 v[156:159], v254 offset:3072
	ds_read_b128 v[178:181], v255
	ds_read_b128 v[182:185], v255 offset:1024
	ds_read_b128 v[186:189], v255 offset:2048
	ds_read_b128 v[190:193], v255 offset:3072
	s_add_u32 s18, s18, 0x80000
	s_addc_u32 s19, s19, 0
	s_mov_b32 m0, s29
	ds_read_b128 v[194:197], v147 offset:32768
	ds_read_b128 v[208:211], v147 offset:33792
	ds_read_b128 v[212:215], v147 offset:34816
	ds_read_b128 v[216:219], v147 offset:35840
	ds_read_b128 v[220:223], v147 offset:36864
	ds_read_b128 v[224:227], v147 offset:37888
	ds_read_b128 v[228:231], v147 offset:38912
	ds_read_b128 v[232:235], v147 offset:39936
	global_load_lds_dwordx4 v134, s[18:19]
	s_mov_b32 m0, s30
	s_nop 0
	global_load_lds_dwordx4 v132, s[18:19]
	s_waitcnt vmcnt(8)
	s_waitcnt lgkmcnt(0)
	s_barrier
	s_setprio 1
	s_waitcnt lgkmcnt(0)
	v_mfma_f32_16x16x32_bf16 v[126:129], v[140:143], v[194:197], v[126:129]
	v_mfma_f32_16x16x32_bf16 v[122:125], v[152:155], v[194:197], v[122:125]
	v_mfma_f32_16x16x32_bf16 v[110:113], v[140:143], v[212:215], v[110:113]
	v_mfma_f32_16x16x32_bf16 v[106:109], v[152:155], v[212:215], v[106:109]
	s_setprio 0
	s_setprio 1
	v_mfma_f32_16x16x32_bf16 v[94:97], v[140:143], v[220:223], v[94:97]
	v_mfma_f32_16x16x32_bf16 v[90:93], v[152:155], v[220:223], v[90:93]
	v_mfma_f32_16x16x32_bf16 v[78:81], v[140:143], v[228:231], v[78:81]
	v_mfma_f32_16x16x32_bf16 v[74:77], v[152:155], v[228:231], v[74:77]
	s_setprio 0
	s_setprio 1
	v_mfma_f32_16x16x32_bf16 v[126:129], v[148:151], v[208:211], v[126:129]
	v_mfma_f32_16x16x32_bf16 v[122:125], v[156:159], v[208:211], v[122:125]
	v_mfma_f32_16x16x32_bf16 v[110:113], v[148:151], v[216:219], v[110:113]
	v_mfma_f32_16x16x32_bf16 v[106:109], v[156:159], v[216:219], v[106:109]
	s_setprio 0
	s_setprio 1
	v_mfma_f32_16x16x32_bf16 v[94:97], v[148:151], v[224:227], v[94:97]
	v_mfma_f32_16x16x32_bf16 v[90:93], v[156:159], v[224:227], v[90:93]
	v_mfma_f32_16x16x32_bf16 v[78:81], v[148:151], v[232:235], v[78:81]
	v_mfma_f32_16x16x32_bf16 v[74:77], v[156:159], v[232:235], v[74:77]
	s_setprio 0
	s_setprio 1
	v_mfma_f32_16x16x32_bf16 v[118:121], v[178:181], v[194:197], v[118:121]
	v_mfma_f32_16x16x32_bf16 v[114:117], v[186:189], v[194:197], v[114:117]
	v_mfma_f32_16x16x32_bf16 v[102:105], v[178:181], v[212:215], v[102:105]
	v_mfma_f32_16x16x32_bf16 v[98:101], v[186:189], v[212:215], v[98:101]
	v_mfma_f32_16x16x32_bf16 v[86:89], v[178:181], v[220:223], v[86:89]
	v_mfma_f32_16x16x32_bf16 v[82:85], v[186:189], v[220:223], v[82:85]
	v_mfma_f32_16x16x32_bf16 v[70:73], v[178:181], v[228:231], v[70:73]
	v_mfma_f32_16x16x32_bf16 v[66:69], v[186:189], v[228:231], v[66:69]
	s_setprio 0
	s_setprio 1
	v_mfma_f32_16x16x32_bf16 v[118:121], v[182:185], v[208:211], v[118:121]
	v_mfma_f32_16x16x32_bf16 v[114:117], v[190:193], v[208:211], v[114:117]
	v_mfma_f32_16x16x32_bf16 v[102:105], v[182:185], v[216:219], v[102:105]
	v_mfma_f32_16x16x32_bf16 v[98:101], v[190:193], v[216:219], v[98:101]
	v_mfma_f32_16x16x32_bf16 v[86:89], v[182:185], v[224:227], v[86:89]
	v_mfma_f32_16x16x32_bf16 v[82:85], v[190:193], v[224:227], v[82:85]
	v_mfma_f32_16x16x32_bf16 v[70:73], v[182:185], v[232:235], v[70:73]
	v_mfma_f32_16x16x32_bf16 v[66:69], v[190:193], v[232:235], v[66:69]
	s_setprio 0
	s_barrier
; #define PG8_STAGE(bufoff, gbase, voff) do { _Pragma("unroll") for (int _i = 0; _i < 2; ++_i) \
;         __builtin_amdgcn_global_load_lds((const unsigned*)((const char*)(gbase) + (voff)[_i]), (PG8_LAS unsigned*)(lds + (bufoff) + ldsw + _i * 8192), 16, 0, 0); } while (0)
; #define PG8_LDA(dst, b, h) do { _Pragma("unroll") for (int m = 0; m < 4; ++m) _Pragma("unroll") for (int k = 0; k < 2; ++k) dst[m][k] = *(const PG8_LAS bf16x8*)(lds + PG8_SA(b, h) + aoff + m * 2048 + k * 1024); } while (0)
; #define PG8_WAIT_V(n) asm volatile("s_waitcnt vmcnt(" #n ")" ::: "memory")
; #define PG8_WAIT_L(n) asm volatile("s_waitcnt lgkmcnt(" #n ")" ::: "memory")
; #define PG8_BAR __builtin_amdgcn_s_barrier()
; template <class Epi, class Sched, bool ALIGN_EPI = false, bool SP2 = false>
; __device__ __forceinline__ void gemm_phase(PG8_LAS unsigned char* lds, const Gemm g, const Sched& S, const Epi& E, const int wave0) {
;     ...
;         for (int t = 0; t < nt; t += 2) {
;             const bool last = (t == nt - 2);
;             const char* a1 = cA + (size_t)(t + 1) * kstep;
;             const char* a2 = last ? nA : cA + (size_t)(t + 2) * kstep; const char* b2 = last ? nB : cB + (size_t)(t + 2) * kstep;
;             const char* a3 = a2 + kstep; const char* b3 = b2 + kstep;
;             if (last && has_next) S.a_ready(nxt);
;             if constexpr (SP2) {
;             PG8_LDB(B0, 0, 0); PG8_LDB(B1, 0, 1); PG8_SCHED; PG8_LDA(At, 0, 0); PG8_STAGE(PG8_SA(1, 1), a1 + hstepA, voffA);
;             PG8_WAIT_V(8); PG8_WAIT_L(0); PG8_BAR; PG8_MMA(0, 0, At, B0); PG8_MMA(0, 1, At, B1); PG8_BAR; PG8_SCHED;
;             PG8_LDA(At, 0, 1); PG8_STAGE(PG8_SB(0, 0), b2, voffB); PG8_STAGE(PG8_SB(0, 1), b2 + hstepB, voffB); PG8_STAGE(PG8_SA(0, 0), a2, voffA);
;             PG8_WAIT_V(8); PG8_WAIT_L(0); PG8_BAR; PG8_MMA(1, 0, At, B0); PG8_MMA(1, 1, At, B1); PG8_BAR; PG8_SCHED;
;             PG8_LDB(B0, 1, 0); PG8_LDB(B1, 1, 1); PG8_SCHED; PG8_LDA(At, 1, 0); PG8_STAGE(PG8_SA(0, 1), a2 + hstepA, voffA);
;             PG8_WAIT_V(8); PG8_WAIT_L(0); PG8_BAR; PG8_MMA(0, 0, At, B0); PG8_MMA(0, 1, At, B1); PG8_BAR; PG8_SCHED;
;             PG8_LDA(At, 1, 1); PG8_STAGE(PG8_SB(1, 0), b3, voffB); PG8_STAGE(PG8_SB(1, 1), b3 + hstepB, voffB); PG8_STAGE(PG8_SA(1, 0), a3, voffA);
;             PG8_WAIT_V(8); PG8_WAIT_L(0); PG8_BAR; PG8_MMA(1, 0, At, B0); PG8_MMA(1, 1, At, B1); PG8_BAR; PG8_SCHED;
	s_add_i32 s18, s46, s28
	s_add_u32 s50, s16, 0x80
	s_addc_u32 s51, s17, 0
	s_mov_b32 m0, s18
	ds_read_b128 v[194:197], v147 offset:49152
	ds_read_b128 v[208:211], v147 offset:50176
	ds_read_b128 v[212:215], v147 offset:51200
	ds_read_b128 v[216:219], v147 offset:52224
	ds_read_b128 v[220:223], v147 offset:53248
	ds_read_b128 v[224:227], v147 offset:54272
	ds_read_b128 v[228:231], v147 offset:55296
	ds_read_b128 v[232:235], v147 offset:56320
	global_load_lds_dwordx4 v64, s[50:51]
	s_add_i32 m0, s18, 0x2000
	s_add_u32 s16, s16, 0x80080
	s_addc_u32 s17, s17, 0
	s_add_i32 s18, s47, s28
	global_load_lds_dwordx4 v130, s[50:51]
	s_mov_b32 m0, s18
	s_nop 0
	global_load_lds_dwordx4 v64, s[16:17]
	s_add_i32 m0, s18, 0x2000
	s_nop 0
	global_load_lds_dwordx4 v130, s[16:17]
	s_add_u32 s100, s100, 0x80
	s_addc_u32 s101, s101, 0
	s_mov_b32 m0, s31
	s_nop 0
	global_load_lds_dwordx4 v134, s[100:101]
	s_mov_b32 m0, s34
	s_nop 0
	global_load_lds_dwordx4 v132, s[100:101]
	s_waitcnt vmcnt(8)
	s_waitcnt lgkmcnt(0)
	s_barrier
	s_setprio 1
	s_waitcnt lgkmcnt(0)
	v_mfma_f32_16x16x32_bf16 v[60:63], v[140:143], v[194:197], v[60:63]
	v_mfma_f32_16x16x32_bf16 v[56:59], v[152:155], v[194:197], v[56:59]
	v_mfma_f32_16x16x32_bf16 v[44:47], v[140:143], v[212:215], v[44:47]
	v_mfma_f32_16x16x32_bf16 v[40:43], v[152:155], v[212:215], v[40:43]
	s_setprio 0
	s_setprio 1
	v_mfma_f32_16x16x32_bf16 v[28:31], v[140:143], v[220:223], v[28:31]
	v_mfma_f32_16x16x32_bf16 v[24:27], v[152:155], v[220:223], v[24:27]
	v_mfma_f32_16x16x32_bf16 v[12:15], v[140:143], v[228:231], v[12:15]
	v_mfma_f32_16x16x32_bf16 v[8:11], v[152:155], v[228:231], v[8:11]
	s_setprio 0
	s_setprio 1
	v_mfma_f32_16x16x32_bf16 v[60:63], v[148:151], v[208:211], v[60:63]
	v_mfma_f32_16x16x32_bf16 v[56:59], v[156:159], v[208:211], v[56:59]
	v_mfma_f32_16x16x32_bf16 v[44:47], v[148:151], v[216:219], v[44:47]
	v_mfma_f32_16x16x32_bf16 v[40:43], v[156:159], v[216:219], v[40:43]
	s_setprio 0
	s_setprio 1
	v_mfma_f32_16x16x32_bf16 v[28:31], v[148:151], v[224:227], v[28:31]
	v_mfma_f32_16x16x32_bf16 v[24:27], v[156:159], v[224:227], v[24:27]
	v_mfma_f32_16x16x32_bf16 v[12:15], v[148:151], v[232:235], v[12:15]
	v_mfma_f32_16x16x32_bf16 v[8:11], v[156:159], v[232:235], v[8:11]
	s_setprio 0
	s_setprio 1
	v_mfma_f32_16x16x32_bf16 v[52:55], v[178:181], v[194:197], v[52:55]
	v_mfma_f32_16x16x32_bf16 v[48:51], v[186:189], v[194:197], v[48:51]
	v_mfma_f32_16x16x32_bf16 v[36:39], v[178:181], v[212:215], v[36:39]
	v_mfma_f32_16x16x32_bf16 v[32:35], v[186:189], v[212:215], v[32:35]
	v_mfma_f32_16x16x32_bf16 v[20:23], v[178:181], v[220:223], v[20:23]
	v_mfma_f32_16x16x32_bf16 v[16:19], v[186:189], v[220:223], v[16:19]
	v_mfma_f32_16x16x32_bf16 v[4:7], v[178:181], v[228:231], v[4:7]
	v_mfma_f32_16x16x32_bf16 v[0:3], v[186:189], v[228:231], v[0:3]
	s_setprio 0
	s_setprio 1
	v_mfma_f32_16x16x32_bf16 v[52:55], v[182:185], v[208:211], v[52:55]
	v_mfma_f32_16x16x32_bf16 v[48:51], v[190:193], v[208:211], v[48:51]
	v_mfma_f32_16x16x32_bf16 v[36:39], v[182:185], v[216:219], v[36:39]
	v_mfma_f32_16x16x32_bf16 v[32:35], v[190:193], v[216:219], v[32:35]
	v_mfma_f32_16x16x32_bf16 v[20:23], v[182:185], v[224:227], v[20:23]
	v_mfma_f32_16x16x32_bf16 v[16:19], v[190:193], v[224:227], v[16:19]
	v_mfma_f32_16x16x32_bf16 v[4:7], v[182:185], v[232:235], v[4:7]
	v_mfma_f32_16x16x32_bf16 v[0:3], v[190:193], v[232:235], v[0:3]
	s_setprio 0
	s_barrier
	s_add_i32 s45, s45, 2
	s_add_u32 s0, s0, 0x100
	s_addc_u32 s1, s1, 0
	s_add_u32 s37, s37, 0x100
	s_addc_u32 s44, s44, 0
	s_cmp_gt_u32 s45, 29
	s_cbranch_scc0 .LBB0_1571
	s_mov_b64 s[50:51], 0x80
	s_and_b64 vcc, exec, s[4:5]
	s_cbranch_vccz .LBB0_1574
	s_barrier

; #define PG8_STAGE(bufoff, gbase, voff) do { _Pragma("unroll") for (int _i = 0; _i < 2; ++_i) \
;         __builtin_amdgcn_global_load_lds((const unsigned*)((const char*)(gbase) + (voff)[_i]), (PG8_LAS unsigned*)(lds + (bufoff) + ldsw + _i * 8192), 16, 0, 0); } while (0)
; #define PG8_LDA(dst, b, h) do { _Pragma("unroll") for (int m = 0; m < 4; ++m) _Pragma("unroll") for (int k = 0; k < 2; ++k) dst[m][k] = *(const PG8_LAS bf16x8*)(lds + PG8_SA(b, h) + aoff + m * 2048 + k * 1024); } while (0)
; #define PG8_WAIT_V(n) asm volatile("s_waitcnt vmcnt(" #n ")" ::: "memory")
; #define PG8_WAIT_L(n) asm volatile("s_waitcnt lgkmcnt(" #n ")" ::: "memory")
; #define PG8_BAR __builtin_amdgcn_s_barrier()
; template <class Epi, class Sched, bool ALIGN_EPI = false, bool SP2 = false>
; __device__ __forceinline__ void gemm_phase(PG8_LAS unsigned char* lds, const Gemm g, const Sched& S, const Epi& E, const int wave0) {
;     ...
;         for (int t = 0; t < nt; t += 2) {
;             const bool last = (t == nt - 2);
;             const char* a1 = cA + (size_t)(t + 1) * kstep;
;             const char* a2 = last ? nA : cA + (size_t)(t + 2) * kstep; const char* b2 = last ? nB : cB + (size_t)(t + 2) * kstep;
;             const char* a3 = a2 + kstep; const char* b3 = b2 + kstep;
;             if (last && has_next) S.a_ready(nxt);
;             if constexpr (SP2) {
;             PG8_LDB(B0, 0, 0); PG8_LDB(B1, 0, 1); PG8_SCHED; PG8_LDA(At, 0, 0); PG8_STAGE(PG8_SA(1, 1), a1 + hstepA, voffA);
;             PG8_WAIT_V(8); PG8_WAIT_L(0); PG8_BAR; PG8_MMA(0, 0, At, B0); PG8_MMA(0, 1, At, B1); PG8_BAR; PG8_SCHED;
;             PG8_LDA(At, 0, 1); PG8_STAGE(PG8_SB(0, 0), b2, voffB); PG8_STAGE(PG8_SB(0, 1), b2 + hstepB, voffB); PG8_STAGE(PG8_SA(0, 0), a2, voffA);
;             PG8_WAIT_V(8); PG8_WAIT_L(0); PG8_BAR; PG8_MMA(1, 0, At, B0); PG8_MMA(1, 1, At, B1); PG8_BAR; PG8_SCHED;
;             PG8_LDB(B0, 1, 0); PG8_LDB(B1, 1, 1); PG8_SCHED; PG8_LDA(At, 1, 0); PG8_STAGE(PG8_SA(0, 1), a2 + hstepA, voffA);
;             PG8_WAIT_V(8); PG8_WAIT_L(0); PG8_BAR; PG8_MMA(0, 0, At, B0); PG8_MMA(0, 1, At, B1); PG8_BAR; PG8_SCHED;
;             PG8_LDA(At, 1, 1); PG8_STAGE(PG8_SB(1, 0), b3, voffB); PG8_STAGE(PG8_SB(1, 1), b3 + hstepB, voffB); PG8_STAGE(PG8_SA(1, 0), a3, voffA);
;             PG8_WAIT_V(8); PG8_WAIT_L(0); PG8_BAR; PG8_MMA(1, 0, At, B0); PG8_MMA(1, 1, At, B1); PG8_BAR; PG8_SCHED;
.LBB0_1685:
	s_add_u32 s16, s0, 0xffe00080
	s_addc_u32 s17, s1, -1
	s_add_i32 s43, 0, 0x10000
	s_cmpk_eq_i32 s42, 0x7c
	s_cselect_b32 s19, s11, s17
	s_cselect_b32 s18, s34, s16
	s_cselect_b32 s17, s9, s37
	s_cselect_b32 s16, s35, s36
	s_add_i32 s46, 0, 0x14000
	ds_read_b128 v[144:147], v252
	ds_read_b128 v[148:151], v252 offset:1024
	ds_read_b128 v[152:155], v252 offset:2048
	ds_read_b128 v[156:159], v252 offset:3072
	ds_read_b128 v[178:181], v253
	ds_read_b128 v[182:185], v253 offset:1024
	ds_read_b128 v[186:189], v253 offset:2048
	ds_read_b128 v[190:193], v253 offset:3072
	s_add_i32 m0, s21, 0xc000
	ds_read_b128 v[194:197], v143
	ds_read_b128 v[208:211], v143 offset:1024
	ds_read_b128 v[212:215], v143 offset:2048
	ds_read_b128 v[216:219], v143 offset:3072
	ds_read_b128 v[220:223], v143 offset:4096
	ds_read_b128 v[224:227], v143 offset:5120
	ds_read_b128 v[228:231], v143 offset:6144
	ds_read_b128 v[232:235], v143 offset:7168
	global_load_lds_dwordx4 v136, s[0:1]
	s_add_i32 m0, s21, 0xe000
	s_nop 0
	global_load_lds_dwordx4 v138, s[0:1]
	s_waitcnt vmcnt(8)
	s_waitcnt lgkmcnt(0)
	s_barrier
	s_setprio 1
	s_waitcnt lgkmcnt(0)
	v_mfma_f32_16x16x32_bf16 v[126:129], v[144:147], v[194:197], v[126:129]
	v_mfma_f32_16x16x32_bf16 v[122:125], v[152:155], v[194:197], v[122:125]
	v_mfma_f32_16x16x32_bf16 v[118:121], v[144:147], v[212:215], v[118:121]
	v_mfma_f32_16x16x32_bf16 v[114:117], v[152:155], v[212:215], v[114:117]
	s_setprio 0
	s_setprio 1
	v_mfma_f32_16x16x32_bf16 v[102:105], v[144:147], v[220:223], v[102:105]
	v_mfma_f32_16x16x32_bf16 v[98:101], v[152:155], v[220:223], v[98:101]
	v_mfma_f32_16x16x32_bf16 v[86:89], v[144:147], v[228:231], v[86:89]
	v_mfma_f32_16x16x32_bf16 v[82:85], v[152:155], v[228:231], v[82:85]
	s_setprio 0
	s_setprio 1
	v_mfma_f32_16x16x32_bf16 v[126:129], v[148:151], v[208:211], v[126:129]
	v_mfma_f32_16x16x32_bf16 v[122:125], v[156:159], v[208:211], v[122:125]
	v_mfma_f32_16x16x32_bf16 v[118:121], v[148:151], v[216:219], v[118:121]
	v_mfma_f32_16x16x32_bf16 v[114:117], v[156:159], v[216:219], v[114:117]
	s_setprio 0
	s_setprio 1
	v_mfma_f32_16x16x32_bf16 v[102:105], v[148:151], v[224:227], v[102:105]
	v_mfma_f32_16x16x32_bf16 v[98:101], v[156:159], v[224:227], v[98:101]
	v_mfma_f32_16x16x32_bf16 v[86:89], v[148:151], v[232:235], v[86:89]
	v_mfma_f32_16x16x32_bf16 v[82:85], v[156:159], v[232:235], v[82:85]
	s_setprio 0
	s_setprio 1
	v_mfma_f32_16x16x32_bf16 v[110:113], v[178:181], v[194:197], v[110:113]
	v_mfma_f32_16x16x32_bf16 v[106:109], v[186:189], v[194:197], v[106:109]
	v_mfma_f32_16x16x32_bf16 v[94:97], v[178:181], v[212:215], v[94:97]
	v_mfma_f32_16x16x32_bf16 v[90:93], v[186:189], v[212:215], v[90:93]
	v_mfma_f32_16x16x32_bf16 v[78:81], v[178:181], v[220:223], v[78:81]
	v_mfma_f32_16x16x32_bf16 v[74:77], v[186:189], v[220:223], v[74:77]
	v_mfma_f32_16x16x32_bf16 v[70:73], v[178:181], v[228:231], v[70:73]
	v_mfma_f32_16x16x32_bf16 v[66:69], v[186:189], v[228:231], v[66:69]
	s_setprio 0
	s_setprio 1
	v_mfma_f32_16x16x32_bf16 v[110:113], v[182:185], v[208:211], v[110:113]
	v_mfma_f32_16x16x32_bf16 v[106:109], v[190:193], v[208:211], v[106:109]
	v_mfma_f32_16x16x32_bf16 v[94:97], v[182:185], v[216:219], v[94:97]
	v_mfma_f32_16x16x32_bf16 v[90:93], v[190:193], v[216:219], v[90:93]
	v_mfma_f32_16x16x32_bf16 v[78:81], v[182:185], v[224:227], v[78:81]
	v_mfma_f32_16x16x32_bf16 v[74:77], v[190:193], v[224:227], v[74:77]
	v_mfma_f32_16x16x32_bf16 v[70:73], v[182:185], v[232:235], v[70:73]
	v_mfma_f32_16x16x32_bf16 v[66:69], v[190:193], v[232:235], v[66:69]
	s_setprio 0
	s_barrier
	s_add_i32 s43, s43, s20
	s_mov_b32 m0, s43
	ds_read_b128 v[194:197], v143 offset:16384
	ds_read_b128 v[208:211], v143 offset:17408
	ds_read_b128 v[212:215], v143 offset:18432
	ds_read_b128 v[216:219], v143 offset:19456
	ds_read_b128 v[220:223], v143 offset:20480
	ds_read_b128 v[224:227], v143 offset:21504
	ds_read_b128 v[228:231], v143 offset:22528
	ds_read_b128 v[232:235], v143 offset:23552
	global_load_lds_dwordx4 v64, s[16:17]
	s_add_i32 m0, s43, 0x2000
	s_add_u32 s44, s16, 0x200000
	s_addc_u32 s45, s17, 0
	s_add_i32 s43, s46, s20
	global_load_lds_dwordx4 v130, s[16:17]
	s_mov_b32 m0, s43
	s_mov_b64 s[100:101], s[18:19]
	global_load_lds_dwordx4 v64, s[44:45]
	s_add_i32 m0, s43, 0x2000
	s_nop 0
	global_load_lds_dwordx4 v130, s[44:45]
	s_mov_b32 m0, s21
	s_nop 0
	global_load_lds_dwordx4 v134, s[18:19]
	s_mov_b32 m0, s25
	s_nop 0
	global_load_lds_dwordx4 v132, s[18:19]
	s_waitcnt vmcnt(8)
	s_waitcnt lgkmcnt(0)
	s_barrier
; #define PG8_STAGE(bufoff, gbase, voff) do { _Pragma("unroll") for (int _i = 0; _i < 2; ++_i) \
;         __builtin_amdgcn_global_load_lds((const unsigned*)((const char*)(gbase) + (voff)[_i]), (PG8_LAS unsigned*)(lds + (bufoff) + ldsw + _i * 8192), 16, 0, 0); } while (0)
; #define PG8_LDA(dst, b, h) do { _Pragma("unroll") for (int m = 0; m < 4; ++m) _Pragma("unroll") for (int k = 0; k < 2; ++k) dst[m][k] = *(const PG8_LAS bf16x8*)(lds + PG8_SA(b, h) + aoff + m * 2048 + k * 1024); } while (0)
; #define PG8_LDB(dst, b, h) do { _Pragma("unroll") for (int n = 0; n < 2; ++n) _Pragma("unroll") for (int k = 0; k < 2; ++k) dst[n][k] = *(const PG8_LAS bf16x8*)(lds + PG8_SB(b, h) + boff + n * 2048 + k * 1024); } while (0)
; #define PG8_MMA(ai, bj, At, Bt) do { __builtin_amdgcn_s_setprio(1); _Pragma("unroll") for (int m = 0; m < 4; ++m) _Pragma("unroll") for (int n = 0; n < 2; ++n) _Pragma("unroll") for (int k = 0; k < 2; ++k) \
;         acc[ai][bj][m][n] = __builtin_amdgcn_mfma_f32_16x16x32_bf16(Bt[n][k], At[m][k], acc[ai][bj][m][n], 0, 0, 0); __builtin_amdgcn_s_setprio(0); } while (0)
; template <class Epi, class Sched, bool ALIGN_EPI = false, bool SP2 = false>
; __device__ __forceinline__ void gemm_phase(PG8_LAS unsigned char* lds, const Gemm g, const Sched& S, const Epi& E, const int wave0) {
;     ...
;             if constexpr (SP2) {
;             PG8_LDB(B0, 0, 0); PG8_LDB(B1, 0, 1); PG8_SCHED; PG8_LDA(At, 0, 0); PG8_STAGE(PG8_SA(1, 1), a1 + hstepA, voffA);
;             PG8_WAIT_V(8); PG8_WAIT_L(0); PG8_BAR; PG8_MMA(0, 0, At, B0); PG8_MMA(0, 1, At, B1); PG8_BAR; PG8_SCHED;
;             PG8_LDA(At, 0, 1); PG8_STAGE(PG8_SB(0, 0), b2, voffB); PG8_STAGE(PG8_SB(0, 1), b2 + hstepB, voffB); PG8_STAGE(PG8_SA(0, 0), a2, voffA);
;             PG8_WAIT_V(8); PG8_WAIT_L(0); PG8_BAR; PG8_MMA(1, 0, At, B0); PG8_MMA(1, 1, At, B1); PG8_BAR; PG8_SCHED;
;             PG8_LDB(B0, 1, 0); PG8_LDB(B1, 1, 1); PG8_SCHED; PG8_LDA(At, 1, 0); PG8_STAGE(PG8_SA(0, 1), a2 + hstepA, voffA);
;             PG8_WAIT_V(8); PG8_WAIT_L(0); PG8_BAR; PG8_MMA(0, 0, At, B0); PG8_MMA(0, 1, At, B1); PG8_BAR; PG8_SCHED;
;             PG8_LDA(At, 1, 1); PG8_STAGE(PG8_SB(1, 0), b3, voffB); PG8_STAGE(PG8_SB(1, 1), b3 + hstepB, voffB); PG8_STAGE(PG8_SA(1, 0), a3, voffA);
;             PG8_WAIT_V(8); PG8_WAIT_L(0); PG8_BAR; PG8_MMA(1, 0, At, B0); PG8_MMA(1, 1, At, B1); PG8_BAR; PG8_SCHED;
	s_setprio 1
	s_waitcnt lgkmcnt(0)
	v_mfma_f32_16x16x32_bf16 v[60:63], v[144:147], v[194:197], v[60:63]
	v_mfma_f32_16x16x32_bf16 v[56:59], v[152:155], v[194:197], v[56:59]
	v_mfma_f32_16x16x32_bf16 v[52:55], v[144:147], v[212:215], v[52:55]
	v_mfma_f32_16x16x32_bf16 v[48:51], v[152:155], v[212:215], v[48:51]
	s_setprio 0
	s_setprio 1
	v_mfma_f32_16x16x32_bf16 v[36:39], v[144:147], v[220:223], v[36:39]
	v_mfma_f32_16x16x32_bf16 v[32:35], v[152:155], v[220:223], v[32:35]
	v_mfma_f32_16x16x32_bf16 v[20:23], v[144:147], v[228:231], v[20:23]
	v_mfma_f32_16x16x32_bf16 v[16:19], v[152:155], v[228:231], v[16:19]
	s_setprio 0
	s_setprio 1
	v_mfma_f32_16x16x32_bf16 v[60:63], v[148:151], v[208:211], v[60:63]
	v_mfma_f32_16x16x32_bf16 v[56:59], v[156:159], v[208:211], v[56:59]
	v_mfma_f32_16x16x32_bf16 v[52:55], v[148:151], v[216:219], v[52:55]
	v_mfma_f32_16x16x32_bf16 v[48:51], v[156:159], v[216:219], v[48:51]
	s_setprio 0
	s_setprio 1
	v_mfma_f32_16x16x32_bf16 v[36:39], v[148:151], v[224:227], v[36:39]
	v_mfma_f32_16x16x32_bf16 v[32:35], v[156:159], v[224:227], v[32:35]
	v_mfma_f32_16x16x32_bf16 v[20:23], v[148:151], v[232:235], v[20:23]
	v_mfma_f32_16x16x32_bf16 v[16:19], v[156:159], v[232:235], v[16:19]
	s_setprio 0
	s_setprio 1
	v_mfma_f32_16x16x32_bf16 v[44:47], v[178:181], v[194:197], v[44:47]
	v_mfma_f32_16x16x32_bf16 v[40:43], v[186:189], v[194:197], v[40:43]
	v_mfma_f32_16x16x32_bf16 v[28:31], v[178:181], v[212:215], v[28:31]
	v_mfma_f32_16x16x32_bf16 v[24:27], v[186:189], v[212:215], v[24:27]
	v_mfma_f32_16x16x32_bf16 v[12:15], v[178:181], v[220:223], v[12:15]
	v_mfma_f32_16x16x32_bf16 v[8:11], v[186:189], v[220:223], v[8:11]
	v_mfma_f32_16x16x32_bf16 v[4:7], v[178:181], v[228:231], v[4:7]
	v_mfma_f32_16x16x32_bf16 v[0:3], v[186:189], v[228:231], v[0:3]
	s_setprio 0
	s_setprio 1
	v_mfma_f32_16x16x32_bf16 v[44:47], v[182:185], v[208:211], v[44:47]
	v_mfma_f32_16x16x32_bf16 v[40:43], v[190:193], v[208:211], v[40:43]
	v_mfma_f32_16x16x32_bf16 v[28:31], v[182:185], v[216:219], v[28:31]
	v_mfma_f32_16x16x32_bf16 v[24:27], v[190:193], v[216:219], v[24:27]
	v_mfma_f32_16x16x32_bf16 v[12:15], v[182:185], v[224:227], v[12:15]
	v_mfma_f32_16x16x32_bf16 v[8:11], v[190:193], v[224:227], v[8:11]
	v_mfma_f32_16x16x32_bf16 v[4:7], v[182:185], v[232:235], v[4:7]
	v_mfma_f32_16x16x32_bf16 v[0:3], v[190:193], v[232:235], v[0:3]
	s_setprio 0
	s_barrier
	s_add_i32 s43, 0, 0x18000
	s_add_i32 s44, 0, 0x1c000
	ds_read_b128 v[144:147], v254
	ds_read_b128 v[148:151], v254 offset:1024
	ds_read_b128 v[152:155], v254 offset:2048
	ds_read_b128 v[156:159], v254 offset:3072
	ds_read_b128 v[178:181], v255
	ds_read_b128 v[182:185], v255 offset:1024
	ds_read_b128 v[186:189], v255 offset:2048
	ds_read_b128 v[190:193], v255 offset:3072
	s_add_u32 s18, s18, 0x200000
	s_addc_u32 s19, s19, 0
	s_mov_b32 m0, s26
	ds_read_b128 v[194:197], v143 offset:32768
	ds_read_b128 v[208:211], v143 offset:33792
	ds_read_b128 v[212:215], v143 offset:34816
	ds_read_b128 v[216:219], v143 offset:35840
	ds_read_b128 v[220:223], v143 offset:36864
	ds_read_b128 v[224:227], v143 offset:37888
	ds_read_b128 v[228:231], v143 offset:38912
	ds_read_b128 v[232:235], v143 offset:39936
	global_load_lds_dwordx4 v134, s[18:19]
	s_mov_b32 m0, s27
	s_nop 0
	global_load_lds_dwordx4 v132, s[18:19]
	s_waitcnt vmcnt(8)
	s_waitcnt lgkmcnt(0)
	s_barrier
	s_setprio 1
	s_waitcnt lgkmcnt(0)
	v_mfma_f32_16x16x32_bf16 v[126:129], v[144:147], v[194:197], v[126:129]
	v_mfma_f32_16x16x32_bf16 v[122:125], v[152:155], v[194:197], v[122:125]
	v_mfma_f32_16x16x32_bf16 v[118:121], v[144:147], v[212:215], v[118:121]
	v_mfma_f32_16x16x32_bf16 v[114:117], v[152:155], v[212:215], v[114:117]
	s_setprio 0
	s_setprio 1
	v_mfma_f32_16x16x32_bf16 v[102:105], v[144:147], v[220:223], v[102:105]
	v_mfma_f32_16x16x32_bf16 v[98:101], v[152:155], v[220:223], v[98:101]
	v_mfma_f32_16x16x32_bf16 v[86:89], v[144:147], v[228:231], v[86:89]
	v_mfma_f32_16x16x32_bf16 v[82:85], v[152:155], v[228:231], v[82:85]
	s_setprio 0
	s_setprio 1
	v_mfma_f32_16x16x32_bf16 v[126:129], v[148:151], v[208:211], v[126:129]
	v_mfma_f32_16x16x32_bf16 v[122:125], v[156:159], v[208:211], v[122:125]
	v_mfma_f32_16x16x32_bf16 v[118:121], v[148:151], v[216:219], v[118:121]
	v_mfma_f32_16x16x32_bf16 v[114:117], v[156:159], v[216:219], v[114:117]
	s_setprio 0
	s_setprio 1
	v_mfma_f32_16x16x32_bf16 v[102:105], v[148:151], v[224:227], v[102:105]
	v_mfma_f32_16x16x32_bf16 v[98:101], v[156:159], v[224:227], v[98:101]
	v_mfma_f32_16x16x32_bf16 v[86:89], v[148:151], v[232:235], v[86:89]
	v_mfma_f32_16x16x32_bf16 v[82:85], v[156:159], v[232:235], v[82:85]
	s_setprio 0
	s_setprio 1
	v_mfma_f32_16x16x32_bf16 v[110:113], v[178:181], v[194:197], v[110:113]
	v_mfma_f32_16x16x32_bf16 v[106:109], v[186:189], v[194:197], v[106:109]
	v_mfma_f32_16x16x32_bf16 v[94:97], v[178:181], v[212:215], v[94:97]
	v_mfma_f32_16x16x32_bf16 v[90:93], v[186:189], v[212:215], v[90:93]
	v_mfma_f32_16x16x32_bf16 v[78:81], v[178:181], v[220:223], v[78:81]
	v_mfma_f32_16x16x32_bf16 v[74:77], v[186:189], v[220:223], v[74:77]
	v_mfma_f32_16x16x32_bf16 v[70:73], v[178:181], v[228:231], v[70:73]
	v_mfma_f32_16x16x32_bf16 v[66:69], v[186:189], v[228:231], v[66:69]
	s_setprio 0
	s_setprio 1
	v_mfma_f32_16x16x32_bf16 v[110:113], v[182:185], v[208:211], v[110:113]
	v_mfma_f32_16x16x32_bf16 v[106:109], v[190:193], v[208:211], v[106:109]
	v_mfma_f32_16x16x32_bf16 v[94:97], v[182:185], v[216:219], v[94:97]
	v_mfma_f32_16x16x32_bf16 v[90:93], v[190:193], v[216:219], v[90:93]
	v_mfma_f32_16x16x32_bf16 v[78:81], v[182:185], v[224:227], v[78:81]
	v_mfma_f32_16x16x32_bf16 v[74:77], v[190:193], v[224:227], v[74:77]
	v_mfma_f32_16x16x32_bf16 v[70:73], v[182:185], v[232:235], v[70:73]
	v_mfma_f32_16x16x32_bf16 v[66:69], v[190:193], v[232:235], v[66:69]
	s_setprio 0
	s_barrier
; #define PG8_STAGE(bufoff, gbase, voff) do { _Pragma("unroll") for (int _i = 0; _i < 2; ++_i) \
;         __builtin_amdgcn_global_load_lds((const unsigned*)((const char*)(gbase) + (voff)[_i]), (PG8_LAS unsigned*)(lds + (bufoff) + ldsw + _i * 8192), 16, 0, 0); } while (0)
; #define PG8_LDA(dst, b, h) do { _Pragma("unroll") for (int m = 0; m < 4; ++m) _Pragma("unroll") for (int k = 0; k < 2; ++k) dst[m][k] = *(const PG8_LAS bf16x8*)(lds + PG8_SA(b, h) + aoff + m * 2048 + k * 1024); } while (0)
; #define PG8_WAIT_V(n) asm volatile("s_waitcnt vmcnt(" #n ")" ::: "memory")
; #define PG8_WAIT_L(n) asm volatile("s_waitcnt lgkmcnt(" #n ")" ::: "memory")
; #define PG8_BAR __builtin_amdgcn_s_barrier()
; template <class Epi, class Sched, bool ALIGN_EPI = false, bool SP2 = false>
; __device__ __forceinline__ void gemm_phase(PG8_LAS unsigned char* lds, const Gemm g, const Sched& S, const Epi& E, const int wave0) {
;     ...
;         for (int t = 0; t < nt; t += 2) {
;             const bool last = (t == nt - 2);
;             const char* a1 = cA + (size_t)(t + 1) * kstep;
;             const char* a2 = last ? nA : cA + (size_t)(t + 2) * kstep; const char* b2 = last ? nB : cB + (size_t)(t + 2) * kstep;
;             const char* a3 = a2 + kstep; const char* b3 = b2 + kstep;
;             if (last && has_next) S.a_ready(nxt);
;             if constexpr (SP2) {
;             PG8_LDB(B0, 0, 0); PG8_LDB(B1, 0, 1); PG8_SCHED; PG8_LDA(At, 0, 0); PG8_STAGE(PG8_SA(1, 1), a1 + hstepA, voffA);
;             PG8_WAIT_V(8); PG8_WAIT_L(0); PG8_BAR; PG8_MMA(0, 0, At, B0); PG8_MMA(0, 1, At, B1); PG8_BAR; PG8_SCHED;
;             PG8_LDA(At, 0, 1); PG8_STAGE(PG8_SB(0, 0), b2, voffB); PG8_STAGE(PG8_SB(0, 1), b2 + hstepB, voffB); PG8_STAGE(PG8_SA(0, 0), a2, voffA);
;             PG8_WAIT_V(8); PG8_WAIT_L(0); PG8_BAR; PG8_MMA(1, 0, At, B0); PG8_MMA(1, 1, At, B1); PG8_BAR; PG8_SCHED;
;             PG8_LDB(B0, 1, 0); PG8_LDB(B1, 1, 1); PG8_SCHED; PG8_LDA(At, 1, 0); PG8_STAGE(PG8_SA(0, 1), a2 + hstepA, voffA);
;             PG8_WAIT_V(8); PG8_WAIT_L(0); PG8_BAR; PG8_MMA(0, 0, At, B0); PG8_MMA(0, 1, At, B1); PG8_BAR; PG8_SCHED;
;             PG8_LDA(At, 1, 1); PG8_STAGE(PG8_SB(1, 0), b3, voffB); PG8_STAGE(PG8_SB(1, 1), b3 + hstepB, voffB); PG8_STAGE(PG8_SA(1, 0), a3, voffA);
;             PG8_WAIT_V(8); PG8_WAIT_L(0); PG8_BAR; PG8_MMA(1, 0, At, B0); PG8_MMA(1, 1, At, B1); PG8_BAR; PG8_SCHED;
	s_add_i32 s18, s43, s20
	s_add_u32 s48, s16, 0x80
	s_addc_u32 s49, s17, 0
	s_mov_b32 m0, s18
	ds_read_b128 v[194:197], v143 offset:49152
	ds_read_b128 v[208:211], v143 offset:50176
	ds_read_b128 v[212:215], v143 offset:51200
	ds_read_b128 v[216:219], v143 offset:52224
	ds_read_b128 v[220:223], v143 offset:53248
	ds_read_b128 v[224:227], v143 offset:54272
	ds_read_b128 v[228:231], v143 offset:55296
	ds_read_b128 v[232:235], v143 offset:56320
	global_load_lds_dwordx4 v64, s[48:49]
	s_add_i32 m0, s18, 0x2000
	s_add_u32 s16, s16, 0x200080
	s_addc_u32 s17, s17, 0
	s_add_i32 s18, s44, s20
	global_load_lds_dwordx4 v130, s[48:49]
	s_mov_b32 m0, s18
	s_nop 0
	global_load_lds_dwordx4 v64, s[16:17]
	s_add_i32 m0, s18, 0x2000
	s_nop 0
	global_load_lds_dwordx4 v130, s[16:17]
	s_add_u32 s100, s100, 0x80
	s_addc_u32 s101, s101, 0
	s_mov_b32 m0, s28
	s_nop 0
	global_load_lds_dwordx4 v134, s[100:101]
	s_mov_b32 m0, s29
	s_nop 0
	global_load_lds_dwordx4 v132, s[100:101]
	s_waitcnt vmcnt(8)
	s_waitcnt lgkmcnt(0)
	s_barrier
	s_setprio 1
	s_waitcnt lgkmcnt(0)
	v_mfma_f32_16x16x32_bf16 v[60:63], v[144:147], v[194:197], v[60:63]
	v_mfma_f32_16x16x32_bf16 v[56:59], v[152:155], v[194:197], v[56:59]
	v_mfma_f32_16x16x32_bf16 v[52:55], v[144:147], v[212:215], v[52:55]
	v_mfma_f32_16x16x32_bf16 v[48:51], v[152:155], v[212:215], v[48:51]
	s_setprio 0
	s_setprio 1
	v_mfma_f32_16x16x32_bf16 v[36:39], v[144:147], v[220:223], v[36:39]
	v_mfma_f32_16x16x32_bf16 v[32:35], v[152:155], v[220:223], v[32:35]
	v_mfma_f32_16x16x32_bf16 v[20:23], v[144:147], v[228:231], v[20:23]
	v_mfma_f32_16x16x32_bf16 v[16:19], v[152:155], v[228:231], v[16:19]
	s_setprio 0
	s_setprio 1
	v_mfma_f32_16x16x32_bf16 v[60:63], v[148:151], v[208:211], v[60:63]
	v_mfma_f32_16x16x32_bf16 v[56:59], v[156:159], v[208:211], v[56:59]
	v_mfma_f32_16x16x32_bf16 v[52:55], v[148:151], v[216:219], v[52:55]
	v_mfma_f32_16x16x32_bf16 v[48:51], v[156:159], v[216:219], v[48:51]
	s_setprio 0
	s_setprio 1
	v_mfma_f32_16x16x32_bf16 v[36:39], v[148:151], v[224:227], v[36:39]
	v_mfma_f32_16x16x32_bf16 v[32:35], v[156:159], v[224:227], v[32:35]
	v_mfma_f32_16x16x32_bf16 v[20:23], v[148:151], v[232:235], v[20:23]
	v_mfma_f32_16x16x32_bf16 v[16:19], v[156:159], v[232:235], v[16:19]
	s_setprio 0
	s_setprio 1
	v_mfma_f32_16x16x32_bf16 v[44:47], v[178:181], v[194:197], v[44:47]
	v_mfma_f32_16x16x32_bf16 v[40:43], v[186:189], v[194:197], v[40:43]
	v_mfma_f32_16x16x32_bf16 v[28:31], v[178:181], v[212:215], v[28:31]
	v_mfma_f32_16x16x32_bf16 v[24:27], v[186:189], v[212:215], v[24:27]
	v_mfma_f32_16x16x32_bf16 v[12:15], v[178:181], v[220:223], v[12:15]
	v_mfma_f32_16x16x32_bf16 v[8:11], v[186:189], v[220:223], v[8:11]
	v_mfma_f32_16x16x32_bf16 v[4:7], v[178:181], v[228:231], v[4:7]
	v_mfma_f32_16x16x32_bf16 v[0:3], v[186:189], v[228:231], v[0:3]
	s_setprio 0
	s_setprio 1
	v_mfma_f32_16x16x32_bf16 v[44:47], v[182:185], v[208:211], v[44:47]
	v_mfma_f32_16x16x32_bf16 v[40:43], v[190:193], v[208:211], v[40:43]
	v_mfma_f32_16x16x32_bf16 v[28:31], v[182:185], v[216:219], v[28:31]
	v_mfma_f32_16x16x32_bf16 v[24:27], v[190:193], v[216:219], v[24:27]
	v_mfma_f32_16x16x32_bf16 v[12:15], v[182:185], v[224:227], v[12:15]
	v_mfma_f32_16x16x32_bf16 v[8:11], v[190:193], v[224:227], v[8:11]
	v_mfma_f32_16x16x32_bf16 v[4:7], v[182:185], v[232:235], v[4:7]
	v_mfma_f32_16x16x32_bf16 v[0:3], v[190:193], v[232:235], v[0:3]
	s_setprio 0
	s_barrier
	s_add_i32 s42, s42, 2
	s_add_u32 s0, s0, 0x100
	s_addc_u32 s1, s1, 0
	s_add_u32 s36, s36, 0x100
	s_addc_u32 s37, s37, 0
	s_cmpk_gt_u32 s42, 0x7d
	s_cbranch_scc0 .LBB0_1685
	s_mov_b64 s[48:49], 0x80
	s_and_b64 vcc, exec, s[6:7]
	s_mov_b64 s[34:35], 0x45000
	s_cbranch_vccz .LBB0_1688
	s_barrier

; #define PG8_STAGE(bufoff, gbase, voff) do { _Pragma("unroll") for (int _i = 0; _i < 2; ++_i) \
;         __builtin_amdgcn_global_load_lds((const unsigned*)((const char*)(gbase) + (voff)[_i]), (PG8_LAS unsigned*)(lds + (bufoff) + ldsw + _i * 8192), 16, 0, 0); } while (0)
; #define PG8_LDA(dst, b, h) do { _Pragma("unroll") for (int m = 0; m < 4; ++m) _Pragma("unroll") for (int k = 0; k < 2; ++k) dst[m][k] = *(const PG8_LAS bf16x8*)(lds + PG8_SA(b, h) + aoff + m * 2048 + k * 1024); } while (0)
; #define PG8_WAIT_V(n) asm volatile("s_waitcnt vmcnt(" #n ")" ::: "memory")
; #define PG8_WAIT_L(n) asm volatile("s_waitcnt lgkmcnt(" #n ")" ::: "memory")
; #define PG8_BAR __builtin_amdgcn_s_barrier()
; template <class Epi, class Sched, bool ALIGN_EPI = false, bool SP2 = false>
; __device__ __forceinline__ void gemm_phase(PG8_LAS unsigned char* lds, const Gemm g, const Sched& S, const Epi& E, const int wave0) {
;     ...
;         for (int t = 0; t < nt; t += 2) {
;             const bool last = (t == nt - 2);
;             const char* a1 = cA + (size_t)(t + 1) * kstep;
;             const char* a2 = last ? nA : cA + (size_t)(t + 2) * kstep; const char* b2 = last ? nB : cB + (size_t)(t + 2) * kstep;
;             const char* a3 = a2 + kstep; const char* b3 = b2 + kstep;
;             if (last && has_next) S.a_ready(nxt);
;             if constexpr (SP2) {
;             PG8_LDB(B0, 0, 0); PG8_LDB(B1, 0, 1); PG8_SCHED; PG8_LDA(At, 0, 0); PG8_STAGE(PG8_SA(1, 1), a1 + hstepA, voffA);
;             PG8_WAIT_V(8); PG8_WAIT_L(0); PG8_BAR; PG8_MMA(0, 0, At, B0); PG8_MMA(0, 1, At, B1); PG8_BAR; PG8_SCHED;
;             PG8_LDA(At, 0, 1); PG8_STAGE(PG8_SB(0, 0), b2, voffB); PG8_STAGE(PG8_SB(0, 1), b2 + hstepB, voffB); PG8_STAGE(PG8_SA(0, 0), a2, voffA);
;             PG8_WAIT_V(8); PG8_WAIT_L(0); PG8_BAR; PG8_MMA(1, 0, At, B0); PG8_MMA(1, 1, At, B1); PG8_BAR; PG8_SCHED;
;             PG8_LDB(B0, 1, 0); PG8_LDB(B1, 1, 1); PG8_SCHED; PG8_LDA(At, 1, 0); PG8_STAGE(PG8_SA(0, 1), a2 + hstepA, voffA);
;             PG8_WAIT_V(8); PG8_WAIT_L(0); PG8_BAR; PG8_MMA(0, 0, At, B0); PG8_MMA(0, 1, At, B1); PG8_BAR; PG8_SCHED;
;             PG8_LDA(At, 1, 1); PG8_STAGE(PG8_SB(1, 0), b3, voffB); PG8_STAGE(PG8_SB(1, 1), b3 + hstepB, voffB); PG8_STAGE(PG8_SA(1, 0), a3, voffA);
;             PG8_WAIT_V(8); PG8_WAIT_L(0); PG8_BAR; PG8_MMA(1, 0, At, B0); PG8_MMA(1, 1, At, B1); PG8_BAR; PG8_SCHED;
.LBB0_1702:
	s_add_u32 s18, s16, 0xffe00080
	s_addc_u32 s19, s17, -1
	s_add_i32 s44, 0, 0x10000
	s_cmp_eq_u32 s43, 12
	s_cselect_b32 s21, s9, s19
	s_cselect_b32 s20, s11, s18
	s_cselect_b32 s19, s13, s42
	s_cselect_b32 s18, s38, s39
	s_add_i32 s46, 0, 0x14000
	ds_read_b128 v[144:147], v252
	ds_read_b128 v[148:151], v252 offset:1024
	ds_read_b128 v[152:155], v252 offset:2048
	ds_read_b128 v[156:159], v252 offset:3072
	ds_read_b128 v[178:181], v253
	ds_read_b128 v[182:185], v253 offset:1024
	ds_read_b128 v[186:189], v253 offset:2048
	ds_read_b128 v[190:193], v253 offset:3072
	s_add_i32 m0, s28, 0xc000
	ds_read_b128 v[194:197], v143
	ds_read_b128 v[208:211], v143 offset:1024
	ds_read_b128 v[212:215], v143 offset:2048
	ds_read_b128 v[216:219], v143 offset:3072
	ds_read_b128 v[220:223], v143 offset:4096
	ds_read_b128 v[224:227], v143 offset:5120
	ds_read_b128 v[228:231], v143 offset:6144
	ds_read_b128 v[232:235], v143 offset:7168
	global_load_lds_dwordx4 v136, s[16:17]
	s_add_i32 m0, s28, 0xe000
	s_nop 0
	global_load_lds_dwordx4 v138, s[16:17]
	s_waitcnt vmcnt(8)
	s_waitcnt lgkmcnt(0)
	s_barrier
	s_setprio 1
	s_waitcnt lgkmcnt(0)
	v_mfma_f32_16x16x32_bf16 v[126:129], v[144:147], v[194:197], v[126:129]
	v_mfma_f32_16x16x32_bf16 v[122:125], v[152:155], v[194:197], v[122:125]
	v_mfma_f32_16x16x32_bf16 v[118:121], v[144:147], v[212:215], v[118:121]
	v_mfma_f32_16x16x32_bf16 v[114:117], v[152:155], v[212:215], v[114:117]
	s_setprio 0
	s_setprio 1
	v_mfma_f32_16x16x32_bf16 v[102:105], v[144:147], v[220:223], v[102:105]
	v_mfma_f32_16x16x32_bf16 v[98:101], v[152:155], v[220:223], v[98:101]
	v_mfma_f32_16x16x32_bf16 v[86:89], v[144:147], v[228:231], v[86:89]
	v_mfma_f32_16x16x32_bf16 v[82:85], v[152:155], v[228:231], v[82:85]
	s_setprio 0
	s_setprio 1
	v_mfma_f32_16x16x32_bf16 v[126:129], v[148:151], v[208:211], v[126:129]
	v_mfma_f32_16x16x32_bf16 v[122:125], v[156:159], v[208:211], v[122:125]
	v_mfma_f32_16x16x32_bf16 v[118:121], v[148:151], v[216:219], v[118:121]
	v_mfma_f32_16x16x32_bf16 v[114:117], v[156:159], v[216:219], v[114:117]
	s_setprio 0
	s_setprio 1
	v_mfma_f32_16x16x32_bf16 v[102:105], v[148:151], v[224:227], v[102:105]
	v_mfma_f32_16x16x32_bf16 v[98:101], v[156:159], v[224:227], v[98:101]
	v_mfma_f32_16x16x32_bf16 v[86:89], v[148:151], v[232:235], v[86:89]
	v_mfma_f32_16x16x32_bf16 v[82:85], v[156:159], v[232:235], v[82:85]
	s_setprio 0
	s_setprio 1
	v_mfma_f32_16x16x32_bf16 v[110:113], v[178:181], v[194:197], v[110:113]
	v_mfma_f32_16x16x32_bf16 v[106:109], v[186:189], v[194:197], v[106:109]
	v_mfma_f32_16x16x32_bf16 v[94:97], v[178:181], v[212:215], v[94:97]
	v_mfma_f32_16x16x32_bf16 v[90:93], v[186:189], v[212:215], v[90:93]
	v_mfma_f32_16x16x32_bf16 v[78:81], v[178:181], v[220:223], v[78:81]
	v_mfma_f32_16x16x32_bf16 v[74:77], v[186:189], v[220:223], v[74:77]
	v_mfma_f32_16x16x32_bf16 v[70:73], v[178:181], v[228:231], v[70:73]
	v_mfma_f32_16x16x32_bf16 v[66:69], v[186:189], v[228:231], v[66:69]
	s_setprio 0
	s_setprio 1
	v_mfma_f32_16x16x32_bf16 v[110:113], v[182:185], v[208:211], v[110:113]
	v_mfma_f32_16x16x32_bf16 v[106:109], v[190:193], v[208:211], v[106:109]
	v_mfma_f32_16x16x32_bf16 v[94:97], v[182:185], v[216:219], v[94:97]
	v_mfma_f32_16x16x32_bf16 v[90:93], v[190:193], v[216:219], v[90:93]
	v_mfma_f32_16x16x32_bf16 v[78:81], v[182:185], v[224:227], v[78:81]
	v_mfma_f32_16x16x32_bf16 v[74:77], v[190:193], v[224:227], v[74:77]
	v_mfma_f32_16x16x32_bf16 v[70:73], v[182:185], v[232:235], v[70:73]
	v_mfma_f32_16x16x32_bf16 v[66:69], v[190:193], v[232:235], v[66:69]
	s_setprio 0
	s_barrier
	s_add_i32 s44, s44, s25
	s_mov_b32 m0, s44
	ds_read_b128 v[194:197], v143 offset:16384
	ds_read_b128 v[208:211], v143 offset:17408
	ds_read_b128 v[212:215], v143 offset:18432
	ds_read_b128 v[216:219], v143 offset:19456
	ds_read_b128 v[220:223], v143 offset:20480
	ds_read_b128 v[224:227], v143 offset:21504
	ds_read_b128 v[228:231], v143 offset:22528
	ds_read_b128 v[232:235], v143 offset:23552
	global_load_lds_dwordx4 v64, s[18:19]
	s_add_i32 m0, s44, 0x2000
	s_add_u32 s44, s18, 0x200000
	s_addc_u32 s45, s19, 0
	s_add_i32 s46, s46, s25
	global_load_lds_dwordx4 v130, s[18:19]
	s_mov_b32 m0, s46
	s_mov_b64 s[100:101], s[20:21]
	global_load_lds_dwordx4 v64, s[44:45]
	s_add_i32 m0, s46, 0x2000
	s_nop 0
	global_load_lds_dwordx4 v130, s[44:45]
	s_mov_b32 m0, s28
	s_nop 0
	global_load_lds_dwordx4 v134, s[20:21]
	s_mov_b32 m0, s29
	s_nop 0
	global_load_lds_dwordx4 v132, s[20:21]
	s_waitcnt vmcnt(8)
	s_waitcnt lgkmcnt(0)
	s_barrier
; #define PG8_STAGE(bufoff, gbase, voff) do { _Pragma("unroll") for (int _i = 0; _i < 2; ++_i) \
;         __builtin_amdgcn_global_load_lds((const unsigned*)((const char*)(gbase) + (voff)[_i]), (PG8_LAS unsigned*)(lds + (bufoff) + ldsw + _i * 8192), 16, 0, 0); } while (0)
; #define PG8_LDA(dst, b, h) do { _Pragma("unroll") for (int m = 0; m < 4; ++m) _Pragma("unroll") for (int k = 0; k < 2; ++k) dst[m][k] = *(const PG8_LAS bf16x8*)(lds + PG8_SA(b, h) + aoff + m * 2048 + k * 1024); } while (0)
; #define PG8_LDB(dst, b, h) do { _Pragma("unroll") for (int n = 0; n < 2; ++n) _Pragma("unroll") for (int k = 0; k < 2; ++k) dst[n][k] = *(const PG8_LAS bf16x8*)(lds + PG8_SB(b, h) + boff + n * 2048 + k * 1024); } while (0)
; #define PG8_MMA(ai, bj, At, Bt) do { __builtin_amdgcn_s_setprio(1); _Pragma("unroll") for (int m = 0; m < 4; ++m) _Pragma("unroll") for (int n = 0; n < 2; ++n) _Pragma("unroll") for (int k = 0; k < 2; ++k) \
;         acc[ai][bj][m][n] = __builtin_amdgcn_mfma_f32_16x16x32_bf16(Bt[n][k], At[m][k], acc[ai][bj][m][n], 0, 0, 0); __builtin_amdgcn_s_setprio(0); } while (0)
; template <class Epi, class Sched, bool ALIGN_EPI = false, bool SP2 = false>
; __device__ __forceinline__ void gemm_phase(PG8_LAS unsigned char* lds, const Gemm g, const Sched& S, const Epi& E, const int wave0) {
;     ...
;             if constexpr (SP2) {
;             PG8_LDB(B0, 0, 0); PG8_LDB(B1, 0, 1); PG8_SCHED; PG8_LDA(At, 0, 0); PG8_STAGE(PG8_SA(1, 1), a1 + hstepA, voffA);
;             PG8_WAIT_V(8); PG8_WAIT_L(0); PG8_BAR; PG8_MMA(0, 0, At, B0); PG8_MMA(0, 1, At, B1); PG8_BAR; PG8_SCHED;
;             PG8_LDA(At, 0, 1); PG8_STAGE(PG8_SB(0, 0), b2, voffB); PG8_STAGE(PG8_SB(0, 1), b2 + hstepB, voffB); PG8_STAGE(PG8_SA(0, 0), a2, voffA);
;             PG8_WAIT_V(8); PG8_WAIT_L(0); PG8_BAR; PG8_MMA(1, 0, At, B0); PG8_MMA(1, 1, At, B1); PG8_BAR; PG8_SCHED;
;             PG8_LDB(B0, 1, 0); PG8_LDB(B1, 1, 1); PG8_SCHED; PG8_LDA(At, 1, 0); PG8_STAGE(PG8_SA(0, 1), a2 + hstepA, voffA);
;             PG8_WAIT_V(8); PG8_WAIT_L(0); PG8_BAR; PG8_MMA(0, 0, At, B0); PG8_MMA(0, 1, At, B1); PG8_BAR; PG8_SCHED;
;             PG8_LDA(At, 1, 1); PG8_STAGE(PG8_SB(1, 0), b3, voffB); PG8_STAGE(PG8_SB(1, 1), b3 + hstepB, voffB); PG8_STAGE(PG8_SA(1, 0), a3, voffA);
;             PG8_WAIT_V(8); PG8_WAIT_L(0); PG8_BAR; PG8_MMA(1, 0, At, B0); PG8_MMA(1, 1, At, B1); PG8_BAR; PG8_SCHED;
	s_setprio 1
	s_waitcnt lgkmcnt(0)
	v_mfma_f32_16x16x32_bf16 v[60:63], v[144:147], v[194:197], v[60:63]
	v_mfma_f32_16x16x32_bf16 v[56:59], v[152:155], v[194:197], v[56:59]
	v_mfma_f32_16x16x32_bf16 v[52:55], v[144:147], v[212:215], v[52:55]
	v_mfma_f32_16x16x32_bf16 v[48:51], v[152:155], v[212:215], v[48:51]
	s_setprio 0
	s_setprio 1
	v_mfma_f32_16x16x32_bf16 v[36:39], v[144:147], v[220:223], v[36:39]
	v_mfma_f32_16x16x32_bf16 v[32:35], v[152:155], v[220:223], v[32:35]
	v_mfma_f32_16x16x32_bf16 v[20:23], v[144:147], v[228:231], v[20:23]
	v_mfma_f32_16x16x32_bf16 v[16:19], v[152:155], v[228:231], v[16:19]
	s_setprio 0
	s_setprio 1
	v_mfma_f32_16x16x32_bf16 v[60:63], v[148:151], v[208:211], v[60:63]
	v_mfma_f32_16x16x32_bf16 v[56:59], v[156:159], v[208:211], v[56:59]
	v_mfma_f32_16x16x32_bf16 v[52:55], v[148:151], v[216:219], v[52:55]
	v_mfma_f32_16x16x32_bf16 v[48:51], v[156:159], v[216:219], v[48:51]
	s_setprio 0
	s_setprio 1
	v_mfma_f32_16x16x32_bf16 v[36:39], v[148:151], v[224:227], v[36:39]
	v_mfma_f32_16x16x32_bf16 v[32:35], v[156:159], v[224:227], v[32:35]
	v_mfma_f32_16x16x32_bf16 v[20:23], v[148:151], v[232:235], v[20:23]
	v_mfma_f32_16x16x32_bf16 v[16:19], v[156:159], v[232:235], v[16:19]
	s_setprio 0
	s_setprio 1
	v_mfma_f32_16x16x32_bf16 v[44:47], v[178:181], v[194:197], v[44:47]
	v_mfma_f32_16x16x32_bf16 v[40:43], v[186:189], v[194:197], v[40:43]
	v_mfma_f32_16x16x32_bf16 v[28:31], v[178:181], v[212:215], v[28:31]
	v_mfma_f32_16x16x32_bf16 v[24:27], v[186:189], v[212:215], v[24:27]
	v_mfma_f32_16x16x32_bf16 v[12:15], v[178:181], v[220:223], v[12:15]
	v_mfma_f32_16x16x32_bf16 v[8:11], v[186:189], v[220:223], v[8:11]
	v_mfma_f32_16x16x32_bf16 v[4:7], v[178:181], v[228:231], v[4:7]
	v_mfma_f32_16x16x32_bf16 v[0:3], v[186:189], v[228:231], v[0:3]
	s_setprio 0
	s_setprio 1
	v_mfma_f32_16x16x32_bf16 v[44:47], v[182:185], v[208:211], v[44:47]
	v_mfma_f32_16x16x32_bf16 v[40:43], v[190:193], v[208:211], v[40:43]
	v_mfma_f32_16x16x32_bf16 v[28:31], v[182:185], v[216:219], v[28:31]
	v_mfma_f32_16x16x32_bf16 v[24:27], v[190:193], v[216:219], v[24:27]
	v_mfma_f32_16x16x32_bf16 v[12:15], v[182:185], v[224:227], v[12:15]
	v_mfma_f32_16x16x32_bf16 v[8:11], v[190:193], v[224:227], v[8:11]
	v_mfma_f32_16x16x32_bf16 v[4:7], v[182:185], v[232:235], v[4:7]
	v_mfma_f32_16x16x32_bf16 v[0:3], v[190:193], v[232:235], v[0:3]
	s_setprio 0
	s_barrier
	s_add_i32 s44, 0, 0x18000
	s_add_i32 s45, 0, 0x1c000
	ds_read_b128 v[144:147], v254
	ds_read_b128 v[148:151], v254 offset:1024
	ds_read_b128 v[152:155], v254 offset:2048
	ds_read_b128 v[156:159], v254 offset:3072
	ds_read_b128 v[178:181], v255
	ds_read_b128 v[182:185], v255 offset:1024
	ds_read_b128 v[186:189], v255 offset:2048
	ds_read_b128 v[190:193], v255 offset:3072
	s_add_u32 s20, s20, 0x200000
	s_addc_u32 s21, s21, 0
	s_mov_b32 m0, s30
	ds_read_b128 v[194:197], v143 offset:32768
	ds_read_b128 v[208:211], v143 offset:33792
	ds_read_b128 v[212:215], v143 offset:34816
	ds_read_b128 v[216:219], v143 offset:35840
	ds_read_b128 v[220:223], v143 offset:36864
	ds_read_b128 v[224:227], v143 offset:37888
	ds_read_b128 v[228:231], v143 offset:38912
	ds_read_b128 v[232:235], v143 offset:39936
	global_load_lds_dwordx4 v134, s[20:21]
	s_mov_b32 m0, s31
	s_nop 0
	global_load_lds_dwordx4 v132, s[20:21]
	s_waitcnt vmcnt(8)
	s_waitcnt lgkmcnt(0)
	s_barrier
	s_setprio 1
	s_waitcnt lgkmcnt(0)
	v_mfma_f32_16x16x32_bf16 v[126:129], v[144:147], v[194:197], v[126:129]
	v_mfma_f32_16x16x32_bf16 v[122:125], v[152:155], v[194:197], v[122:125]
	v_mfma_f32_16x16x32_bf16 v[118:121], v[144:147], v[212:215], v[118:121]
	v_mfma_f32_16x16x32_bf16 v[114:117], v[152:155], v[212:215], v[114:117]
	s_setprio 0
	s_setprio 1
	v_mfma_f32_16x16x32_bf16 v[102:105], v[144:147], v[220:223], v[102:105]
	v_mfma_f32_16x16x32_bf16 v[98:101], v[152:155], v[220:223], v[98:101]
	v_mfma_f32_16x16x32_bf16 v[86:89], v[144:147], v[228:231], v[86:89]
	v_mfma_f32_16x16x32_bf16 v[82:85], v[152:155], v[228:231], v[82:85]
	s_setprio 0
	s_setprio 1
	v_mfma_f32_16x16x32_bf16 v[126:129], v[148:151], v[208:211], v[126:129]
	v_mfma_f32_16x16x32_bf16 v[122:125], v[156:159], v[208:211], v[122:125]
	v_mfma_f32_16x16x32_bf16 v[118:121], v[148:151], v[216:219], v[118:121]
	v_mfma_f32_16x16x32_bf16 v[114:117], v[156:159], v[216:219], v[114:117]
	s_setprio 0
	s_setprio 1
	v_mfma_f32_16x16x32_bf16 v[102:105], v[148:151], v[224:227], v[102:105]
	v_mfma_f32_16x16x32_bf16 v[98:101], v[156:159], v[224:227], v[98:101]
	v_mfma_f32_16x16x32_bf16 v[86:89], v[148:151], v[232:235], v[86:89]
	v_mfma_f32_16x16x32_bf16 v[82:85], v[156:159], v[232:235], v[82:85]
	s_setprio 0
	s_setprio 1
	v_mfma_f32_16x16x32_bf16 v[110:113], v[178:181], v[194:197], v[110:113]
	v_mfma_f32_16x16x32_bf16 v[106:109], v[186:189], v[194:197], v[106:109]
	v_mfma_f32_16x16x32_bf16 v[94:97], v[178:181], v[212:215], v[94:97]
	v_mfma_f32_16x16x32_bf16 v[90:93], v[186:189], v[212:215], v[90:93]
	v_mfma_f32_16x16x32_bf16 v[78:81], v[178:181], v[220:223], v[78:81]
	v_mfma_f32_16x16x32_bf16 v[74:77], v[186:189], v[220:223], v[74:77]
	v_mfma_f32_16x16x32_bf16 v[70:73], v[178:181], v[228:231], v[70:73]
	v_mfma_f32_16x16x32_bf16 v[66:69], v[186:189], v[228:231], v[66:69]
	s_setprio 0
	s_setprio 1
	v_mfma_f32_16x16x32_bf16 v[110:113], v[182:185], v[208:211], v[110:113]
	v_mfma_f32_16x16x32_bf16 v[106:109], v[190:193], v[208:211], v[106:109]
	v_mfma_f32_16x16x32_bf16 v[94:97], v[182:185], v[216:219], v[94:97]
	v_mfma_f32_16x16x32_bf16 v[90:93], v[190:193], v[216:219], v[90:93]
	v_mfma_f32_16x16x32_bf16 v[78:81], v[182:185], v[224:227], v[78:81]
	v_mfma_f32_16x16x32_bf16 v[74:77], v[190:193], v[224:227], v[74:77]
	v_mfma_f32_16x16x32_bf16 v[70:73], v[182:185], v[232:235], v[70:73]
	v_mfma_f32_16x16x32_bf16 v[66:69], v[190:193], v[232:235], v[66:69]
	s_setprio 0
	s_barrier
; #define PG8_STAGE(bufoff, gbase, voff) do { _Pragma("unroll") for (int _i = 0; _i < 2; ++_i) \
;         __builtin_amdgcn_global_load_lds((const unsigned*)((const char*)(gbase) + (voff)[_i]), (PG8_LAS unsigned*)(lds + (bufoff) + ldsw + _i * 8192), 16, 0, 0); } while (0)
; #define PG8_LDA(dst, b, h) do { _Pragma("unroll") for (int m = 0; m < 4; ++m) _Pragma("unroll") for (int k = 0; k < 2; ++k) dst[m][k] = *(const PG8_LAS bf16x8*)(lds + PG8_SA(b, h) + aoff + m * 2048 + k * 1024); } while (0)
; #define PG8_WAIT_V(n) asm volatile("s_waitcnt vmcnt(" #n ")" ::: "memory")
; #define PG8_WAIT_L(n) asm volatile("s_waitcnt lgkmcnt(" #n ")" ::: "memory")
; #define PG8_BAR __builtin_amdgcn_s_barrier()
; template <class Epi, class Sched, bool ALIGN_EPI = false, bool SP2 = false>
; __device__ __forceinline__ void gemm_phase(PG8_LAS unsigned char* lds, const Gemm g, const Sched& S, const Epi& E, const int wave0) {
;     ...
;         for (int t = 0; t < nt; t += 2) {
;             const bool last = (t == nt - 2);
;             const char* a1 = cA + (size_t)(t + 1) * kstep;
;             const char* a2 = last ? nA : cA + (size_t)(t + 2) * kstep; const char* b2 = last ? nB : cB + (size_t)(t + 2) * kstep;
;             const char* a3 = a2 + kstep; const char* b3 = b2 + kstep;
;             if (last && has_next) S.a_ready(nxt);
;             if constexpr (SP2) {
;             PG8_LDB(B0, 0, 0); PG8_LDB(B1, 0, 1); PG8_SCHED; PG8_LDA(At, 0, 0); PG8_STAGE(PG8_SA(1, 1), a1 + hstepA, voffA);
;             PG8_WAIT_V(8); PG8_WAIT_L(0); PG8_BAR; PG8_MMA(0, 0, At, B0); PG8_MMA(0, 1, At, B1); PG8_BAR; PG8_SCHED;
;             PG8_LDA(At, 0, 1); PG8_STAGE(PG8_SB(0, 0), b2, voffB); PG8_STAGE(PG8_SB(0, 1), b2 + hstepB, voffB); PG8_STAGE(PG8_SA(0, 0), a2, voffA);
;             PG8_WAIT_V(8); PG8_WAIT_L(0); PG8_BAR; PG8_MMA(1, 0, At, B0); PG8_MMA(1, 1, At, B1); PG8_BAR; PG8_SCHED;
;             PG8_LDB(B0, 1, 0); PG8_LDB(B1, 1, 1); PG8_SCHED; PG8_LDA(At, 1, 0); PG8_STAGE(PG8_SA(0, 1), a2 + hstepA, voffA);
;             PG8_WAIT_V(8); PG8_WAIT_L(0); PG8_BAR; PG8_MMA(0, 0, At, B0); PG8_MMA(0, 1, At, B1); PG8_BAR; PG8_SCHED;
;             PG8_LDA(At, 1, 1); PG8_STAGE(PG8_SB(1, 0), b3, voffB); PG8_STAGE(PG8_SB(1, 1), b3 + hstepB, voffB); PG8_STAGE(PG8_SA(1, 0), a3, voffA);
;             PG8_WAIT_V(8); PG8_WAIT_L(0); PG8_BAR; PG8_MMA(1, 0, At, B0); PG8_MMA(1, 1, At, B1); PG8_BAR; PG8_SCHED;
	s_add_i32 s20, s44, s25
	s_add_u32 s48, s18, 0x80
	s_addc_u32 s49, s19, 0
	s_mov_b32 m0, s20
	ds_read_b128 v[194:197], v143 offset:49152
	ds_read_b128 v[208:211], v143 offset:50176
	ds_read_b128 v[212:215], v143 offset:51200
	ds_read_b128 v[216:219], v143 offset:52224
	ds_read_b128 v[220:223], v143 offset:53248
	ds_read_b128 v[224:227], v143 offset:54272
	ds_read_b128 v[228:231], v143 offset:55296
	ds_read_b128 v[232:235], v143 offset:56320
	global_load_lds_dwordx4 v64, s[48:49]
	s_add_i32 m0, s20, 0x2000
	s_add_u32 s18, s18, 0x200080
	s_addc_u32 s19, s19, 0
	s_add_i32 s20, s45, s25
	global_load_lds_dwordx4 v130, s[48:49]
	s_mov_b32 m0, s20
	s_nop 0
	global_load_lds_dwordx4 v64, s[18:19]
	s_add_i32 m0, s20, 0x2000
	s_nop 0
	global_load_lds_dwordx4 v130, s[18:19]
	s_add_u32 s100, s100, 0x80
	s_addc_u32 s101, s101, 0
	s_mov_b32 m0, s33
	s_nop 0
	global_load_lds_dwordx4 v134, s[100:101]
	s_mov_b32 m0, s34
	s_nop 0
	global_load_lds_dwordx4 v132, s[100:101]
	s_waitcnt vmcnt(8)
	s_waitcnt lgkmcnt(0)
	s_barrier
	s_setprio 1
	s_waitcnt lgkmcnt(0)
	v_mfma_f32_16x16x32_bf16 v[60:63], v[144:147], v[194:197], v[60:63]
	v_mfma_f32_16x16x32_bf16 v[56:59], v[152:155], v[194:197], v[56:59]
	v_mfma_f32_16x16x32_bf16 v[52:55], v[144:147], v[212:215], v[52:55]
	v_mfma_f32_16x16x32_bf16 v[48:51], v[152:155], v[212:215], v[48:51]
	s_setprio 0
	s_setprio 1
	v_mfma_f32_16x16x32_bf16 v[36:39], v[144:147], v[220:223], v[36:39]
	v_mfma_f32_16x16x32_bf16 v[32:35], v[152:155], v[220:223], v[32:35]
	v_mfma_f32_16x16x32_bf16 v[20:23], v[144:147], v[228:231], v[20:23]
	v_mfma_f32_16x16x32_bf16 v[16:19], v[152:155], v[228:231], v[16:19]
	s_setprio 0
	s_setprio 1
	v_mfma_f32_16x16x32_bf16 v[60:63], v[148:151], v[208:211], v[60:63]
	v_mfma_f32_16x16x32_bf16 v[56:59], v[156:159], v[208:211], v[56:59]
	v_mfma_f32_16x16x32_bf16 v[52:55], v[148:151], v[216:219], v[52:55]
	v_mfma_f32_16x16x32_bf16 v[48:51], v[156:159], v[216:219], v[48:51]
	s_setprio 0
	s_setprio 1
	v_mfma_f32_16x16x32_bf16 v[36:39], v[148:151], v[224:227], v[36:39]
	v_mfma_f32_16x16x32_bf16 v[32:35], v[156:159], v[224:227], v[32:35]
	v_mfma_f32_16x16x32_bf16 v[20:23], v[148:151], v[232:235], v[20:23]
	v_mfma_f32_16x16x32_bf16 v[16:19], v[156:159], v[232:235], v[16:19]
	s_setprio 0
	s_setprio 1
	v_mfma_f32_16x16x32_bf16 v[44:47], v[178:181], v[194:197], v[44:47]
	v_mfma_f32_16x16x32_bf16 v[40:43], v[186:189], v[194:197], v[40:43]
	v_mfma_f32_16x16x32_bf16 v[28:31], v[178:181], v[212:215], v[28:31]
	v_mfma_f32_16x16x32_bf16 v[24:27], v[186:189], v[212:215], v[24:27]
	v_mfma_f32_16x16x32_bf16 v[12:15], v[178:181], v[220:223], v[12:15]
	v_mfma_f32_16x16x32_bf16 v[8:11], v[186:189], v[220:223], v[8:11]
	v_mfma_f32_16x16x32_bf16 v[4:7], v[178:181], v[228:231], v[4:7]
	v_mfma_f32_16x16x32_bf16 v[0:3], v[186:189], v[228:231], v[0:3]
	s_setprio 0
	s_setprio 1
	v_mfma_f32_16x16x32_bf16 v[44:47], v[182:185], v[208:211], v[44:47]
	v_mfma_f32_16x16x32_bf16 v[40:43], v[190:193], v[208:211], v[40:43]
	v_mfma_f32_16x16x32_bf16 v[28:31], v[182:185], v[216:219], v[28:31]
	v_mfma_f32_16x16x32_bf16 v[24:27], v[190:193], v[216:219], v[24:27]
	v_mfma_f32_16x16x32_bf16 v[12:15], v[182:185], v[224:227], v[12:15]
	v_mfma_f32_16x16x32_bf16 v[8:11], v[190:193], v[224:227], v[8:11]
	v_mfma_f32_16x16x32_bf16 v[4:7], v[182:185], v[232:235], v[4:7]
	v_mfma_f32_16x16x32_bf16 v[0:3], v[190:193], v[232:235], v[0:3]
	s_setprio 0
	s_barrier
	s_add_i32 s43, s43, 2
	s_add_u32 s16, s16, 0x100
	s_addc_u32 s17, s17, 0
	s_add_u32 s39, s39, 0x100
	s_addc_u32 s42, s42, 0
	s_cmp_gt_u32 s43, 13
	s_cbranch_scc0 .LBB0_1702
	s_mov_b64 s[48:49], 0x80
	s_and_b64 vcc, exec, s[6:7]
	s_cbranch_vccz .LBB0_1705
	s_barrier
